# speedup vs baseline: 1.0158x; 1.0003x over previous
; #define LDA(dst, b, h) for (int m = 0; m < 4; ++m) for (int k = 0; k < 2; ++k) \
;     dst[m][k] = *reinterpret_cast<const bf16x8*>((char*)SA(b, h) + lds_byte(wr * 64 + m * 16 + fr, k * 32 + fq * 8))
; #define LDB(dst, b, h) for (int n = 0; n < 2; ++n) for (int k = 0; k < 2; ++k) \
;     dst[n][k] = *reinterpret_cast<const bf16x8*>((char*)SB(b, h) + lds_byte(wc * 32 + n * 16 + fr, k * 32 + fq * 8))
; #define MMA(ai, bj, At, Bt_) do { __builtin_amdgcn_s_setprio(1); \
;     for (int m = 0; m < 4; ++m) for (int n = 0; n < 2; ++n) for (int k = 0; k < 2; ++k) \
;       acc[ai][bj][m][n] = __builtin_amdgcn_mfma_f32_16x16x32_bf16(At[m][k], Bt_[n][k], acc[ai][bj][m][n], 0, 0, 0); \
;     __builtin_amdgcn_s_setprio(0); } while (0)
; #define WAIT_V(n) asm volatile("s_waitcnt vmcnt(" #n ")" ::: "memory")
; #define WAIT_L(n) asm volatile("s_waitcnt lgkmcnt(" #n ")" ::: "memory")
; #define BAR __builtin_amdgcn_s_barrier()
; #define SCHED __builtin_amdgcn_sched_barrier(0)
;     ...
;     for (int t = 0; t < nt - 2; t += 2) {
;       LDB(B0, 0, 0); SCHED; LDA(At, 0, 0); STAGE(SA(1, 1), A, brow + HALF, t + 1);
;       WAIT_L(8); BAR; WAIT_L(0); MMA(0, 0, At, B0); BAR; SCHED;
;       LDB(B1, 0, 1); STAGE(SB(0, 0), Bt, bcol, t + 2);
;       BAR; WAIT_L(0); MMA(0, 1, At, B1); BAR;
;       LDA(At, 0, 1); STAGE(SA(0, 0), A, brow, t + 2);
;       BAR; WAIT_L(0); MMA(1, 0, At, B0); BAR; SCHED;
;       STAGE(SB(0, 1), Bt, bcol + HALF, t + 2);
;       WAIT_V(6); BAR; MMA(1, 1, At, B1); BAR;
.LBB0_98:
	v_add_u32_e32 v143, s2, v142
	ds_read_b128 v[146:149], v143
	ds_read_b128 v[150:153], v143 offset:1024
	ds_read_b128 v[154:157], v143 offset:2048
	ds_read_b128 v[158:161], v143 offset:3072
	s_add_u32 s66, s55, s4
	s_addc_u32 s67, s57, s5
	s_add_i32 s63, s15, 0xc000
	ds_read_b128 v[162:165], v133
	ds_read_b128 v[184:187], v133 offset:1024
	ds_read_b128 v[188:191], v134
	ds_read_b128 v[192:195], v134 offset:1024
	ds_read_b128 v[196:199], v137
	ds_read_b128 v[200:203], v137 offset:1024
	ds_read_b128 v[204:207], v139
	ds_read_b128 v[208:211], v139 offset:1024
	s_mov_b32 m0, s63
	v_lshl_add_u64 v[144:145], s[66:67], 0, v[0:1]
	s_add_i32 s59, s15, 0xe000
	global_load_lds_dwordx4 v[144:145], off
	v_lshl_add_u64 v[144:145], s[66:67], 0, v[140:141]
	s_mov_b32 m0, s59
	s_nop 0
	global_load_lds_dwordx4 v[144:145], off
	s_waitcnt lgkmcnt(8)
	s_barrier
	s_waitcnt lgkmcnt(0)
	v_mfma_f32_16x16x32_bf16 v[126:129], v[162:165], v[146:149], v[126:129]
	v_mfma_f32_16x16x32_bf16 v[122:125], v[162:165], v[154:157], v[122:125]
	v_mfma_f32_16x16x32_bf16 v[118:121], v[188:191], v[146:149], v[118:121]
	v_mfma_f32_16x16x32_bf16 v[114:117], v[188:191], v[154:157], v[114:117]
	v_mfma_f32_16x16x32_bf16 v[110:113], v[196:199], v[146:149], v[110:113]
	v_mfma_f32_16x16x32_bf16 v[106:109], v[196:199], v[154:157], v[106:109]
	v_mfma_f32_16x16x32_bf16 v[102:105], v[204:207], v[146:149], v[102:105]
	v_mfma_f32_16x16x32_bf16 v[98:101], v[204:207], v[154:157], v[98:101]
	v_mfma_f32_16x16x32_bf16 v[126:129], v[184:187], v[150:153], v[126:129]
	v_mfma_f32_16x16x32_bf16 v[122:125], v[184:187], v[158:161], v[122:125]
	v_mfma_f32_16x16x32_bf16 v[118:121], v[192:195], v[150:153], v[118:121]
	v_mfma_f32_16x16x32_bf16 v[114:117], v[192:195], v[158:161], v[114:117]
	v_mfma_f32_16x16x32_bf16 v[110:113], v[200:203], v[150:153], v[110:113]
	v_mfma_f32_16x16x32_bf16 v[106:109], v[200:203], v[158:161], v[106:109]
	v_mfma_f32_16x16x32_bf16 v[102:105], v[208:211], v[150:153], v[102:105]
	v_mfma_f32_16x16x32_bf16 v[98:101], v[208:211], v[158:161], v[98:101]
	s_barrier
	v_add_u32_e32 v144, s76, v142
	ds_read_b128 v[212:215], v144
	ds_read_b128 v[216:219], v144 offset:1024
	ds_read_b128 v[220:223], v144 offset:2048
	ds_read_b128 v[224:227], v144 offset:3072
	s_add_i32 s58, s58, 2
	s_add_u32 s65, s50, s4
	s_addc_u32 s70, s51, s5
	s_add_u32 s66, s65, 0x100
	s_addc_u32 s67, s70, 0
	s_mov_b32 m0, s16
	s_nop 0
	v_lshl_add_u64 v[166:167], s[66:67], 0, v[0:1]
	global_load_lds_dwordx4 v[166:167], off
	v_lshl_add_u64 v[166:167], s[66:67], 0, v[140:141]
	s_mov_b32 m0, s17
	s_nop 0
	global_load_lds_dwordx4 v[166:167], off
	s_barrier
	s_waitcnt lgkmcnt(0)
	v_mfma_f32_16x16x32_bf16 v[94:97], v[162:165], v[212:215], v[94:97]
	v_mfma_f32_16x16x32_bf16 v[90:93], v[162:165], v[220:223], v[90:93]
	v_mfma_f32_16x16x32_bf16 v[86:89], v[188:191], v[212:215], v[86:89]
	v_mfma_f32_16x16x32_bf16 v[82:85], v[188:191], v[220:223], v[82:85]
	v_mfma_f32_16x16x32_bf16 v[78:81], v[196:199], v[212:215], v[78:81]
	v_mfma_f32_16x16x32_bf16 v[74:77], v[196:199], v[220:223], v[74:77]
	v_mfma_f32_16x16x32_bf16 v[70:73], v[204:207], v[212:215], v[70:73]
	v_mfma_f32_16x16x32_bf16 v[66:69], v[204:207], v[220:223], v[66:69]
	v_mfma_f32_16x16x32_bf16 v[94:97], v[184:187], v[216:219], v[94:97]
	v_mfma_f32_16x16x32_bf16 v[90:93], v[184:187], v[224:227], v[90:93]
	v_mfma_f32_16x16x32_bf16 v[86:89], v[192:195], v[216:219], v[86:89]
	v_mfma_f32_16x16x32_bf16 v[82:85], v[192:195], v[224:227], v[82:85]
	v_mfma_f32_16x16x32_bf16 v[78:81], v[200:203], v[216:219], v[78:81]
	v_mfma_f32_16x16x32_bf16 v[74:77], v[200:203], v[224:227], v[74:77]
	v_mfma_f32_16x16x32_bf16 v[70:73], v[208:211], v[216:219], v[70:73]
	v_mfma_f32_16x16x32_bf16 v[66:69], v[208:211], v[224:227], v[66:69]
	s_barrier
	ds_read_b128 v[162:165], v133 offset:16384
	ds_read_b128 v[184:187], v133 offset:17408
	ds_read_b128 v[188:191], v134 offset:16384
	ds_read_b128 v[192:195], v134 offset:17408
	ds_read_b128 v[196:199], v137 offset:16384
	ds_read_b128 v[200:203], v137 offset:17408
	ds_read_b128 v[204:207], v139 offset:16384
	ds_read_b128 v[208:211], v139 offset:17408
	s_add_u32 s71, s44, s4
	s_addc_u32 s72, s45, s5
	s_add_u32 s66, s71, 0x100
	s_addc_u32 s67, s72, 0
	s_mov_b32 m0, s15
	s_nop 0
	v_lshl_add_u64 v[166:167], s[66:67], 0, v[0:1]
	global_load_lds_dwordx4 v[166:167], off
	v_lshl_add_u64 v[166:167], s[66:67], 0, v[140:141]
	s_mov_b32 m0, s18
	s_nop 0
	global_load_lds_dwordx4 v[166:167], off
	s_barrier
	s_waitcnt lgkmcnt(0)
	v_mfma_f32_16x16x32_bf16 v[62:65], v[162:165], v[146:149], v[62:65]
	v_mfma_f32_16x16x32_bf16 v[58:61], v[162:165], v[154:157], v[58:61]
	v_mfma_f32_16x16x32_bf16 v[54:57], v[188:191], v[146:149], v[54:57]
	v_mfma_f32_16x16x32_bf16 v[50:53], v[188:191], v[154:157], v[50:53]
	v_mfma_f32_16x16x32_bf16 v[46:49], v[196:199], v[146:149], v[46:49]
	v_mfma_f32_16x16x32_bf16 v[42:45], v[196:199], v[154:157], v[42:45]
	v_mfma_f32_16x16x32_bf16 v[38:41], v[204:207], v[146:149], v[38:41]
	v_mfma_f32_16x16x32_bf16 v[34:37], v[204:207], v[154:157], v[34:37]
	v_mfma_f32_16x16x32_bf16 v[62:65], v[184:187], v[150:153], v[62:65]
	v_mfma_f32_16x16x32_bf16 v[58:61], v[184:187], v[158:161], v[58:61]
	v_mfma_f32_16x16x32_bf16 v[54:57], v[192:195], v[150:153], v[54:57]
	v_mfma_f32_16x16x32_bf16 v[50:53], v[192:195], v[158:161], v[50:53]
	v_mfma_f32_16x16x32_bf16 v[46:49], v[200:203], v[150:153], v[46:49]
	v_mfma_f32_16x16x32_bf16 v[42:45], v[200:203], v[158:161], v[42:45]
	v_mfma_f32_16x16x32_bf16 v[38:41], v[208:211], v[150:153], v[38:41]
	v_mfma_f32_16x16x32_bf16 v[34:37], v[208:211], v[158:161], v[34:37]
	s_barrier
; #define LDA(dst, b, h) for (int m = 0; m < 4; ++m) for (int k = 0; k < 2; ++k) \
;     dst[m][k] = *reinterpret_cast<const bf16x8*>((char*)SA(b, h) + lds_byte(wr * 64 + m * 16 + fr, k * 32 + fq * 8))
; #define LDB(dst, b, h) for (int n = 0; n < 2; ++n) for (int k = 0; k < 2; ++k) \
;     dst[n][k] = *reinterpret_cast<const bf16x8*>((char*)SB(b, h) + lds_byte(wc * 32 + n * 16 + fr, k * 32 + fq * 8))
; #define MMA(ai, bj, At, Bt_) do { __builtin_amdgcn_s_setprio(1); \
;     for (int m = 0; m < 4; ++m) for (int n = 0; n < 2; ++n) for (int k = 0; k < 2; ++k) \
;       acc[ai][bj][m][n] = __builtin_amdgcn_mfma_f32_16x16x32_bf16(At[m][k], Bt_[n][k], acc[ai][bj][m][n], 0, 0, 0); \
;     __builtin_amdgcn_s_setprio(0); } while (0)
; #define WAIT_V(n) asm volatile("s_waitcnt vmcnt(" #n ")" ::: "memory")
; #define WAIT_L(n) asm volatile("s_waitcnt lgkmcnt(" #n ")" ::: "memory")
; #define BAR __builtin_amdgcn_s_barrier()
; #define SCHED __builtin_amdgcn_sched_barrier(0)
;     ...
;       WAIT_V(6); BAR; MMA(1, 1, At, B1); BAR;
;       LDB(B0, 1, 0); SCHED; LDA(At, 1, 0); STAGE(SA(0, 1), A, brow + HALF, t + 2);
;       WAIT_L(8); BAR; WAIT_L(0); MMA(0, 0, At, B0); BAR; SCHED;
;       LDB(B1, 1, 1); STAGE(SB(1, 0), Bt, bcol, t + 3);
;       BAR; WAIT_L(0); MMA(0, 1, At, B1); BAR;
;       LDA(At, 1, 1); STAGE(SA(1, 0), A, brow, t + 3);
;       BAR; WAIT_L(0); MMA(1, 0, At, B0); BAR; SCHED;
	s_add_u32 s73, s6, s4
	s_addc_u32 s82, s7, s5
	s_add_u32 s66, s73, 0x160100
	s_addc_u32 s67, s82, 0
	s_mov_b32 m0, s19
	s_nop 0
	v_lshl_add_u64 v[146:147], s[66:67], 0, v[0:1]
	global_load_lds_dwordx4 v[146:147], off
	v_lshl_add_u64 v[146:147], s[66:67], 0, v[140:141]
	s_mov_b32 m0, s21
	s_nop 0
	global_load_lds_dwordx4 v[146:147], off
	s_waitcnt vmcnt(6)
	s_barrier
	v_mfma_f32_16x16x32_bf16 v[30:33], v[162:165], v[212:215], v[30:33]
	v_mfma_f32_16x16x32_bf16 v[26:29], v[162:165], v[220:223], v[26:29]
	v_mfma_f32_16x16x32_bf16 v[22:25], v[188:191], v[212:215], v[22:25]
	v_mfma_f32_16x16x32_bf16 v[18:21], v[188:191], v[220:223], v[18:21]
	v_mfma_f32_16x16x32_bf16 v[14:17], v[196:199], v[212:215], v[14:17]
	v_mfma_f32_16x16x32_bf16 v[10:13], v[196:199], v[220:223], v[10:13]
	v_mfma_f32_16x16x32_bf16 v[6:9], v[204:207], v[212:215], v[6:9]
	v_mfma_f32_16x16x32_bf16 v[2:5], v[204:207], v[220:223], v[2:5]
	v_mfma_f32_16x16x32_bf16 v[30:33], v[184:187], v[216:219], v[30:33]
	v_mfma_f32_16x16x32_bf16 v[26:29], v[184:187], v[224:227], v[26:29]
	v_mfma_f32_16x16x32_bf16 v[22:25], v[192:195], v[216:219], v[22:25]
	v_mfma_f32_16x16x32_bf16 v[18:21], v[192:195], v[224:227], v[18:21]
	v_mfma_f32_16x16x32_bf16 v[14:17], v[200:203], v[216:219], v[14:17]
	v_mfma_f32_16x16x32_bf16 v[10:13], v[200:203], v[224:227], v[10:13]
	v_mfma_f32_16x16x32_bf16 v[6:9], v[208:211], v[216:219], v[6:9]
	v_mfma_f32_16x16x32_bf16 v[2:5], v[208:211], v[224:227], v[2:5]
	s_barrier
	v_add_u32_e32 v145, s77, v142
	ds_read_b128 v[148:151], v145
	ds_read_b128 v[152:155], v145 offset:1024
	ds_read_b128 v[156:159], v145 offset:2048
	ds_read_b128 v[160:163], v145 offset:3072
	s_add_u32 s66, s71, 0x160100
	s_addc_u32 s67, s72, 0
	s_mov_b32 m0, s30
	ds_read_b128 v[164:167], v133 offset:32768
	ds_read_b128 v[184:187], v133 offset:33792
	ds_read_b128 v[188:191], v134 offset:32768
	ds_read_b128 v[192:195], v134 offset:33792
	ds_read_b128 v[196:199], v137 offset:32768
	ds_read_b128 v[200:203], v137 offset:33792
	ds_read_b128 v[204:207], v139 offset:32768
	ds_read_b128 v[208:211], v139 offset:33792
	s_nop 0
	v_lshl_add_u64 v[146:147], s[66:67], 0, v[0:1]
	global_load_lds_dwordx4 v[146:147], off
	v_lshl_add_u64 v[146:147], s[66:67], 0, v[140:141]
	s_mov_b32 m0, s31
	s_nop 0
	global_load_lds_dwordx4 v[146:147], off
	s_waitcnt lgkmcnt(8)
	s_barrier
	s_waitcnt lgkmcnt(0)
	v_mfma_f32_16x16x32_bf16 v[126:129], v[164:167], v[148:151], v[126:129]
	v_mfma_f32_16x16x32_bf16 v[122:125], v[164:167], v[156:159], v[122:125]
	v_mfma_f32_16x16x32_bf16 v[118:121], v[188:191], v[148:151], v[118:121]
	v_mfma_f32_16x16x32_bf16 v[114:117], v[188:191], v[156:159], v[114:117]
	v_mfma_f32_16x16x32_bf16 v[110:113], v[196:199], v[148:151], v[110:113]
	v_mfma_f32_16x16x32_bf16 v[106:109], v[196:199], v[156:159], v[106:109]
	v_mfma_f32_16x16x32_bf16 v[102:105], v[204:207], v[148:151], v[102:105]
	v_mfma_f32_16x16x32_bf16 v[98:101], v[204:207], v[156:159], v[98:101]
	v_mfma_f32_16x16x32_bf16 v[126:129], v[184:187], v[152:155], v[126:129]
	v_mfma_f32_16x16x32_bf16 v[122:125], v[184:187], v[160:163], v[122:125]
	v_mfma_f32_16x16x32_bf16 v[118:121], v[192:195], v[152:155], v[118:121]
	v_mfma_f32_16x16x32_bf16 v[114:117], v[192:195], v[160:163], v[114:117]
	v_mfma_f32_16x16x32_bf16 v[110:113], v[200:203], v[152:155], v[110:113]
	v_mfma_f32_16x16x32_bf16 v[106:109], v[200:203], v[160:163], v[106:109]
	v_mfma_f32_16x16x32_bf16 v[102:105], v[208:211], v[152:155], v[102:105]
	v_mfma_f32_16x16x32_bf16 v[98:101], v[208:211], v[160:163], v[98:101]
	s_barrier
	v_add_u32_e32 v146, s78, v142
	ds_read_b128 v[212:215], v146
	ds_read_b128 v[216:219], v146 offset:1024
	ds_read_b128 v[220:223], v146 offset:2048
	ds_read_b128 v[224:227], v146 offset:3072
	s_add_u32 s66, s65, 0x180
	s_addc_u32 s67, s70, 0
	s_mov_b32 m0, s34
	s_nop 0
	v_lshl_add_u64 v[228:229], s[66:67], 0, v[0:1]
	global_load_lds_dwordx4 v[228:229], off
	v_lshl_add_u64 v[228:229], s[66:67], 0, v[140:141]
	s_mov_b32 m0, s35
	s_nop 0
	global_load_lds_dwordx4 v[228:229], off
	s_barrier
	s_waitcnt lgkmcnt(0)
	v_mfma_f32_16x16x32_bf16 v[94:97], v[164:167], v[212:215], v[94:97]
	v_mfma_f32_16x16x32_bf16 v[90:93], v[164:167], v[220:223], v[90:93]
	v_mfma_f32_16x16x32_bf16 v[86:89], v[188:191], v[212:215], v[86:89]
	v_mfma_f32_16x16x32_bf16 v[82:85], v[188:191], v[220:223], v[82:85]
	v_mfma_f32_16x16x32_bf16 v[78:81], v[196:199], v[212:215], v[78:81]
	v_mfma_f32_16x16x32_bf16 v[74:77], v[196:199], v[220:223], v[74:77]
	v_mfma_f32_16x16x32_bf16 v[70:73], v[204:207], v[212:215], v[70:73]
	v_mfma_f32_16x16x32_bf16 v[66:69], v[204:207], v[220:223], v[66:69]
	v_mfma_f32_16x16x32_bf16 v[94:97], v[184:187], v[216:219], v[94:97]
	v_mfma_f32_16x16x32_bf16 v[90:93], v[184:187], v[224:227], v[90:93]
	v_mfma_f32_16x16x32_bf16 v[86:89], v[192:195], v[216:219], v[86:89]
	v_mfma_f32_16x16x32_bf16 v[82:85], v[192:195], v[224:227], v[82:85]
	v_mfma_f32_16x16x32_bf16 v[78:81], v[200:203], v[216:219], v[78:81]
	v_mfma_f32_16x16x32_bf16 v[74:77], v[200:203], v[224:227], v[74:77]
	v_mfma_f32_16x16x32_bf16 v[70:73], v[208:211], v[216:219], v[70:73]
	v_mfma_f32_16x16x32_bf16 v[66:69], v[208:211], v[224:227], v[66:69]
	s_barrier
	ds_read_b128 v[164:167], v133 offset:49152
	ds_read_b128 v[184:187], v133 offset:50176
	ds_read_b128 v[188:191], v134 offset:49152
	ds_read_b128 v[192:195], v134 offset:50176
	ds_read_b128 v[196:199], v137 offset:49152
	ds_read_b128 v[200:203], v137 offset:50176
	ds_read_b128 v[204:207], v139 offset:49152
	ds_read_b128 v[208:211], v139 offset:50176
	s_add_u32 s66, s71, 0x180
	s_addc_u32 s67, s72, 0
	s_mov_b32 m0, s37
	s_nop 0
	v_lshl_add_u64 v[228:229], s[66:67], 0, v[0:1]
	global_load_lds_dwordx4 v[228:229], off
	v_lshl_add_u64 v[228:229], s[66:67], 0, v[140:141]
	s_mov_b32 m0, s38
	s_nop 0
	global_load_lds_dwordx4 v[228:229], off
	s_barrier
; #define LDA(dst, b, h) for (int m = 0; m < 4; ++m) for (int k = 0; k < 2; ++k) \
;     dst[m][k] = *reinterpret_cast<const bf16x8*>((char*)SA(b, h) + lds_byte(wr * 64 + m * 16 + fr, k * 32 + fq * 8))
; #define LDB(dst, b, h) for (int n = 0; n < 2; ++n) for (int k = 0; k < 2; ++k) \
;     dst[n][k] = *reinterpret_cast<const bf16x8*>((char*)SB(b, h) + lds_byte(wc * 32 + n * 16 + fr, k * 32 + fq * 8))
; #define MMA(ai, bj, At, Bt_) do { __builtin_amdgcn_s_setprio(1); \
;     for (int m = 0; m < 4; ++m) for (int n = 0; n < 2; ++n) for (int k = 0; k < 2; ++k) \
;       acc[ai][bj][m][n] = __builtin_amdgcn_mfma_f32_16x16x32_bf16(At[m][k], Bt_[n][k], acc[ai][bj][m][n], 0, 0, 0); \
;     __builtin_amdgcn_s_setprio(0); } while (0)
; #define WAIT_V(n) asm volatile("s_waitcnt vmcnt(" #n ")" ::: "memory")
; #define WAIT_L(n) asm volatile("s_waitcnt lgkmcnt(" #n ")" ::: "memory")
; #define BAR __builtin_amdgcn_s_barrier()
; #define SCHED __builtin_amdgcn_sched_barrier(0)
;     ...
;       BAR; WAIT_L(0); MMA(1, 0, At, B0); BAR; SCHED;
;       STAGE(SB(1, 1), Bt, bcol + HALF, t + 3);
;       WAIT_V(6); BAR; MMA(1, 1, At, B1); BAR;
;     }
;     { LDB(B0, 0, 0); LDA(At, 0, 0); STAGE(SA(1, 1), A, brow + HALF, nt - 1);
;       BAR; WAIT_L(0); MMA(0, 0, At, B0); BAR;
;       LDB(B1, 0, 1); BAR; WAIT_L(0); MMA(0, 1, At, B1); BAR;
	s_waitcnt lgkmcnt(0)
	v_mfma_f32_16x16x32_bf16 v[62:65], v[164:167], v[148:151], v[62:65]
	v_mfma_f32_16x16x32_bf16 v[58:61], v[164:167], v[156:159], v[58:61]
	v_mfma_f32_16x16x32_bf16 v[54:57], v[188:191], v[148:151], v[54:57]
	v_mfma_f32_16x16x32_bf16 v[50:53], v[188:191], v[156:159], v[50:53]
	v_mfma_f32_16x16x32_bf16 v[46:49], v[196:199], v[148:151], v[46:49]
	v_mfma_f32_16x16x32_bf16 v[42:45], v[196:199], v[156:159], v[42:45]
	v_mfma_f32_16x16x32_bf16 v[38:41], v[204:207], v[148:151], v[38:41]
	v_mfma_f32_16x16x32_bf16 v[34:37], v[204:207], v[156:159], v[34:37]
	v_mfma_f32_16x16x32_bf16 v[62:65], v[184:187], v[152:155], v[62:65]
	v_mfma_f32_16x16x32_bf16 v[58:61], v[184:187], v[160:163], v[58:61]
	v_mfma_f32_16x16x32_bf16 v[54:57], v[192:195], v[152:155], v[54:57]
	v_mfma_f32_16x16x32_bf16 v[50:53], v[192:195], v[160:163], v[50:53]
	v_mfma_f32_16x16x32_bf16 v[46:49], v[200:203], v[152:155], v[46:49]
	v_mfma_f32_16x16x32_bf16 v[42:45], v[200:203], v[160:163], v[42:45]
	v_mfma_f32_16x16x32_bf16 v[38:41], v[208:211], v[152:155], v[38:41]
	v_mfma_f32_16x16x32_bf16 v[34:37], v[208:211], v[160:163], v[34:37]
	s_barrier
	s_add_u32 s66, s73, 0x160180
	s_addc_u32 s67, s82, 0
	s_mov_b32 m0, s41
	s_nop 0
	v_lshl_add_u64 v[148:149], s[66:67], 0, v[0:1]
	global_load_lds_dwordx4 v[148:149], off
	v_lshl_add_u64 v[148:149], s[66:67], 0, v[140:141]
	s_mov_b32 m0, s42
	s_nop 0
	global_load_lds_dwordx4 v[148:149], off
	s_add_u32 s6, s6, 0x100
	s_addc_u32 s7, s7, 0
	s_add_u32 s44, s44, 0x100
	s_addc_u32 s45, s45, 0
	s_add_u32 s50, s50, 0x100
	s_addc_u32 s51, s51, 0
	s_add_u32 s55, s55, 0x100
	s_addc_u32 s57, s57, 0
	s_cmp_ge_u32 s58, s43
	s_waitcnt vmcnt(6)
	s_barrier
	v_mfma_f32_16x16x32_bf16 v[30:33], v[164:167], v[212:215], v[30:33]
	v_mfma_f32_16x16x32_bf16 v[26:29], v[164:167], v[220:223], v[26:29]
	v_mfma_f32_16x16x32_bf16 v[22:25], v[188:191], v[212:215], v[22:25]
	v_mfma_f32_16x16x32_bf16 v[18:21], v[188:191], v[220:223], v[18:21]
	v_mfma_f32_16x16x32_bf16 v[14:17], v[196:199], v[212:215], v[14:17]
	v_mfma_f32_16x16x32_bf16 v[10:13], v[196:199], v[220:223], v[10:13]
	v_mfma_f32_16x16x32_bf16 v[6:9], v[204:207], v[212:215], v[6:9]
	v_mfma_f32_16x16x32_bf16 v[2:5], v[204:207], v[220:223], v[2:5]
	v_mfma_f32_16x16x32_bf16 v[30:33], v[184:187], v[216:219], v[30:33]
	v_mfma_f32_16x16x32_bf16 v[26:29], v[184:187], v[224:227], v[26:29]
	v_mfma_f32_16x16x32_bf16 v[22:25], v[192:195], v[216:219], v[22:25]
	v_mfma_f32_16x16x32_bf16 v[18:21], v[192:195], v[224:227], v[18:21]
	v_mfma_f32_16x16x32_bf16 v[14:17], v[200:203], v[216:219], v[14:17]
	v_mfma_f32_16x16x32_bf16 v[10:13], v[200:203], v[224:227], v[10:13]
	v_mfma_f32_16x16x32_bf16 v[6:9], v[208:211], v[216:219], v[6:9]
	v_mfma_f32_16x16x32_bf16 v[2:5], v[208:211], v[224:227], v[2:5]
	s_barrier
	s_cbranch_scc0 .LBB0_98
	s_add_i32 s4, s48, s14
	s_add_i32 s48, s4, -1
	s_lshl_b64 s[4:5], s[48:49], 7
	s_add_u32 s4, s22, s4
	s_addc_u32 s5, s23, s5
	s_add_u32 s4, s4, s40
	s_addc_u32 s5, s5, s39
	s_mov_b32 m0, s63
	ds_read_b128 v[148:151], v143
	ds_read_b128 v[152:155], v143 offset:1024
	ds_read_b128 v[156:159], v143 offset:2048
	ds_read_b128 v[160:163], v143 offset:3072
	ds_read_b128 v[164:167], v133
	ds_read_b128 v[184:187], v133 offset:1024
	ds_read_b128 v[188:191], v134
	ds_read_b128 v[192:195], v134 offset:1024
	ds_read_b128 v[196:199], v137
	ds_read_b128 v[200:203], v137 offset:1024
	ds_read_b128 v[204:207], v139
	ds_read_b128 v[208:211], v139 offset:1024
	s_nop 0
	v_lshl_add_u64 v[142:143], s[4:5], 0, v[0:1]
	global_load_lds_dwordx4 v[142:143], off
	v_lshl_add_u64 v[140:141], s[4:5], 0, v[140:141]
	s_mov_b32 m0, s59
	s_nop 0
	global_load_lds_dwordx4 v[140:141], off
	s_barrier
	s_waitcnt lgkmcnt(0)
	s_setprio 1
	s_waitcnt lgkmcnt(0)
	v_mfma_f32_16x16x32_bf16 v[126:129], v[164:167], v[148:151], v[126:129]
	v_mfma_f32_16x16x32_bf16 v[122:125], v[164:167], v[156:159], v[122:125]
	v_mfma_f32_16x16x32_bf16 v[118:121], v[188:191], v[148:151], v[118:121]
	v_mfma_f32_16x16x32_bf16 v[110:113], v[196:199], v[148:151], v[110:113]
	v_mfma_f32_16x16x32_bf16 v[106:109], v[196:199], v[156:159], v[106:109]
	v_mfma_f32_16x16x32_bf16 v[102:105], v[204:207], v[148:151], v[102:105]
	v_mfma_f32_16x16x32_bf16 v[98:101], v[204:207], v[156:159], v[98:101]
	v_mfma_f32_16x16x32_bf16 v[126:129], v[184:187], v[152:155], v[126:129]
	v_mfma_f32_16x16x32_bf16 v[122:125], v[184:187], v[160:163], v[122:125]
	v_mfma_f32_16x16x32_bf16 v[118:121], v[192:195], v[152:155], v[118:121]
	v_mfma_f32_16x16x32_bf16 v[114:117], v[188:191], v[156:159], v[114:117]
	v_mfma_f32_16x16x32_bf16 v[110:113], v[200:203], v[152:155], v[110:113]
	v_mfma_f32_16x16x32_bf16 v[106:109], v[200:203], v[160:163], v[106:109]
	v_mfma_f32_16x16x32_bf16 v[102:105], v[208:211], v[152:155], v[102:105]
	v_mfma_f32_16x16x32_bf16 v[98:101], v[208:211], v[160:163], v[98:101]
	v_mfma_f32_16x16x32_bf16 v[140:143], v[192:195], v[160:163], v[114:117]
	s_setprio 0
	s_barrier
	s_nop 0
	ds_read_b128 v[114:117], v144
	ds_read_b128 v[212:215], v144 offset:1024
	ds_read_b128 v[216:219], v144 offset:2048
	ds_read_b128 v[220:223], v144 offset:3072
	s_barrier
; #define LDA(dst, b, h) for (int m = 0; m < 4; ++m) for (int k = 0; k < 2; ++k) \
;     dst[m][k] = *reinterpret_cast<const bf16x8*>((char*)SA(b, h) + lds_byte(wr * 64 + m * 16 + fr, k * 32 + fq * 8))
; #define LDB(dst, b, h) for (int n = 0; n < 2; ++n) for (int k = 0; k < 2; ++k) \
;     dst[n][k] = *reinterpret_cast<const bf16x8*>((char*)SB(b, h) + lds_byte(wc * 32 + n * 16 + fr, k * 32 + fq * 8))
; #define MMA(ai, bj, At, Bt_) do { __builtin_amdgcn_s_setprio(1); \
;     for (int m = 0; m < 4; ++m) for (int n = 0; n < 2; ++n) for (int k = 0; k < 2; ++k) \
;       acc[ai][bj][m][n] = __builtin_amdgcn_mfma_f32_16x16x32_bf16(At[m][k], Bt_[n][k], acc[ai][bj][m][n], 0, 0, 0); \
;     __builtin_amdgcn_s_setprio(0); } while (0)
; #define WAIT_V(n) asm volatile("s_waitcnt vmcnt(" #n ")" ::: "memory")
; #define WAIT_L(n) asm volatile("s_waitcnt lgkmcnt(" #n ")" ::: "memory")
; #define BAR __builtin_amdgcn_s_barrier()
;     ...
;       LDB(B1, 0, 1); BAR; WAIT_L(0); MMA(0, 1, At, B1); BAR;
;       LDA(At, 0, 1); WAIT_V(4); BAR; WAIT_L(0); MMA(1, 0, At, B0); MMA(1, 1, At, B1); BAR; }
;     { LDB(B0, 1, 0); LDA(At, 1, 0); WAIT_V(2); BAR; WAIT_L(0); MMA(0, 0, At, B0); BAR;
	s_waitcnt lgkmcnt(0)
	s_setprio 1
	s_waitcnt lgkmcnt(0)
	v_mfma_f32_16x16x32_bf16 v[90:93], v[164:167], v[216:219], v[90:93]
	v_mfma_f32_16x16x32_bf16 v[86:89], v[188:191], v[114:117], v[86:89]
	v_mfma_f32_16x16x32_bf16 v[94:97], v[164:167], v[114:117], v[94:97]
	v_mfma_f32_16x16x32_bf16 v[90:93], v[184:187], v[220:223], v[90:93]
	v_mfma_f32_16x16x32_bf16 v[86:89], v[192:195], v[212:215], v[86:89]
	v_mfma_f32_16x16x32_bf16 v[82:85], v[188:191], v[216:219], v[82:85]
	v_mfma_f32_16x16x32_bf16 v[78:81], v[196:199], v[114:117], v[78:81]
	v_mfma_f32_16x16x32_bf16 v[74:77], v[196:199], v[216:219], v[74:77]
	v_mfma_f32_16x16x32_bf16 v[70:73], v[204:207], v[114:117], v[70:73]
	v_mfma_f32_16x16x32_bf16 v[66:69], v[204:207], v[216:219], v[66:69]
	v_mfma_f32_16x16x32_bf16 v[224:227], v[184:187], v[212:215], v[94:97]
	v_mfma_f32_16x16x32_bf16 v[164:167], v[192:195], v[220:223], v[82:85]
	v_mfma_f32_16x16x32_bf16 v[184:187], v[200:203], v[212:215], v[78:81]
	v_mfma_f32_16x16x32_bf16 v[188:191], v[200:203], v[220:223], v[74:77]
	v_mfma_f32_16x16x32_bf16 v[192:195], v[208:211], v[212:215], v[70:73]
	v_mfma_f32_16x16x32_bf16 v[196:199], v[208:211], v[220:223], v[66:69]
	s_setprio 0
	s_barrier
	s_nop 0
	ds_read_b128 v[66:69], v133 offset:16384
	ds_read_b128 v[70:73], v133 offset:17408
	ds_read_b128 v[74:77], v134 offset:16384
	ds_read_b128 v[78:81], v134 offset:17408
	ds_read_b128 v[82:85], v137 offset:16384
	ds_read_b128 v[94:97], v137 offset:17408
	ds_read_b128 v[200:203], v139 offset:16384
	ds_read_b128 v[204:207], v139 offset:17408
	s_waitcnt vmcnt(4)
	s_barrier
	s_waitcnt lgkmcnt(0)
	s_setprio 1
	s_waitcnt lgkmcnt(0)
	v_mfma_f32_16x16x32_bf16 v[62:65], v[66:69], v[148:151], v[62:65]
	v_mfma_f32_16x16x32_bf16 v[58:61], v[66:69], v[156:159], v[58:61]
	v_mfma_f32_16x16x32_bf16 v[54:57], v[74:77], v[148:151], v[54:57]
	v_mfma_f32_16x16x32_bf16 v[50:53], v[74:77], v[156:159], v[50:53]
	v_mfma_f32_16x16x32_bf16 v[46:49], v[82:85], v[148:151], v[46:49]
	v_mfma_f32_16x16x32_bf16 v[42:45], v[82:85], v[156:159], v[42:45]
	v_mfma_f32_16x16x32_bf16 v[38:41], v[200:203], v[148:151], v[38:41]
	v_mfma_f32_16x16x32_bf16 v[34:37], v[200:203], v[156:159], v[34:37]
	v_mfma_f32_16x16x32_bf16 v[62:65], v[70:73], v[152:155], v[62:65]
	v_mfma_f32_16x16x32_bf16 v[58:61], v[70:73], v[160:163], v[58:61]
	v_mfma_f32_16x16x32_bf16 v[54:57], v[78:81], v[152:155], v[54:57]
	v_mfma_f32_16x16x32_bf16 v[50:53], v[78:81], v[160:163], v[50:53]
	v_mfma_f32_16x16x32_bf16 v[46:49], v[94:97], v[152:155], v[46:49]
	v_mfma_f32_16x16x32_bf16 v[42:45], v[94:97], v[160:163], v[42:45]
	v_mfma_f32_16x16x32_bf16 v[38:41], v[204:207], v[152:155], v[38:41]
	v_mfma_f32_16x16x32_bf16 v[34:37], v[204:207], v[160:163], v[34:37]
	s_setprio 0
	s_setprio 1
	v_mfma_f32_16x16x32_bf16 v[30:33], v[66:69], v[114:117], v[30:33]
	v_mfma_f32_16x16x32_bf16 v[26:29], v[66:69], v[216:219], v[26:29]
	v_mfma_f32_16x16x32_bf16 v[22:25], v[74:77], v[114:117], v[22:25]
	v_mfma_f32_16x16x32_bf16 v[18:21], v[74:77], v[216:219], v[18:21]
	v_mfma_f32_16x16x32_bf16 v[14:17], v[82:85], v[114:117], v[14:17]
	v_mfma_f32_16x16x32_bf16 v[10:13], v[82:85], v[216:219], v[10:13]
	v_mfma_f32_16x16x32_bf16 v[6:9], v[200:203], v[114:117], v[6:9]
	v_mfma_f32_16x16x32_bf16 v[2:5], v[200:203], v[216:219], v[2:5]
	v_mfma_f32_16x16x32_bf16 v[148:151], v[70:73], v[212:215], v[30:33]
	v_mfma_f32_16x16x32_bf16 v[152:155], v[70:73], v[220:223], v[26:29]
	v_mfma_f32_16x16x32_bf16 v[156:159], v[78:81], v[212:215], v[22:25]
	v_mfma_f32_16x16x32_bf16 v[160:163], v[78:81], v[220:223], v[18:21]
	v_mfma_f32_16x16x32_bf16 v[208:211], v[94:97], v[212:215], v[14:17]
	v_mfma_f32_16x16x32_bf16 v[228:231], v[94:97], v[220:223], v[10:13]
	v_mfma_f32_16x16x32_bf16 v[212:215], v[204:207], v[212:215], v[6:9]
	v_mfma_f32_16x16x32_bf16 v[200:203], v[204:207], v[220:223], v[2:5]
	s_setprio 0
	s_barrier
	ds_read_b128 v[14:17], v145
	ds_read_b128 v[30:33], v145 offset:1024
	ds_read_b128 v[204:207], v145 offset:2048
	ds_read_b128 v[216:219], v145 offset:3072
	ds_read_b128 v[2:5], v133 offset:32768
	ds_read_b128 v[6:9], v133 offset:33792
	ds_read_b128 v[10:13], v134 offset:32768
	ds_read_b128 v[18:21], v134 offset:33792
	ds_read_b128 v[22:25], v137 offset:32768
	ds_read_b128 v[26:29], v137 offset:33792
	ds_read_b128 v[220:223], v139 offset:32768
	ds_read_b128 v[232:235], v139 offset:33792
	s_waitcnt vmcnt(2)
	s_barrier
; #define LDA(dst, b, h) for (int m = 0; m < 4; ++m) for (int k = 0; k < 2; ++k) \
;     dst[m][k] = *reinterpret_cast<const bf16x8*>((char*)SA(b, h) + lds_byte(wr * 64 + m * 16 + fr, k * 32 + fq * 8))
; #define LDB(dst, b, h) for (int n = 0; n < 2; ++n) for (int k = 0; k < 2; ++k) \
;     dst[n][k] = *reinterpret_cast<const bf16x8*>((char*)SB(b, h) + lds_byte(wc * 32 + n * 16 + fr, k * 32 + fq * 8))
; #define MMA(ai, bj, At, Bt_) do { __builtin_amdgcn_s_setprio(1); \
;     for (int m = 0; m < 4; ++m) for (int n = 0; n < 2; ++n) for (int k = 0; k < 2; ++k) \
;       acc[ai][bj][m][n] = __builtin_amdgcn_mfma_f32_16x16x32_bf16(At[m][k], Bt_[n][k], acc[ai][bj][m][n], 0, 0, 0); \
;     __builtin_amdgcn_s_setprio(0); } while (0)
; #define WAIT_V(n) asm volatile("s_waitcnt vmcnt(" #n ")" ::: "memory")
; #define WAIT_L(n) asm volatile("s_waitcnt lgkmcnt(" #n ")" ::: "memory")
; #define BAR __builtin_amdgcn_s_barrier()
;     ...
;     { LDB(B0, 1, 0); LDA(At, 1, 0); WAIT_V(2); BAR; WAIT_L(0); MMA(0, 0, At, B0); BAR;
;       LDB(B1, 1, 1); WAIT_V(0); BAR; WAIT_L(0); MMA(0, 1, At, B1); BAR;
;       LDA(At, 1, 1); BAR; WAIT_L(0); MMA(1, 0, At, B0); MMA(1, 1, At, B1); BAR; }
;     if (wr == 0) BAR;
	s_waitcnt lgkmcnt(0)
	s_setprio 1
	s_waitcnt lgkmcnt(0)
	v_mfma_f32_16x16x32_bf16 v[66:69], v[2:5], v[14:17], v[126:129]
	v_mfma_f32_16x16x32_bf16 v[114:117], v[6:9], v[30:33], v[66:69]
	v_mfma_f32_16x16x32_bf16 v[66:69], v[2:5], v[204:207], v[122:125]
	v_mfma_f32_16x16x32_bf16 v[126:129], v[6:9], v[216:219], v[66:69]
	v_mfma_f32_16x16x32_bf16 v[66:69], v[10:13], v[14:17], v[118:121]
	v_mfma_f32_16x16x32_bf16 v[82:85], v[18:21], v[30:33], v[66:69]
	v_mfma_f32_16x16x32_bf16 v[66:69], v[10:13], v[204:207], v[140:143]
	v_mfma_f32_16x16x32_bf16 v[94:97], v[18:21], v[216:219], v[66:69]
	v_mfma_f32_16x16x32_bf16 v[66:69], v[22:25], v[14:17], v[110:113]
	v_mfma_f32_16x16x32_bf16 v[74:77], v[26:29], v[30:33], v[66:69]
	v_mfma_f32_16x16x32_bf16 v[66:69], v[22:25], v[204:207], v[106:109]
	v_mfma_f32_16x16x32_bf16 v[78:81], v[26:29], v[216:219], v[66:69]
	v_mfma_f32_16x16x32_bf16 v[66:69], v[220:223], v[14:17], v[102:105]
	v_mfma_f32_16x16x32_bf16 v[70:73], v[220:223], v[204:207], v[98:101]
	v_mfma_f32_16x16x32_bf16 v[66:69], v[232:235], v[30:33], v[66:69]
	v_mfma_f32_16x16x32_bf16 v[70:73], v[232:235], v[216:219], v[70:73]
	s_setprio 0
	s_barrier
	ds_read_b128 v[140:143], v146
	ds_read_b128 v[236:239], v146 offset:1024
	ds_read_b128 v[240:243], v146 offset:2048
	ds_read_b128 v[144:147], v146 offset:3072
	s_waitcnt vmcnt(0)
	s_barrier
	s_waitcnt lgkmcnt(0)
	s_setprio 1
	s_waitcnt lgkmcnt(0)
	v_mfma_f32_16x16x32_bf16 v[98:101], v[2:5], v[140:143], v[224:227]
	v_mfma_f32_16x16x32_bf16 v[2:5], v[2:5], v[240:243], v[90:93]
	v_mfma_f32_16x16x32_bf16 v[118:121], v[6:9], v[144:147], v[2:5]
	v_mfma_f32_16x16x32_bf16 v[2:5], v[10:13], v[140:143], v[86:89]
	v_mfma_f32_16x16x32_bf16 v[102:105], v[18:21], v[236:239], v[2:5]
	v_mfma_f32_16x16x32_bf16 v[2:5], v[10:13], v[240:243], v[164:167]
	v_mfma_f32_16x16x32_bf16 v[122:125], v[18:21], v[144:147], v[2:5]
	v_mfma_f32_16x16x32_bf16 v[2:5], v[22:25], v[140:143], v[184:187]
	v_mfma_f32_16x16x32_bf16 v[90:93], v[26:29], v[236:239], v[2:5]
	v_mfma_f32_16x16x32_bf16 v[2:5], v[22:25], v[240:243], v[188:191]
	v_mfma_f32_16x16x32_bf16 v[110:113], v[26:29], v[144:147], v[2:5]
	v_mfma_f32_16x16x32_bf16 v[2:5], v[220:223], v[140:143], v[192:195]
	v_mfma_f32_16x16x32_bf16 v[86:89], v[232:235], v[236:239], v[2:5]
	v_mfma_f32_16x16x32_bf16 v[2:5], v[220:223], v[240:243], v[196:199]
	v_mfma_f32_16x16x32_bf16 v[98:101], v[6:9], v[236:239], v[98:101]
	v_mfma_f32_16x16x32_bf16 v[106:109], v[232:235], v[144:147], v[2:5]
	s_setprio 0
	s_barrier
	ds_read_b128 v[164:167], v133 offset:49152
	ds_read_b128 v[184:187], v133 offset:50176
	ds_read_b128 v[188:191], v134 offset:49152
	ds_read_b128 v[192:195], v134 offset:50176
	ds_read_b128 v[196:199], v137 offset:49152
	ds_read_b128 v[220:223], v137 offset:50176
	ds_read_b128 v[224:227], v139 offset:49152
	ds_read_b128 v[232:235], v139 offset:50176
	s_barrier
	s_waitcnt lgkmcnt(0)
	s_setprio 1
	s_waitcnt lgkmcnt(0)
	v_mfma_f32_16x16x32_bf16 v[6:9], v[164:167], v[204:207], v[58:61]
	v_mfma_f32_16x16x32_bf16 v[10:13], v[188:191], v[204:207], v[50:53]
	v_mfma_f32_16x16x32_bf16 v[2:5], v[164:167], v[14:17], v[62:65]
	v_mfma_f32_16x16x32_bf16 v[18:21], v[184:187], v[216:219], v[6:9]
	v_mfma_f32_16x16x32_bf16 v[6:9], v[188:191], v[14:17], v[54:57]
	v_mfma_f32_16x16x32_bf16 v[22:25], v[192:195], v[216:219], v[10:13]
	v_mfma_f32_16x16x32_bf16 v[10:13], v[196:199], v[14:17], v[46:49]
	v_mfma_f32_16x16x32_bf16 v[14:17], v[224:227], v[14:17], v[38:41]
	v_mfma_f32_16x16x32_bf16 v[2:5], v[184:187], v[30:33], v[2:5]
	v_mfma_f32_16x16x32_bf16 v[6:9], v[192:195], v[30:33], v[6:9]
	v_mfma_f32_16x16x32_bf16 v[10:13], v[220:223], v[30:33], v[10:13]
	v_mfma_f32_16x16x32_bf16 v[26:29], v[196:199], v[204:207], v[42:45]
	v_mfma_f32_16x16x32_bf16 v[14:17], v[232:235], v[30:33], v[14:17]
	v_mfma_f32_16x16x32_bf16 v[30:33], v[224:227], v[204:207], v[34:37]
	v_mfma_f32_16x16x32_bf16 v[26:29], v[220:223], v[216:219], v[26:29]
	v_mfma_f32_16x16x32_bf16 v[30:33], v[232:235], v[216:219], v[30:33]
	s_setprio 0
	s_setprio 1
	v_mfma_f32_16x16x32_bf16 v[38:41], v[164:167], v[240:243], v[152:155]
	v_mfma_f32_16x16x32_bf16 v[42:45], v[188:191], v[240:243], v[160:163]
	v_mfma_f32_16x16x32_bf16 v[46:49], v[196:199], v[240:243], v[228:231]
	v_mfma_f32_16x16x32_bf16 v[34:37], v[164:167], v[140:143], v[148:151]
	v_mfma_f32_16x16x32_bf16 v[50:53], v[184:187], v[144:147], v[38:41]
	v_mfma_f32_16x16x32_bf16 v[38:41], v[188:191], v[140:143], v[156:159]
	v_mfma_f32_16x16x32_bf16 v[54:57], v[192:195], v[144:147], v[42:45]
	v_mfma_f32_16x16x32_bf16 v[42:45], v[196:199], v[140:143], v[208:211]
	v_mfma_f32_16x16x32_bf16 v[58:61], v[220:223], v[144:147], v[46:49]
	v_mfma_f32_16x16x32_bf16 v[46:49], v[224:227], v[140:143], v[212:215]
	v_mfma_f32_16x16x32_bf16 v[62:65], v[224:227], v[240:243], v[200:203]
	v_mfma_f32_16x16x32_bf16 v[34:37], v[184:187], v[236:239], v[34:37]
	v_mfma_f32_16x16x32_bf16 v[38:41], v[192:195], v[236:239], v[38:41]
	v_mfma_f32_16x16x32_bf16 v[42:45], v[220:223], v[236:239], v[42:45]
	v_mfma_f32_16x16x32_bf16 v[46:49], v[232:235], v[236:239], v[46:49]
	v_mfma_f32_16x16x32_bf16 v[62:65], v[232:235], v[144:147], v[62:65]
	s_setprio 0
	v_readlane_b32 s4, v245, 33
	v_readlane_b32 s5, v245, 34
	s_and_b64 vcc, exec, s[4:5]
	s_barrier
	s_cbranch_vccz .LBB0_101
	s_barrier

; #define LDA(dst, b, h) for (int m = 0; m < 4; ++m) for (int k = 0; k < 2; ++k) \
;     dst[m][k] = *reinterpret_cast<const bf16x8*>((char*)SA(b, h) + lds_byte(wr * 64 + m * 16 + fr, k * 32 + fq * 8))
; #define LDB(dst, b, h) for (int n = 0; n < 2; ++n) for (int k = 0; k < 2; ++k) \
;     dst[n][k] = *reinterpret_cast<const bf16x8*>((char*)SB(b, h) + lds_byte(wc * 32 + n * 16 + fr, k * 32 + fq * 8))
; #define MMA(ai, bj, At, Bt_) do { __builtin_amdgcn_s_setprio(1); \
;     for (int m = 0; m < 4; ++m) for (int n = 0; n < 2; ++n) for (int k = 0; k < 2; ++k) \
;       acc[ai][bj][m][n] = __builtin_amdgcn_mfma_f32_16x16x32_bf16(At[m][k], Bt_[n][k], acc[ai][bj][m][n], 0, 0, 0); \
;     __builtin_amdgcn_s_setprio(0); } while (0)
; #define WAIT_V(n) asm volatile("s_waitcnt vmcnt(" #n ")" ::: "memory")
; #define WAIT_L(n) asm volatile("s_waitcnt lgkmcnt(" #n ")" ::: "memory")
; #define BAR __builtin_amdgcn_s_barrier()
; #define SCHED __builtin_amdgcn_sched_barrier(0)
;     ...
;     for (int t = 0; t < nt - 2; t += 2) {
;       LDB(B0, 0, 0); SCHED; LDA(At, 0, 0); STAGE(SA(1, 1), A, brow + HALF, t + 1);
;       WAIT_L(8); BAR; WAIT_L(0); MMA(0, 0, At, B0); BAR; SCHED;
;       LDB(B1, 0, 1); STAGE(SB(0, 0), Bt, bcol, t + 2);
;       BAR; WAIT_L(0); MMA(0, 1, At, B1); BAR;
;       LDA(At, 0, 1); STAGE(SA(0, 0), A, brow, t + 2);
;       BAR; WAIT_L(0); MMA(1, 0, At, B0); BAR; SCHED;
;       STAGE(SB(0, 1), Bt, bcol + HALF, t + 2);
;       WAIT_V(6); BAR; MMA(1, 1, At, B1); BAR;
;       LDB(B0, 1, 0); SCHED; LDA(At, 1, 0); STAGE(SA(0, 1), A, brow + HALF, t + 2);
;       WAIT_L(8); BAR; WAIT_L(0); MMA(0, 0, At, B0); BAR; SCHED;
;       LDB(B1, 1, 1); STAGE(SB(1, 0), Bt, bcol, t + 3);
;       BAR; WAIT_L(0); MMA(0, 1, At, B1); BAR;
;       LDA(At, 1, 1); STAGE(SA(1, 0), A, brow, t + 3);
;       BAR; WAIT_L(0); MMA(1, 0, At, B0); BAR; SCHED;
;       STAGE(SB(1, 1), Bt, bcol + HALF, t + 3);
;       WAIT_V(6); BAR; MMA(1, 1, At, B1); BAR;
;     }
.LBB0_155:
	v_add_u32_e32 v143, s2, v142
	ds_read_b128 v[146:149], v143
	ds_read_b128 v[150:153], v143 offset:1024
	ds_read_b128 v[154:157], v143 offset:2048
	ds_read_b128 v[158:161], v143 offset:3072
	s_add_u32 s40, s30, s10
	s_addc_u32 s41, s31, s11
	s_add_u32 s42, s40, 0x80080
	s_addc_u32 s43, s41, 0
	s_add_i32 s39, s24, 0xc000
	ds_read_b128 v[162:165], v133
	ds_read_b128 v[184:187], v133 offset:1024
	ds_read_b128 v[188:191], v134
	ds_read_b128 v[192:195], v134 offset:1024
	ds_read_b128 v[196:199], v137
	ds_read_b128 v[200:203], v137 offset:1024
	ds_read_b128 v[204:207], v139
	ds_read_b128 v[208:211], v139 offset:1024
	s_mov_b32 m0, s39
	v_lshl_add_u64 v[144:145], s[42:43], 0, v[0:1]
	s_add_i32 s38, s24, 0xe000
	global_load_lds_dwordx4 v[144:145], off
	v_lshl_add_u64 v[144:145], s[42:43], 0, v[140:141]
	s_mov_b32 m0, s38
	s_nop 0
	global_load_lds_dwordx4 v[144:145], off
	s_waitcnt lgkmcnt(8)
	s_barrier
	s_waitcnt lgkmcnt(0)
	v_mfma_f32_16x16x32_bf16 v[126:129], v[162:165], v[146:149], v[126:129]
	v_mfma_f32_16x16x32_bf16 v[122:125], v[162:165], v[154:157], v[122:125]
	v_mfma_f32_16x16x32_bf16 v[118:121], v[188:191], v[146:149], v[118:121]
	v_mfma_f32_16x16x32_bf16 v[114:117], v[188:191], v[154:157], v[114:117]
	v_mfma_f32_16x16x32_bf16 v[110:113], v[196:199], v[146:149], v[110:113]
	v_mfma_f32_16x16x32_bf16 v[106:109], v[196:199], v[154:157], v[106:109]
	v_mfma_f32_16x16x32_bf16 v[102:105], v[204:207], v[146:149], v[102:105]
	v_mfma_f32_16x16x32_bf16 v[98:101], v[204:207], v[154:157], v[98:101]
	v_mfma_f32_16x16x32_bf16 v[126:129], v[184:187], v[150:153], v[126:129]
	v_mfma_f32_16x16x32_bf16 v[122:125], v[184:187], v[158:161], v[122:125]
	v_mfma_f32_16x16x32_bf16 v[118:121], v[192:195], v[150:153], v[118:121]
	v_mfma_f32_16x16x32_bf16 v[114:117], v[192:195], v[158:161], v[114:117]
	v_mfma_f32_16x16x32_bf16 v[110:113], v[200:203], v[150:153], v[110:113]
	v_mfma_f32_16x16x32_bf16 v[106:109], v[200:203], v[158:161], v[106:109]
	v_mfma_f32_16x16x32_bf16 v[102:105], v[208:211], v[150:153], v[102:105]
	v_mfma_f32_16x16x32_bf16 v[98:101], v[208:211], v[158:161], v[98:101]
	s_barrier
	v_add_u32_e32 v144, s76, v142
	ds_read_b128 v[212:215], v144
	ds_read_b128 v[216:219], v144 offset:1024
	ds_read_b128 v[220:223], v144 offset:2048
	ds_read_b128 v[224:227], v144 offset:3072
	s_add_u32 s42, s34, s10
	s_addc_u32 s43, s35, s11
	s_add_u32 s44, s42, 0x100
	s_addc_u32 s45, s43, 0
	s_mov_b32 m0, s25
	s_nop 0
	v_lshl_add_u64 v[166:167], s[44:45], 0, v[0:1]
	global_load_lds_dwordx4 v[166:167], off
	v_lshl_add_u64 v[166:167], s[44:45], 0, v[140:141]
	s_mov_b32 m0, s26
	s_nop 0
	global_load_lds_dwordx4 v[166:167], off
	s_barrier
	s_waitcnt lgkmcnt(0)
	v_mfma_f32_16x16x32_bf16 v[94:97], v[162:165], v[212:215], v[94:97]
	v_mfma_f32_16x16x32_bf16 v[90:93], v[162:165], v[220:223], v[90:93]
	v_mfma_f32_16x16x32_bf16 v[86:89], v[188:191], v[212:215], v[86:89]
	v_mfma_f32_16x16x32_bf16 v[82:85], v[188:191], v[220:223], v[82:85]
	v_mfma_f32_16x16x32_bf16 v[78:81], v[196:199], v[212:215], v[78:81]
	v_mfma_f32_16x16x32_bf16 v[74:77], v[196:199], v[220:223], v[74:77]
	v_mfma_f32_16x16x32_bf16 v[70:73], v[204:207], v[212:215], v[70:73]
	v_mfma_f32_16x16x32_bf16 v[66:69], v[204:207], v[220:223], v[66:69]
	v_mfma_f32_16x16x32_bf16 v[94:97], v[184:187], v[216:219], v[94:97]
	v_mfma_f32_16x16x32_bf16 v[90:93], v[184:187], v[224:227], v[90:93]
	v_mfma_f32_16x16x32_bf16 v[86:89], v[192:195], v[216:219], v[86:89]
	v_mfma_f32_16x16x32_bf16 v[82:85], v[192:195], v[224:227], v[82:85]
	v_mfma_f32_16x16x32_bf16 v[78:81], v[200:203], v[216:219], v[78:81]
	v_mfma_f32_16x16x32_bf16 v[74:77], v[200:203], v[224:227], v[74:77]
	v_mfma_f32_16x16x32_bf16 v[70:73], v[208:211], v[216:219], v[70:73]
	v_mfma_f32_16x16x32_bf16 v[66:69], v[208:211], v[224:227], v[66:69]
	s_barrier
	ds_read_b128 v[162:165], v133 offset:16384
	ds_read_b128 v[184:187], v133 offset:17408
	ds_read_b128 v[188:191], v134 offset:16384
	ds_read_b128 v[192:195], v134 offset:17408
	ds_read_b128 v[196:199], v137 offset:16384
	ds_read_b128 v[200:203], v137 offset:17408
	ds_read_b128 v[204:207], v139 offset:16384
	ds_read_b128 v[208:211], v139 offset:17408
	s_add_u32 s44, s40, 0x100
	s_addc_u32 s45, s41, 0
	s_mov_b32 m0, s24
	s_nop 0
	v_lshl_add_u64 v[166:167], s[44:45], 0, v[0:1]
	global_load_lds_dwordx4 v[166:167], off
	v_lshl_add_u64 v[166:167], s[44:45], 0, v[140:141]
	s_mov_b32 m0, s9
	s_nop 0
	global_load_lds_dwordx4 v[166:167], off
	s_barrier
	s_waitcnt lgkmcnt(0)
	v_mfma_f32_16x16x32_bf16 v[62:65], v[162:165], v[146:149], v[62:65]
	v_mfma_f32_16x16x32_bf16 v[58:61], v[162:165], v[154:157], v[58:61]
	v_mfma_f32_16x16x32_bf16 v[54:57], v[188:191], v[146:149], v[54:57]
	v_mfma_f32_16x16x32_bf16 v[50:53], v[188:191], v[154:157], v[50:53]
	v_mfma_f32_16x16x32_bf16 v[46:49], v[196:199], v[146:149], v[46:49]
	v_mfma_f32_16x16x32_bf16 v[42:45], v[196:199], v[154:157], v[42:45]
	v_mfma_f32_16x16x32_bf16 v[38:41], v[204:207], v[146:149], v[38:41]
	v_mfma_f32_16x16x32_bf16 v[34:37], v[204:207], v[154:157], v[34:37]
	v_mfma_f32_16x16x32_bf16 v[62:65], v[184:187], v[150:153], v[62:65]
	v_mfma_f32_16x16x32_bf16 v[58:61], v[184:187], v[158:161], v[58:61]
	v_mfma_f32_16x16x32_bf16 v[54:57], v[192:195], v[150:153], v[54:57]
	v_mfma_f32_16x16x32_bf16 v[50:53], v[192:195], v[158:161], v[50:53]
	v_mfma_f32_16x16x32_bf16 v[46:49], v[200:203], v[150:153], v[46:49]
	v_mfma_f32_16x16x32_bf16 v[42:45], v[200:203], v[158:161], v[42:45]
	v_mfma_f32_16x16x32_bf16 v[38:41], v[208:211], v[150:153], v[38:41]
	v_mfma_f32_16x16x32_bf16 v[34:37], v[208:211], v[158:161], v[34:37]
	s_barrier
; #define LDA(dst, b, h) for (int m = 0; m < 4; ++m) for (int k = 0; k < 2; ++k) \
;     dst[m][k] = *reinterpret_cast<const bf16x8*>((char*)SA(b, h) + lds_byte(wr * 64 + m * 16 + fr, k * 32 + fq * 8))
; #define LDB(dst, b, h) for (int n = 0; n < 2; ++n) for (int k = 0; k < 2; ++k) \
;     dst[n][k] = *reinterpret_cast<const bf16x8*>((char*)SB(b, h) + lds_byte(wc * 32 + n * 16 + fr, k * 32 + fq * 8))
; #define MMA(ai, bj, At, Bt_) do { __builtin_amdgcn_s_setprio(1); \
;     for (int m = 0; m < 4; ++m) for (int n = 0; n < 2; ++n) for (int k = 0; k < 2; ++k) \
;       acc[ai][bj][m][n] = __builtin_amdgcn_mfma_f32_16x16x32_bf16(At[m][k], Bt_[n][k], acc[ai][bj][m][n], 0, 0, 0); \
;     __builtin_amdgcn_s_setprio(0); } while (0)
; #define WAIT_V(n) asm volatile("s_waitcnt vmcnt(" #n ")" ::: "memory")
; #define WAIT_L(n) asm volatile("s_waitcnt lgkmcnt(" #n ")" ::: "memory")
; #define BAR __builtin_amdgcn_s_barrier()
; #define SCHED __builtin_amdgcn_sched_barrier(0)
;     ...
;     for (int t = 0; t < nt - 2; t += 2) {
;       LDB(B0, 0, 0); SCHED; LDA(At, 0, 0); STAGE(SA(1, 1), A, brow + HALF, t + 1);
;       WAIT_L(8); BAR; WAIT_L(0); MMA(0, 0, At, B0); BAR; SCHED;
;       LDB(B1, 0, 1); STAGE(SB(0, 0), Bt, bcol, t + 2);
;       BAR; WAIT_L(0); MMA(0, 1, At, B1); BAR;
;       LDA(At, 0, 1); STAGE(SA(0, 0), A, brow, t + 2);
;       BAR; WAIT_L(0); MMA(1, 0, At, B0); BAR; SCHED;
;       STAGE(SB(0, 1), Bt, bcol + HALF, t + 2);
;       WAIT_V(6); BAR; MMA(1, 1, At, B1); BAR;
;       LDB(B0, 1, 0); SCHED; LDA(At, 1, 0); STAGE(SA(0, 1), A, brow + HALF, t + 2);
;       WAIT_L(8); BAR; WAIT_L(0); MMA(0, 0, At, B0); BAR; SCHED;
;       LDB(B1, 1, 1); STAGE(SB(1, 0), Bt, bcol, t + 3);
;       BAR; WAIT_L(0); MMA(0, 1, At, B1); BAR;
;       LDA(At, 1, 1); STAGE(SA(1, 0), A, brow, t + 3);
;       BAR; WAIT_L(0); MMA(1, 0, At, B0); BAR; SCHED;
;       STAGE(SB(1, 1), Bt, bcol + HALF, t + 3);
;       WAIT_V(6); BAR; MMA(1, 1, At, B1); BAR;
;     }
	s_add_u32 s44, s42, 0x80100
	s_addc_u32 s45, s43, 0
	s_mov_b32 m0, s27
	s_nop 0
	v_lshl_add_u64 v[146:147], s[44:45], 0, v[0:1]
	global_load_lds_dwordx4 v[146:147], off
	v_lshl_add_u64 v[146:147], s[44:45], 0, v[140:141]
	s_mov_b32 m0, s28
	s_nop 0
	global_load_lds_dwordx4 v[146:147], off
	s_waitcnt vmcnt(6)
	s_barrier
	v_mfma_f32_16x16x32_bf16 v[30:33], v[162:165], v[212:215], v[30:33]
	v_mfma_f32_16x16x32_bf16 v[26:29], v[162:165], v[220:223], v[26:29]
	v_mfma_f32_16x16x32_bf16 v[22:25], v[188:191], v[212:215], v[22:25]
	v_mfma_f32_16x16x32_bf16 v[18:21], v[188:191], v[220:223], v[18:21]
	v_mfma_f32_16x16x32_bf16 v[14:17], v[196:199], v[212:215], v[14:17]
	v_mfma_f32_16x16x32_bf16 v[10:13], v[196:199], v[220:223], v[10:13]
	v_mfma_f32_16x16x32_bf16 v[6:9], v[204:207], v[212:215], v[6:9]
	v_mfma_f32_16x16x32_bf16 v[2:5], v[204:207], v[220:223], v[2:5]
	v_mfma_f32_16x16x32_bf16 v[30:33], v[184:187], v[216:219], v[30:33]
	v_mfma_f32_16x16x32_bf16 v[26:29], v[184:187], v[224:227], v[26:29]
	v_mfma_f32_16x16x32_bf16 v[22:25], v[192:195], v[216:219], v[22:25]
	v_mfma_f32_16x16x32_bf16 v[18:21], v[192:195], v[224:227], v[18:21]
	v_mfma_f32_16x16x32_bf16 v[14:17], v[200:203], v[216:219], v[14:17]
	v_mfma_f32_16x16x32_bf16 v[10:13], v[200:203], v[224:227], v[10:13]
	v_mfma_f32_16x16x32_bf16 v[6:9], v[208:211], v[216:219], v[6:9]
	v_mfma_f32_16x16x32_bf16 v[2:5], v[208:211], v[224:227], v[2:5]
	s_barrier
	v_add_u32_e32 v145, s77, v142
	ds_read_b128 v[148:151], v145
	ds_read_b128 v[152:155], v145 offset:1024
	ds_read_b128 v[156:159], v145 offset:2048
	ds_read_b128 v[160:163], v145 offset:3072
	s_add_u32 s44, s40, 0x80100
	s_addc_u32 s45, s41, 0
	s_mov_b32 m0, s7
	ds_read_b128 v[164:167], v133 offset:32768
	ds_read_b128 v[184:187], v133 offset:33792
	ds_read_b128 v[188:191], v134 offset:32768
	ds_read_b128 v[192:195], v134 offset:33792
	ds_read_b128 v[196:199], v137 offset:32768
	ds_read_b128 v[200:203], v137 offset:33792
	ds_read_b128 v[204:207], v139 offset:32768
	ds_read_b128 v[208:211], v139 offset:33792
	s_nop 0
	v_lshl_add_u64 v[146:147], s[44:45], 0, v[0:1]
	global_load_lds_dwordx4 v[146:147], off
	v_lshl_add_u64 v[146:147], s[44:45], 0, v[140:141]
	s_mov_b32 m0, s29
	s_nop 0
	global_load_lds_dwordx4 v[146:147], off
	s_waitcnt lgkmcnt(8)
	s_barrier
	s_waitcnt lgkmcnt(0)
	v_mfma_f32_16x16x32_bf16 v[126:129], v[164:167], v[148:151], v[126:129]
	v_mfma_f32_16x16x32_bf16 v[122:125], v[164:167], v[156:159], v[122:125]
	v_mfma_f32_16x16x32_bf16 v[118:121], v[188:191], v[148:151], v[118:121]
	v_mfma_f32_16x16x32_bf16 v[114:117], v[188:191], v[156:159], v[114:117]
	v_mfma_f32_16x16x32_bf16 v[110:113], v[196:199], v[148:151], v[110:113]
	v_mfma_f32_16x16x32_bf16 v[106:109], v[196:199], v[156:159], v[106:109]
	v_mfma_f32_16x16x32_bf16 v[102:105], v[204:207], v[148:151], v[102:105]
	v_mfma_f32_16x16x32_bf16 v[98:101], v[204:207], v[156:159], v[98:101]
	v_mfma_f32_16x16x32_bf16 v[126:129], v[184:187], v[152:155], v[126:129]
	v_mfma_f32_16x16x32_bf16 v[122:125], v[184:187], v[160:163], v[122:125]
	v_mfma_f32_16x16x32_bf16 v[118:121], v[192:195], v[152:155], v[118:121]
	v_mfma_f32_16x16x32_bf16 v[114:117], v[192:195], v[160:163], v[114:117]
	v_mfma_f32_16x16x32_bf16 v[110:113], v[200:203], v[152:155], v[110:113]
	v_mfma_f32_16x16x32_bf16 v[106:109], v[200:203], v[160:163], v[106:109]
	v_mfma_f32_16x16x32_bf16 v[102:105], v[208:211], v[152:155], v[102:105]
	v_mfma_f32_16x16x32_bf16 v[98:101], v[208:211], v[160:163], v[98:101]
	s_barrier
	v_add_u32_e32 v146, s78, v142
	ds_read_b128 v[212:215], v146
	ds_read_b128 v[216:219], v146 offset:1024
	ds_read_b128 v[220:223], v146 offset:2048
	ds_read_b128 v[224:227], v146 offset:3072
	s_add_u32 s44, s42, 0x180
	s_addc_u32 s45, s43, 0
	s_mov_b32 m0, s12
	s_nop 0
	v_lshl_add_u64 v[228:229], s[44:45], 0, v[0:1]
	global_load_lds_dwordx4 v[228:229], off
	v_lshl_add_u64 v[228:229], s[44:45], 0, v[140:141]
	s_mov_b32 m0, s13
	s_nop 0
	global_load_lds_dwordx4 v[228:229], off
	s_barrier
	s_waitcnt lgkmcnt(0)
	v_mfma_f32_16x16x32_bf16 v[94:97], v[164:167], v[212:215], v[94:97]
	v_mfma_f32_16x16x32_bf16 v[90:93], v[164:167], v[220:223], v[90:93]
	v_mfma_f32_16x16x32_bf16 v[86:89], v[188:191], v[212:215], v[86:89]
	v_mfma_f32_16x16x32_bf16 v[82:85], v[188:191], v[220:223], v[82:85]
	v_mfma_f32_16x16x32_bf16 v[78:81], v[196:199], v[212:215], v[78:81]
	v_mfma_f32_16x16x32_bf16 v[74:77], v[196:199], v[220:223], v[74:77]
	v_mfma_f32_16x16x32_bf16 v[70:73], v[204:207], v[212:215], v[70:73]
	v_mfma_f32_16x16x32_bf16 v[66:69], v[204:207], v[220:223], v[66:69]
	v_mfma_f32_16x16x32_bf16 v[94:97], v[184:187], v[216:219], v[94:97]
	v_mfma_f32_16x16x32_bf16 v[90:93], v[184:187], v[224:227], v[90:93]
	v_mfma_f32_16x16x32_bf16 v[86:89], v[192:195], v[216:219], v[86:89]
	v_mfma_f32_16x16x32_bf16 v[82:85], v[192:195], v[224:227], v[82:85]
	v_mfma_f32_16x16x32_bf16 v[78:81], v[200:203], v[216:219], v[78:81]
	v_mfma_f32_16x16x32_bf16 v[74:77], v[200:203], v[224:227], v[74:77]
	v_mfma_f32_16x16x32_bf16 v[70:73], v[208:211], v[216:219], v[70:73]
	v_mfma_f32_16x16x32_bf16 v[66:69], v[208:211], v[224:227], v[66:69]
	s_barrier
	ds_read_b128 v[164:167], v133 offset:49152
	ds_read_b128 v[184:187], v133 offset:50176
	ds_read_b128 v[188:191], v134 offset:49152
	ds_read_b128 v[192:195], v134 offset:50176
	ds_read_b128 v[196:199], v137 offset:49152
	ds_read_b128 v[200:203], v137 offset:50176
	ds_read_b128 v[204:207], v139 offset:49152
	ds_read_b128 v[208:211], v139 offset:50176
	s_add_u32 s40, s40, 0x180
	s_addc_u32 s41, s41, 0
	s_mov_b32 m0, s14
	s_nop 0
	v_lshl_add_u64 v[228:229], s[40:41], 0, v[0:1]
	global_load_lds_dwordx4 v[228:229], off
	v_lshl_add_u64 v[228:229], s[40:41], 0, v[140:141]
	s_mov_b32 m0, s15
	s_nop 0
	global_load_lds_dwordx4 v[228:229], off
	s_barrier
; #define LDA(dst, b, h) for (int m = 0; m < 4; ++m) for (int k = 0; k < 2; ++k) \
;     dst[m][k] = *reinterpret_cast<const bf16x8*>((char*)SA(b, h) + lds_byte(wr * 64 + m * 16 + fr, k * 32 + fq * 8))
; #define LDB(dst, b, h) for (int n = 0; n < 2; ++n) for (int k = 0; k < 2; ++k) \
;     dst[n][k] = *reinterpret_cast<const bf16x8*>((char*)SB(b, h) + lds_byte(wc * 32 + n * 16 + fr, k * 32 + fq * 8))
; #define MMA(ai, bj, At, Bt_) do { __builtin_amdgcn_s_setprio(1); \
;     for (int m = 0; m < 4; ++m) for (int n = 0; n < 2; ++n) for (int k = 0; k < 2; ++k) \
;       acc[ai][bj][m][n] = __builtin_amdgcn_mfma_f32_16x16x32_bf16(At[m][k], Bt_[n][k], acc[ai][bj][m][n], 0, 0, 0); \
;     __builtin_amdgcn_s_setprio(0); } while (0)
; #define WAIT_V(n) asm volatile("s_waitcnt vmcnt(" #n ")" ::: "memory")
; #define WAIT_L(n) asm volatile("s_waitcnt lgkmcnt(" #n ")" ::: "memory")
; #define BAR __builtin_amdgcn_s_barrier()
; #define SCHED __builtin_amdgcn_sched_barrier(0)
;     ...
;       WAIT_V(6); BAR; MMA(1, 1, At, B1); BAR;
;       LDB(B0, 1, 0); SCHED; LDA(At, 1, 0); STAGE(SA(0, 1), A, brow + HALF, t + 2);
;       WAIT_L(8); BAR; WAIT_L(0); MMA(0, 0, At, B0); BAR; SCHED;
;       LDB(B1, 1, 1); STAGE(SB(1, 0), Bt, bcol, t + 3);
;       BAR; WAIT_L(0); MMA(0, 1, At, B1); BAR;
;       LDA(At, 1, 1); STAGE(SA(1, 0), A, brow, t + 3);
;       BAR; WAIT_L(0); MMA(1, 0, At, B0); BAR; SCHED;
;       STAGE(SB(1, 1), Bt, bcol + HALF, t + 3);
;       WAIT_V(6); BAR; MMA(1, 1, At, B1); BAR;
;     }
;     { LDB(B0, 0, 0); LDA(At, 0, 0); STAGE(SA(1, 1), A, brow + HALF, nt - 1);
;       BAR; WAIT_L(0); MMA(0, 0, At, B0); BAR;
;       LDB(B1, 0, 1); BAR; WAIT_L(0); MMA(0, 1, At, B1); BAR;
;       LDA(At, 0, 1); WAIT_V(4); BAR; WAIT_L(0); MMA(1, 0, At, B0); MMA(1, 1, At, B1); BAR; }
;     { LDB(B0, 1, 0); LDA(At, 1, 0); WAIT_V(2); BAR; WAIT_L(0); MMA(0, 0, At, B0); BAR;
;       LDB(B1, 1, 1); WAIT_V(0); BAR; WAIT_L(0); MMA(0, 1, At, B1); BAR;
;       LDA(At, 1, 1); BAR; WAIT_L(0); MMA(1, 0, At, B0); MMA(1, 1, At, B1); BAR; }
	s_waitcnt lgkmcnt(0)
	v_mfma_f32_16x16x32_bf16 v[62:65], v[164:167], v[148:151], v[62:65]
	v_mfma_f32_16x16x32_bf16 v[58:61], v[164:167], v[156:159], v[58:61]
	v_mfma_f32_16x16x32_bf16 v[54:57], v[188:191], v[148:151], v[54:57]
	v_mfma_f32_16x16x32_bf16 v[50:53], v[188:191], v[156:159], v[50:53]
	v_mfma_f32_16x16x32_bf16 v[46:49], v[196:199], v[148:151], v[46:49]
	v_mfma_f32_16x16x32_bf16 v[42:45], v[196:199], v[156:159], v[42:45]
	v_mfma_f32_16x16x32_bf16 v[38:41], v[204:207], v[148:151], v[38:41]
	v_mfma_f32_16x16x32_bf16 v[34:37], v[204:207], v[156:159], v[34:37]
	v_mfma_f32_16x16x32_bf16 v[62:65], v[184:187], v[152:155], v[62:65]
	v_mfma_f32_16x16x32_bf16 v[58:61], v[184:187], v[160:163], v[58:61]
	v_mfma_f32_16x16x32_bf16 v[54:57], v[192:195], v[152:155], v[54:57]
	v_mfma_f32_16x16x32_bf16 v[50:53], v[192:195], v[160:163], v[50:53]
	v_mfma_f32_16x16x32_bf16 v[46:49], v[200:203], v[152:155], v[46:49]
	v_mfma_f32_16x16x32_bf16 v[42:45], v[200:203], v[160:163], v[42:45]
	v_mfma_f32_16x16x32_bf16 v[38:41], v[208:211], v[152:155], v[38:41]
	v_mfma_f32_16x16x32_bf16 v[34:37], v[208:211], v[160:163], v[34:37]
	s_barrier
	s_add_u32 s40, s42, 0x80180
	s_addc_u32 s41, s43, 0
	s_mov_b32 m0, s16
	s_nop 0
	v_lshl_add_u64 v[148:149], s[40:41], 0, v[0:1]
	global_load_lds_dwordx4 v[148:149], off
	v_lshl_add_u64 v[148:149], s[40:41], 0, v[140:141]
	s_mov_b32 m0, s17
	s_nop 0
	global_load_lds_dwordx4 v[148:149], off
	s_add_i32 s37, s37, 2
	s_add_u32 s10, s10, 0x100
	s_addc_u32 s11, s11, 0
	s_cmp_gt_u32 s37, 27
	s_waitcnt vmcnt(6)
	s_barrier
	v_mfma_f32_16x16x32_bf16 v[30:33], v[164:167], v[212:215], v[30:33]
	v_mfma_f32_16x16x32_bf16 v[26:29], v[164:167], v[220:223], v[26:29]
	v_mfma_f32_16x16x32_bf16 v[22:25], v[188:191], v[212:215], v[22:25]
	v_mfma_f32_16x16x32_bf16 v[18:21], v[188:191], v[220:223], v[18:21]
	v_mfma_f32_16x16x32_bf16 v[14:17], v[196:199], v[212:215], v[14:17]
	v_mfma_f32_16x16x32_bf16 v[10:13], v[196:199], v[220:223], v[10:13]
	v_mfma_f32_16x16x32_bf16 v[6:9], v[204:207], v[212:215], v[6:9]
	v_mfma_f32_16x16x32_bf16 v[2:5], v[204:207], v[220:223], v[2:5]
	v_mfma_f32_16x16x32_bf16 v[30:33], v[184:187], v[216:219], v[30:33]
	v_mfma_f32_16x16x32_bf16 v[26:29], v[184:187], v[224:227], v[26:29]
	v_mfma_f32_16x16x32_bf16 v[22:25], v[192:195], v[216:219], v[22:25]
	v_mfma_f32_16x16x32_bf16 v[18:21], v[192:195], v[224:227], v[18:21]
	v_mfma_f32_16x16x32_bf16 v[14:17], v[200:203], v[216:219], v[14:17]
	v_mfma_f32_16x16x32_bf16 v[10:13], v[200:203], v[224:227], v[10:13]
	v_mfma_f32_16x16x32_bf16 v[6:9], v[208:211], v[216:219], v[6:9]
	v_mfma_f32_16x16x32_bf16 v[2:5], v[208:211], v[224:227], v[2:5]
	s_barrier
	s_cbranch_scc0 .LBB0_155
	s_add_u32 s4, s4, 0xf80
	s_addc_u32 s5, s5, 0
	s_mov_b32 m0, s39
	ds_read_b128 v[148:151], v143
	ds_read_b128 v[152:155], v143 offset:1024
	ds_read_b128 v[156:159], v143 offset:2048
	ds_read_b128 v[160:163], v143 offset:3072
	ds_read_b128 v[164:167], v133
	ds_read_b128 v[184:187], v133 offset:1024
	ds_read_b128 v[188:191], v134
	ds_read_b128 v[192:195], v134 offset:1024
	ds_read_b128 v[196:199], v137
	ds_read_b128 v[200:203], v137 offset:1024
	ds_read_b128 v[204:207], v139
	ds_read_b128 v[208:211], v139 offset:1024
	s_nop 0
	v_lshl_add_u64 v[142:143], s[4:5], 0, v[0:1]
	global_load_lds_dwordx4 v[142:143], off
	v_lshl_add_u64 v[140:141], s[4:5], 0, v[140:141]
	s_mov_b32 m0, s38
	s_nop 0
	global_load_lds_dwordx4 v[140:141], off
	s_barrier
	s_waitcnt lgkmcnt(0)
	s_setprio 1
	s_waitcnt lgkmcnt(0)
	v_mfma_f32_16x16x32_bf16 v[126:129], v[164:167], v[148:151], v[126:129]
	v_mfma_f32_16x16x32_bf16 v[118:121], v[188:191], v[148:151], v[118:121]
	v_mfma_f32_16x16x32_bf16 v[110:113], v[196:199], v[148:151], v[110:113]
	v_mfma_f32_16x16x32_bf16 v[102:105], v[204:207], v[148:151], v[102:105]
	v_mfma_f32_16x16x32_bf16 v[126:129], v[184:187], v[152:155], v[126:129]
	v_mfma_f32_16x16x32_bf16 v[122:125], v[164:167], v[156:159], v[122:125]
	v_mfma_f32_16x16x32_bf16 v[118:121], v[192:195], v[152:155], v[118:121]
	v_mfma_f32_16x16x32_bf16 v[114:117], v[188:191], v[156:159], v[114:117]
	v_mfma_f32_16x16x32_bf16 v[110:113], v[200:203], v[152:155], v[110:113]
	v_mfma_f32_16x16x32_bf16 v[106:109], v[196:199], v[156:159], v[106:109]
	v_mfma_f32_16x16x32_bf16 v[102:105], v[208:211], v[152:155], v[102:105]
	v_mfma_f32_16x16x32_bf16 v[98:101], v[204:207], v[156:159], v[98:101]
	v_mfma_f32_16x16x32_bf16 v[140:143], v[184:187], v[160:163], v[122:125]
	v_mfma_f32_16x16x32_bf16 v[212:215], v[192:195], v[160:163], v[114:117]
	v_mfma_f32_16x16x32_bf16 v[216:219], v[200:203], v[160:163], v[106:109]
	v_mfma_f32_16x16x32_bf16 v[220:223], v[208:211], v[160:163], v[98:101]
	s_setprio 0
	s_barrier
	s_nop 1
	ds_read_b128 v[98:101], v144
	ds_read_b128 v[106:109], v144 offset:1024
	ds_read_b128 v[114:117], v144 offset:2048
	ds_read_b128 v[122:125], v144 offset:3072
	s_barrier
	s_waitcnt lgkmcnt(0)
	s_setprio 1
	s_waitcnt lgkmcnt(0)
	v_mfma_f32_16x16x32_bf16 v[94:97], v[164:167], v[98:101], v[94:97]
	v_mfma_f32_16x16x32_bf16 v[86:89], v[188:191], v[98:101], v[86:89]
	v_mfma_f32_16x16x32_bf16 v[78:81], v[196:199], v[98:101], v[78:81]
	v_mfma_f32_16x16x32_bf16 v[70:73], v[204:207], v[98:101], v[70:73]
	v_mfma_f32_16x16x32_bf16 v[94:97], v[184:187], v[106:109], v[94:97]
	v_mfma_f32_16x16x32_bf16 v[90:93], v[164:167], v[114:117], v[90:93]
	v_mfma_f32_16x16x32_bf16 v[86:89], v[192:195], v[106:109], v[86:89]
	v_mfma_f32_16x16x32_bf16 v[82:85], v[188:191], v[114:117], v[82:85]
	v_mfma_f32_16x16x32_bf16 v[78:81], v[200:203], v[106:109], v[78:81]
	v_mfma_f32_16x16x32_bf16 v[74:77], v[196:199], v[114:117], v[74:77]
	v_mfma_f32_16x16x32_bf16 v[70:73], v[208:211], v[106:109], v[70:73]
	v_mfma_f32_16x16x32_bf16 v[66:69], v[204:207], v[114:117], v[66:69]
	v_mfma_f32_16x16x32_bf16 v[164:167], v[184:187], v[122:125], v[90:93]
	v_mfma_f32_16x16x32_bf16 v[184:187], v[192:195], v[122:125], v[82:85]
	v_mfma_f32_16x16x32_bf16 v[188:191], v[200:203], v[122:125], v[74:77]
	v_mfma_f32_16x16x32_bf16 v[192:195], v[208:211], v[122:125], v[66:69]
	s_setprio 0
	s_barrier
; #define LDA(dst, b, h) for (int m = 0; m < 4; ++m) for (int k = 0; k < 2; ++k) \
;     dst[m][k] = *reinterpret_cast<const bf16x8*>((char*)SA(b, h) + lds_byte(wr * 64 + m * 16 + fr, k * 32 + fq * 8))
; #define LDB(dst, b, h) for (int n = 0; n < 2; ++n) for (int k = 0; k < 2; ++k) \
;     dst[n][k] = *reinterpret_cast<const bf16x8*>((char*)SB(b, h) + lds_byte(wc * 32 + n * 16 + fr, k * 32 + fq * 8))
; #define MMA(ai, bj, At, Bt_) do { __builtin_amdgcn_s_setprio(1); \
;     for (int m = 0; m < 4; ++m) for (int n = 0; n < 2; ++n) for (int k = 0; k < 2; ++k) \
;       acc[ai][bj][m][n] = __builtin_amdgcn_mfma_f32_16x16x32_bf16(At[m][k], Bt_[n][k], acc[ai][bj][m][n], 0, 0, 0); \
;     __builtin_amdgcn_s_setprio(0); } while (0)
; #define WAIT_V(n) asm volatile("s_waitcnt vmcnt(" #n ")" ::: "memory")
; #define WAIT_L(n) asm volatile("s_waitcnt lgkmcnt(" #n ")" ::: "memory")
; #define BAR __builtin_amdgcn_s_barrier()
;     ...
;       LDB(B1, 0, 1); BAR; WAIT_L(0); MMA(0, 1, At, B1); BAR;
;       LDA(At, 0, 1); WAIT_V(4); BAR; WAIT_L(0); MMA(1, 0, At, B0); MMA(1, 1, At, B1); BAR; }
;     { LDB(B0, 1, 0); LDA(At, 1, 0); WAIT_V(2); BAR; WAIT_L(0); MMA(0, 0, At, B0); BAR;
;       LDB(B1, 1, 1); WAIT_V(0); BAR; WAIT_L(0); MMA(0, 1, At, B1); BAR;
;       LDA(At, 1, 1); BAR; WAIT_L(0); MMA(1, 0, At, B0); MMA(1, 1, At, B1); BAR; }
	s_nop 1
	ds_read_b128 v[66:69], v133 offset:16384
	ds_read_b128 v[74:77], v133 offset:17408
	ds_read_b128 v[82:85], v134 offset:16384
	ds_read_b128 v[90:93], v134 offset:17408
	ds_read_b128 v[196:199], v137 offset:16384
	ds_read_b128 v[200:203], v137 offset:17408
	ds_read_b128 v[204:207], v139 offset:16384
	ds_read_b128 v[208:211], v139 offset:17408
	s_waitcnt vmcnt(4)
	s_barrier
	s_waitcnt lgkmcnt(0)
	s_setprio 1
	s_waitcnt lgkmcnt(0)
	v_mfma_f32_16x16x32_bf16 v[62:65], v[66:69], v[148:151], v[62:65]
	v_mfma_f32_16x16x32_bf16 v[54:57], v[82:85], v[148:151], v[54:57]
	v_mfma_f32_16x16x32_bf16 v[46:49], v[196:199], v[148:151], v[46:49]
	v_mfma_f32_16x16x32_bf16 v[38:41], v[204:207], v[148:151], v[38:41]
	v_mfma_f32_16x16x32_bf16 v[62:65], v[74:77], v[152:155], v[62:65]
	v_mfma_f32_16x16x32_bf16 v[58:61], v[66:69], v[156:159], v[58:61]
	v_mfma_f32_16x16x32_bf16 v[54:57], v[90:93], v[152:155], v[54:57]
	v_mfma_f32_16x16x32_bf16 v[50:53], v[82:85], v[156:159], v[50:53]
	v_mfma_f32_16x16x32_bf16 v[46:49], v[200:203], v[152:155], v[46:49]
	v_mfma_f32_16x16x32_bf16 v[42:45], v[196:199], v[156:159], v[42:45]
	v_mfma_f32_16x16x32_bf16 v[38:41], v[208:211], v[152:155], v[38:41]
	v_mfma_f32_16x16x32_bf16 v[34:37], v[204:207], v[156:159], v[34:37]
	v_mfma_f32_16x16x32_bf16 v[224:227], v[74:77], v[160:163], v[58:61]
	v_mfma_f32_16x16x32_bf16 v[228:231], v[90:93], v[160:163], v[50:53]
	v_mfma_f32_16x16x32_bf16 v[232:235], v[200:203], v[160:163], v[42:45]
	v_mfma_f32_16x16x32_bf16 v[148:151], v[208:211], v[160:163], v[34:37]
	s_setprio 0
	s_setprio 1
	v_mfma_f32_16x16x32_bf16 v[30:33], v[66:69], v[98:101], v[30:33]
	v_mfma_f32_16x16x32_bf16 v[22:25], v[82:85], v[98:101], v[22:25]
	v_mfma_f32_16x16x32_bf16 v[14:17], v[196:199], v[98:101], v[14:17]
	v_mfma_f32_16x16x32_bf16 v[6:9], v[204:207], v[98:101], v[6:9]
	v_mfma_f32_16x16x32_bf16 v[30:33], v[74:77], v[106:109], v[30:33]
	v_mfma_f32_16x16x32_bf16 v[26:29], v[66:69], v[114:117], v[26:29]
	v_mfma_f32_16x16x32_bf16 v[22:25], v[90:93], v[106:109], v[22:25]
	v_mfma_f32_16x16x32_bf16 v[18:21], v[82:85], v[114:117], v[18:21]
	v_mfma_f32_16x16x32_bf16 v[14:17], v[200:203], v[106:109], v[14:17]
	v_mfma_f32_16x16x32_bf16 v[10:13], v[196:199], v[114:117], v[10:13]
	v_mfma_f32_16x16x32_bf16 v[6:9], v[208:211], v[106:109], v[6:9]
	v_mfma_f32_16x16x32_bf16 v[2:5], v[204:207], v[114:117], v[2:5]
	v_mfma_f32_16x16x32_bf16 v[152:155], v[74:77], v[122:125], v[26:29]
	v_mfma_f32_16x16x32_bf16 v[156:159], v[90:93], v[122:125], v[18:21]
	v_mfma_f32_16x16x32_bf16 v[160:163], v[200:203], v[122:125], v[10:13]
	v_mfma_f32_16x16x32_bf16 v[196:199], v[208:211], v[122:125], v[2:5]
	s_setprio 0
	s_barrier
	s_nop 1
	ds_read_b128 v[2:5], v145
	ds_read_b128 v[10:13], v145 offset:1024
	ds_read_b128 v[200:203], v145 offset:2048
	ds_read_b128 v[204:207], v145 offset:3072
	ds_read_b128 v[18:21], v133 offset:32768
	ds_read_b128 v[26:29], v133 offset:33792
	ds_read_b128 v[34:37], v134 offset:32768
	ds_read_b128 v[42:45], v134 offset:33792
	ds_read_b128 v[50:53], v137 offset:32768
	ds_read_b128 v[58:61], v137 offset:33792
	ds_read_b128 v[208:211], v139 offset:32768
	ds_read_b128 v[236:239], v139 offset:33792
	s_waitcnt vmcnt(2)
	s_barrier
	s_waitcnt lgkmcnt(0)
	s_setprio 1
	s_waitcnt lgkmcnt(0)
	v_mfma_f32_16x16x32_bf16 v[66:69], v[18:21], v[2:5], v[126:129]
	v_mfma_f32_16x16x32_bf16 v[122:125], v[26:29], v[10:13], v[66:69]
	v_mfma_f32_16x16x32_bf16 v[66:69], v[18:21], v[200:203], v[140:143]
	v_mfma_f32_16x16x32_bf16 v[114:117], v[26:29], v[204:207], v[66:69]
	v_mfma_f32_16x16x32_bf16 v[66:69], v[34:37], v[2:5], v[118:121]
	v_mfma_f32_16x16x32_bf16 v[106:109], v[42:45], v[10:13], v[66:69]
	v_mfma_f32_16x16x32_bf16 v[66:69], v[34:37], v[200:203], v[212:215]
	v_mfma_f32_16x16x32_bf16 v[98:101], v[42:45], v[204:207], v[66:69]
	v_mfma_f32_16x16x32_bf16 v[66:69], v[50:53], v[2:5], v[110:113]
	v_mfma_f32_16x16x32_bf16 v[90:93], v[58:61], v[10:13], v[66:69]
	v_mfma_f32_16x16x32_bf16 v[66:69], v[50:53], v[200:203], v[216:219]
	v_mfma_f32_16x16x32_bf16 v[82:85], v[58:61], v[204:207], v[66:69]
	v_mfma_f32_16x16x32_bf16 v[66:69], v[208:211], v[2:5], v[102:105]
	v_mfma_f32_16x16x32_bf16 v[74:77], v[236:239], v[10:13], v[66:69]
	v_mfma_f32_16x16x32_bf16 v[66:69], v[208:211], v[200:203], v[220:223]
	v_mfma_f32_16x16x32_bf16 v[66:69], v[236:239], v[204:207], v[66:69]
	s_setprio 0
	s_barrier
; #define LDA(dst, b, h) for (int m = 0; m < 4; ++m) for (int k = 0; k < 2; ++k) \
;     dst[m][k] = *reinterpret_cast<const bf16x8*>((char*)SA(b, h) + lds_byte(wr * 64 + m * 16 + fr, k * 32 + fq * 8))
; #define LDB(dst, b, h) for (int n = 0; n < 2; ++n) for (int k = 0; k < 2; ++k) \
;     dst[n][k] = *reinterpret_cast<const bf16x8*>((char*)SB(b, h) + lds_byte(wc * 32 + n * 16 + fr, k * 32 + fq * 8))
; #define MMA(ai, bj, At, Bt_) do { __builtin_amdgcn_s_setprio(1); \
;     for (int m = 0; m < 4; ++m) for (int n = 0; n < 2; ++n) for (int k = 0; k < 2; ++k) \
;       acc[ai][bj][m][n] = __builtin_amdgcn_mfma_f32_16x16x32_bf16(At[m][k], Bt_[n][k], acc[ai][bj][m][n], 0, 0, 0); \
;     __builtin_amdgcn_s_setprio(0); } while (0)
; #define WAIT_V(n) asm volatile("s_waitcnt vmcnt(" #n ")" ::: "memory")
; #define WAIT_L(n) asm volatile("s_waitcnt lgkmcnt(" #n ")" ::: "memory")
; #define BAR __builtin_amdgcn_s_barrier()
;     ...
;     { LDB(B0, 1, 0); LDA(At, 1, 0); WAIT_V(2); BAR; WAIT_L(0); MMA(0, 0, At, B0); BAR;
;       LDB(B1, 1, 1); WAIT_V(0); BAR; WAIT_L(0); MMA(0, 1, At, B1); BAR;
;       LDA(At, 1, 1); BAR; WAIT_L(0); MMA(1, 0, At, B0); MMA(1, 1, At, B1); BAR; }
;     if (wr == 0) BAR;
	ds_read_b128 v[140:143], v146
	ds_read_b128 v[212:215], v146 offset:1024
	ds_read_b128 v[216:219], v146 offset:2048
	ds_read_b128 v[144:147], v146 offset:3072
	s_waitcnt vmcnt(0)
	s_barrier
	s_waitcnt lgkmcnt(0)
	s_setprio 1
	s_waitcnt lgkmcnt(0)
	v_mfma_f32_16x16x32_bf16 v[94:97], v[18:21], v[140:143], v[94:97]
	v_mfma_f32_16x16x32_bf16 v[18:21], v[18:21], v[216:219], v[164:167]
	v_mfma_f32_16x16x32_bf16 v[118:121], v[26:29], v[144:147], v[18:21]
	v_mfma_f32_16x16x32_bf16 v[18:21], v[34:37], v[140:143], v[86:89]
	v_mfma_f32_16x16x32_bf16 v[110:113], v[42:45], v[212:215], v[18:21]
	v_mfma_f32_16x16x32_bf16 v[18:21], v[34:37], v[216:219], v[184:187]
	v_mfma_f32_16x16x32_bf16 v[102:105], v[42:45], v[144:147], v[18:21]
	v_mfma_f32_16x16x32_bf16 v[18:21], v[50:53], v[140:143], v[78:81]
	v_mfma_f32_16x16x32_bf16 v[126:129], v[26:29], v[212:215], v[94:97]
	v_mfma_f32_16x16x32_bf16 v[94:97], v[58:61], v[212:215], v[18:21]
	v_mfma_f32_16x16x32_bf16 v[18:21], v[50:53], v[216:219], v[188:191]
	v_mfma_f32_16x16x32_bf16 v[86:89], v[58:61], v[144:147], v[18:21]
	v_mfma_f32_16x16x32_bf16 v[18:21], v[208:211], v[140:143], v[70:73]
	v_mfma_f32_16x16x32_bf16 v[78:81], v[236:239], v[212:215], v[18:21]
	v_mfma_f32_16x16x32_bf16 v[18:21], v[208:211], v[216:219], v[192:195]
	v_mfma_f32_16x16x32_bf16 v[70:73], v[236:239], v[144:147], v[18:21]
	s_setprio 0
	s_barrier
	ds_read_b128 v[164:167], v133 offset:49152
	ds_read_b128 v[184:187], v133 offset:50176
	ds_read_b128 v[188:191], v134 offset:49152
	ds_read_b128 v[192:195], v134 offset:50176
	ds_read_b128 v[208:211], v137 offset:49152
	ds_read_b128 v[220:223], v137 offset:50176
	ds_read_b128 v[236:239], v139 offset:49152
	ds_read_b128 v[240:243], v139 offset:50176
	s_barrier
	s_waitcnt lgkmcnt(0)
	s_setprio 1
	s_waitcnt lgkmcnt(0)
	v_mfma_f32_16x16x32_bf16 v[18:21], v[164:167], v[2:5], v[62:65]
	v_mfma_f32_16x16x32_bf16 v[58:61], v[184:187], v[10:13], v[18:21]
	v_mfma_f32_16x16x32_bf16 v[18:21], v[164:167], v[200:203], v[224:227]
	v_mfma_f32_16x16x32_bf16 v[50:53], v[184:187], v[204:207], v[18:21]
	v_mfma_f32_16x16x32_bf16 v[18:21], v[188:191], v[2:5], v[54:57]
	v_mfma_f32_16x16x32_bf16 v[42:45], v[192:195], v[10:13], v[18:21]
	v_mfma_f32_16x16x32_bf16 v[18:21], v[188:191], v[200:203], v[228:231]
	v_mfma_f32_16x16x32_bf16 v[34:37], v[192:195], v[204:207], v[18:21]
	v_mfma_f32_16x16x32_bf16 v[18:21], v[208:211], v[2:5], v[46:49]
	v_mfma_f32_16x16x32_bf16 v[2:5], v[236:239], v[2:5], v[38:41]
	v_mfma_f32_16x16x32_bf16 v[26:29], v[220:223], v[10:13], v[18:21]
	v_mfma_f32_16x16x32_bf16 v[18:21], v[208:211], v[200:203], v[232:235]
	v_mfma_f32_16x16x32_bf16 v[10:13], v[240:243], v[10:13], v[2:5]
	v_mfma_f32_16x16x32_bf16 v[2:5], v[236:239], v[200:203], v[148:151]
	v_mfma_f32_16x16x32_bf16 v[18:21], v[220:223], v[204:207], v[18:21]
	v_mfma_f32_16x16x32_bf16 v[2:5], v[240:243], v[204:207], v[2:5]
	s_setprio 0
	s_setprio 1
	v_mfma_f32_16x16x32_bf16 v[30:33], v[164:167], v[140:143], v[30:33]
	v_mfma_f32_16x16x32_bf16 v[62:65], v[184:187], v[212:215], v[30:33]
	v_mfma_f32_16x16x32_bf16 v[30:33], v[164:167], v[216:219], v[152:155]
	v_mfma_f32_16x16x32_bf16 v[22:25], v[188:191], v[140:143], v[22:25]
	v_mfma_f32_16x16x32_bf16 v[14:17], v[208:211], v[140:143], v[14:17]
	v_mfma_f32_16x16x32_bf16 v[54:57], v[184:187], v[144:147], v[30:33]
	v_mfma_f32_16x16x32_bf16 v[46:49], v[192:195], v[212:215], v[22:25]
	v_mfma_f32_16x16x32_bf16 v[22:25], v[188:191], v[216:219], v[156:159]
	v_mfma_f32_16x16x32_bf16 v[30:33], v[220:223], v[212:215], v[14:17]
	v_mfma_f32_16x16x32_bf16 v[14:17], v[208:211], v[216:219], v[160:163]
	v_mfma_f32_16x16x32_bf16 v[6:9], v[236:239], v[140:143], v[6:9]
	v_mfma_f32_16x16x32_bf16 v[38:41], v[192:195], v[144:147], v[22:25]
	v_mfma_f32_16x16x32_bf16 v[22:25], v[220:223], v[144:147], v[14:17]
	v_mfma_f32_16x16x32_bf16 v[14:17], v[240:243], v[212:215], v[6:9]
	v_mfma_f32_16x16x32_bf16 v[6:9], v[236:239], v[216:219], v[196:199]
	v_mfma_f32_16x16x32_bf16 v[6:9], v[240:243], v[144:147], v[6:9]
	s_setprio 0
	v_readlane_b32 s4, v245, 33
	v_readlane_b32 s5, v245, 34
	s_and_b64 vcc, exec, s[4:5]
	s_barrier
	s_cbranch_vccz .LBB0_158
	s_barrier

; #define LDA(dst, b, h) for (int m = 0; m < 4; ++m) for (int k = 0; k < 2; ++k) \
;     dst[m][k] = *reinterpret_cast<const bf16x8*>((char*)SA(b, h) + lds_byte(wr * 64 + m * 16 + fr, k * 32 + fq * 8))
; #define LDB(dst, b, h) for (int n = 0; n < 2; ++n) for (int k = 0; k < 2; ++k) \
;     dst[n][k] = *reinterpret_cast<const bf16x8*>((char*)SB(b, h) + lds_byte(wc * 32 + n * 16 + fr, k * 32 + fq * 8))
; #define MMA(ai, bj, At, Bt_) do { __builtin_amdgcn_s_setprio(1); \
;     for (int m = 0; m < 4; ++m) for (int n = 0; n < 2; ++n) for (int k = 0; k < 2; ++k) \
;       acc[ai][bj][m][n] = __builtin_amdgcn_mfma_f32_16x16x32_bf16(At[m][k], Bt_[n][k], acc[ai][bj][m][n], 0, 0, 0); \
;     __builtin_amdgcn_s_setprio(0); } while (0)
; #define WAIT_V(n) asm volatile("s_waitcnt vmcnt(" #n ")" ::: "memory")
; #define WAIT_L(n) asm volatile("s_waitcnt lgkmcnt(" #n ")" ::: "memory")
; #define BAR __builtin_amdgcn_s_barrier()
; #define SCHED __builtin_amdgcn_sched_barrier(0)
;     ...
;     for (int t = 0; t < nt - 2; t += 2) {
;       LDB(B0, 0, 0); SCHED; LDA(At, 0, 0); STAGE(SA(1, 1), A, brow + HALF, t + 1);
;       WAIT_L(8); BAR; WAIT_L(0); MMA(0, 0, At, B0); BAR; SCHED;
;       LDB(B1, 0, 1); STAGE(SB(0, 0), Bt, bcol, t + 2);
;       BAR; WAIT_L(0); MMA(0, 1, At, B1); BAR;
;       LDA(At, 0, 1); STAGE(SA(0, 0), A, brow, t + 2);
;       BAR; WAIT_L(0); MMA(1, 0, At, B0); BAR; SCHED;
;       STAGE(SB(0, 1), Bt, bcol + HALF, t + 2);
;       WAIT_V(6); BAR; MMA(1, 1, At, B1); BAR;
;       LDB(B0, 1, 0); SCHED; LDA(At, 1, 0); STAGE(SA(0, 1), A, brow + HALF, t + 2);
;       WAIT_L(8); BAR; WAIT_L(0); MMA(0, 0, At, B0); BAR; SCHED;
;       LDB(B1, 1, 1); STAGE(SB(1, 0), Bt, bcol, t + 3);
;       BAR; WAIT_L(0); MMA(0, 1, At, B1); BAR;
;       LDA(At, 1, 1); STAGE(SA(1, 0), A, brow, t + 3);
;       BAR; WAIT_L(0); MMA(1, 0, At, B0); BAR; SCHED;
;       STAGE(SB(1, 1), Bt, bcol + HALF, t + 3);
;       WAIT_V(6); BAR; MMA(1, 1, At, B1); BAR;
;     }
.LBB0_202:
	v_add_u32_e32 v143, s2, v142
	ds_read_b128 v[146:149], v143
	ds_read_b128 v[150:153], v143 offset:1024
	ds_read_b128 v[154:157], v143 offset:2048
	ds_read_b128 v[158:161], v143 offset:3072
	s_add_u32 s66, s50, s16
	s_addc_u32 s67, s51, s17
	s_add_i32 s58, s21, 0xc000
	ds_read_b128 v[162:165], v133
	ds_read_b128 v[184:187], v133 offset:1024
	ds_read_b128 v[188:191], v134
	ds_read_b128 v[192:195], v134 offset:1024
	ds_read_b128 v[196:199], v137
	ds_read_b128 v[200:203], v137 offset:1024
	ds_read_b128 v[204:207], v139
	ds_read_b128 v[208:211], v139 offset:1024
	s_mov_b32 m0, s58
	v_lshl_add_u64 v[144:145], s[66:67], 0, v[0:1]
	s_add_i32 s57, s21, 0xe000
	global_load_lds_dwordx4 v[144:145], off
	v_lshl_add_u64 v[144:145], s[66:67], 0, v[140:141]
	s_mov_b32 m0, s57
	s_nop 0
	global_load_lds_dwordx4 v[144:145], off
	s_waitcnt lgkmcnt(8)
	s_barrier
	s_waitcnt lgkmcnt(0)
	v_mfma_f32_16x16x32_bf16 v[126:129], v[162:165], v[146:149], v[126:129]
	v_mfma_f32_16x16x32_bf16 v[122:125], v[162:165], v[154:157], v[122:125]
	v_mfma_f32_16x16x32_bf16 v[118:121], v[188:191], v[146:149], v[118:121]
	v_mfma_f32_16x16x32_bf16 v[114:117], v[188:191], v[154:157], v[114:117]
	v_mfma_f32_16x16x32_bf16 v[110:113], v[196:199], v[146:149], v[110:113]
	v_mfma_f32_16x16x32_bf16 v[106:109], v[196:199], v[154:157], v[106:109]
	v_mfma_f32_16x16x32_bf16 v[102:105], v[204:207], v[146:149], v[102:105]
	v_mfma_f32_16x16x32_bf16 v[98:101], v[204:207], v[154:157], v[98:101]
	v_mfma_f32_16x16x32_bf16 v[126:129], v[184:187], v[150:153], v[126:129]
	v_mfma_f32_16x16x32_bf16 v[122:125], v[184:187], v[158:161], v[122:125]
	v_mfma_f32_16x16x32_bf16 v[118:121], v[192:195], v[150:153], v[118:121]
	v_mfma_f32_16x16x32_bf16 v[114:117], v[192:195], v[158:161], v[114:117]
	v_mfma_f32_16x16x32_bf16 v[110:113], v[200:203], v[150:153], v[110:113]
	v_mfma_f32_16x16x32_bf16 v[106:109], v[200:203], v[158:161], v[106:109]
	v_mfma_f32_16x16x32_bf16 v[102:105], v[208:211], v[150:153], v[102:105]
	v_mfma_f32_16x16x32_bf16 v[98:101], v[208:211], v[158:161], v[98:101]
	s_barrier
	v_add_u32_e32 v144, s76, v142
	ds_read_b128 v[212:215], v144
	ds_read_b128 v[216:219], v144 offset:1024
	ds_read_b128 v[220:223], v144 offset:2048
	ds_read_b128 v[224:227], v144 offset:3072
	s_add_i32 s55, s55, 2
	s_add_u32 s59, s11, s16
	s_addc_u32 s63, s44, s17
	s_add_u32 s66, s59, 0x100
	s_addc_u32 s67, s63, 0
	s_mov_b32 m0, s29
	s_nop 0
	v_lshl_add_u64 v[166:167], s[66:67], 0, v[0:1]
	global_load_lds_dwordx4 v[166:167], off
	v_lshl_add_u64 v[166:167], s[66:67], 0, v[140:141]
	s_mov_b32 m0, s30
	s_nop 0
	global_load_lds_dwordx4 v[166:167], off
	s_barrier
	s_waitcnt lgkmcnt(0)
	v_mfma_f32_16x16x32_bf16 v[94:97], v[162:165], v[212:215], v[94:97]
	v_mfma_f32_16x16x32_bf16 v[90:93], v[162:165], v[220:223], v[90:93]
	v_mfma_f32_16x16x32_bf16 v[86:89], v[188:191], v[212:215], v[86:89]
	v_mfma_f32_16x16x32_bf16 v[82:85], v[188:191], v[220:223], v[82:85]
	v_mfma_f32_16x16x32_bf16 v[78:81], v[196:199], v[212:215], v[78:81]
	v_mfma_f32_16x16x32_bf16 v[74:77], v[196:199], v[220:223], v[74:77]
	v_mfma_f32_16x16x32_bf16 v[70:73], v[204:207], v[212:215], v[70:73]
	v_mfma_f32_16x16x32_bf16 v[66:69], v[204:207], v[220:223], v[66:69]
	v_mfma_f32_16x16x32_bf16 v[94:97], v[184:187], v[216:219], v[94:97]
	v_mfma_f32_16x16x32_bf16 v[90:93], v[184:187], v[224:227], v[90:93]
	v_mfma_f32_16x16x32_bf16 v[86:89], v[192:195], v[216:219], v[86:89]
	v_mfma_f32_16x16x32_bf16 v[82:85], v[192:195], v[224:227], v[82:85]
	v_mfma_f32_16x16x32_bf16 v[78:81], v[200:203], v[216:219], v[78:81]
	v_mfma_f32_16x16x32_bf16 v[74:77], v[200:203], v[224:227], v[74:77]
	v_mfma_f32_16x16x32_bf16 v[70:73], v[208:211], v[216:219], v[70:73]
	v_mfma_f32_16x16x32_bf16 v[66:69], v[208:211], v[224:227], v[66:69]
	s_barrier
	ds_read_b128 v[162:165], v133 offset:16384
	ds_read_b128 v[184:187], v133 offset:17408
	ds_read_b128 v[188:191], v134 offset:16384
	ds_read_b128 v[192:195], v134 offset:17408
	ds_read_b128 v[196:199], v137 offset:16384
	ds_read_b128 v[200:203], v137 offset:17408
	ds_read_b128 v[204:207], v139 offset:16384
	ds_read_b128 v[208:211], v139 offset:17408
	s_add_u32 s65, s13, s16
	s_addc_u32 s70, s45, s17
	s_add_u32 s66, s65, 0x100
	s_addc_u32 s67, s70, 0
	s_mov_b32 m0, s21
	s_nop 0
	v_lshl_add_u64 v[166:167], s[66:67], 0, v[0:1]
	global_load_lds_dwordx4 v[166:167], off
	v_lshl_add_u64 v[166:167], s[66:67], 0, v[140:141]
	s_mov_b32 m0, s31
	s_nop 0
	global_load_lds_dwordx4 v[166:167], off
	s_barrier
	s_waitcnt lgkmcnt(0)
	v_mfma_f32_16x16x32_bf16 v[62:65], v[162:165], v[146:149], v[62:65]
	v_mfma_f32_16x16x32_bf16 v[58:61], v[162:165], v[154:157], v[58:61]
	v_mfma_f32_16x16x32_bf16 v[54:57], v[188:191], v[146:149], v[54:57]
	v_mfma_f32_16x16x32_bf16 v[50:53], v[188:191], v[154:157], v[50:53]
	v_mfma_f32_16x16x32_bf16 v[46:49], v[196:199], v[146:149], v[46:49]
	v_mfma_f32_16x16x32_bf16 v[42:45], v[196:199], v[154:157], v[42:45]
	v_mfma_f32_16x16x32_bf16 v[38:41], v[204:207], v[146:149], v[38:41]
	v_mfma_f32_16x16x32_bf16 v[34:37], v[204:207], v[154:157], v[34:37]
	v_mfma_f32_16x16x32_bf16 v[62:65], v[184:187], v[150:153], v[62:65]
	v_mfma_f32_16x16x32_bf16 v[58:61], v[184:187], v[158:161], v[58:61]
	v_mfma_f32_16x16x32_bf16 v[54:57], v[192:195], v[150:153], v[54:57]
	v_mfma_f32_16x16x32_bf16 v[50:53], v[192:195], v[158:161], v[50:53]
	v_mfma_f32_16x16x32_bf16 v[46:49], v[200:203], v[150:153], v[46:49]
	v_mfma_f32_16x16x32_bf16 v[42:45], v[200:203], v[158:161], v[42:45]
	v_mfma_f32_16x16x32_bf16 v[38:41], v[208:211], v[150:153], v[38:41]
	v_mfma_f32_16x16x32_bf16 v[34:37], v[208:211], v[158:161], v[34:37]
	s_barrier
; #define LDA(dst, b, h) for (int m = 0; m < 4; ++m) for (int k = 0; k < 2; ++k) \
;     dst[m][k] = *reinterpret_cast<const bf16x8*>((char*)SA(b, h) + lds_byte(wr * 64 + m * 16 + fr, k * 32 + fq * 8))
; #define LDB(dst, b, h) for (int n = 0; n < 2; ++n) for (int k = 0; k < 2; ++k) \
;     dst[n][k] = *reinterpret_cast<const bf16x8*>((char*)SB(b, h) + lds_byte(wc * 32 + n * 16 + fr, k * 32 + fq * 8))
; #define MMA(ai, bj, At, Bt_) do { __builtin_amdgcn_s_setprio(1); \
;     for (int m = 0; m < 4; ++m) for (int n = 0; n < 2; ++n) for (int k = 0; k < 2; ++k) \
;       acc[ai][bj][m][n] = __builtin_amdgcn_mfma_f32_16x16x32_bf16(At[m][k], Bt_[n][k], acc[ai][bj][m][n], 0, 0, 0); \
;     __builtin_amdgcn_s_setprio(0); } while (0)
; #define WAIT_V(n) asm volatile("s_waitcnt vmcnt(" #n ")" ::: "memory")
; #define WAIT_L(n) asm volatile("s_waitcnt lgkmcnt(" #n ")" ::: "memory")
; #define BAR __builtin_amdgcn_s_barrier()
; #define SCHED __builtin_amdgcn_sched_barrier(0)
;     ...
;     for (int t = 0; t < nt - 2; t += 2) {
;       LDB(B0, 0, 0); SCHED; LDA(At, 0, 0); STAGE(SA(1, 1), A, brow + HALF, t + 1);
;       WAIT_L(8); BAR; WAIT_L(0); MMA(0, 0, At, B0); BAR; SCHED;
;       LDB(B1, 0, 1); STAGE(SB(0, 0), Bt, bcol, t + 2);
;       BAR; WAIT_L(0); MMA(0, 1, At, B1); BAR;
;       LDA(At, 0, 1); STAGE(SA(0, 0), A, brow, t + 2);
;       BAR; WAIT_L(0); MMA(1, 0, At, B0); BAR; SCHED;
;       STAGE(SB(0, 1), Bt, bcol + HALF, t + 2);
;       WAIT_V(6); BAR; MMA(1, 1, At, B1); BAR;
;       LDB(B0, 1, 0); SCHED; LDA(At, 1, 0); STAGE(SA(0, 1), A, brow + HALF, t + 2);
;       WAIT_L(8); BAR; WAIT_L(0); MMA(0, 0, At, B0); BAR; SCHED;
;       LDB(B1, 1, 1); STAGE(SB(1, 0), Bt, bcol, t + 3);
;       BAR; WAIT_L(0); MMA(0, 1, At, B1); BAR;
;       LDA(At, 1, 1); STAGE(SA(1, 0), A, brow, t + 3);
;       BAR; WAIT_L(0); MMA(1, 0, At, B0); BAR; SCHED;
;       STAGE(SB(1, 1), Bt, bcol + HALF, t + 3);
;       WAIT_V(6); BAR; MMA(1, 1, At, B1); BAR;
;     }
	s_add_u32 s66, s59, 0x80100
	s_addc_u32 s67, s63, 0
	s_mov_b32 m0, s34
	s_nop 0
	v_lshl_add_u64 v[146:147], s[66:67], 0, v[0:1]
	global_load_lds_dwordx4 v[146:147], off
	v_lshl_add_u64 v[146:147], s[66:67], 0, v[140:141]
	s_mov_b32 m0, s35
	s_nop 0
	global_load_lds_dwordx4 v[146:147], off
	s_waitcnt vmcnt(6)
	s_barrier
	v_mfma_f32_16x16x32_bf16 v[30:33], v[162:165], v[212:215], v[30:33]
	v_mfma_f32_16x16x32_bf16 v[26:29], v[162:165], v[220:223], v[26:29]
	v_mfma_f32_16x16x32_bf16 v[22:25], v[188:191], v[212:215], v[22:25]
	v_mfma_f32_16x16x32_bf16 v[18:21], v[188:191], v[220:223], v[18:21]
	v_mfma_f32_16x16x32_bf16 v[14:17], v[196:199], v[212:215], v[14:17]
	v_mfma_f32_16x16x32_bf16 v[10:13], v[196:199], v[220:223], v[10:13]
	v_mfma_f32_16x16x32_bf16 v[6:9], v[204:207], v[212:215], v[6:9]
	v_mfma_f32_16x16x32_bf16 v[2:5], v[204:207], v[220:223], v[2:5]
	v_mfma_f32_16x16x32_bf16 v[30:33], v[184:187], v[216:219], v[30:33]
	v_mfma_f32_16x16x32_bf16 v[26:29], v[184:187], v[224:227], v[26:29]
	v_mfma_f32_16x16x32_bf16 v[22:25], v[192:195], v[216:219], v[22:25]
	v_mfma_f32_16x16x32_bf16 v[18:21], v[192:195], v[224:227], v[18:21]
	v_mfma_f32_16x16x32_bf16 v[14:17], v[200:203], v[216:219], v[14:17]
	v_mfma_f32_16x16x32_bf16 v[10:13], v[200:203], v[224:227], v[10:13]
	v_mfma_f32_16x16x32_bf16 v[6:9], v[208:211], v[216:219], v[6:9]
	v_mfma_f32_16x16x32_bf16 v[2:5], v[208:211], v[224:227], v[2:5]
	s_barrier
	v_add_u32_e32 v145, s77, v142
	ds_read_b128 v[148:151], v145
	ds_read_b128 v[152:155], v145 offset:1024
	ds_read_b128 v[156:159], v145 offset:2048
	ds_read_b128 v[160:163], v145 offset:3072
	s_add_u32 s66, s65, 0x80100
	s_addc_u32 s67, s70, 0
	s_mov_b32 m0, s37
	ds_read_b128 v[164:167], v133 offset:32768
	ds_read_b128 v[184:187], v133 offset:33792
	ds_read_b128 v[188:191], v134 offset:32768
	ds_read_b128 v[192:195], v134 offset:33792
	ds_read_b128 v[196:199], v137 offset:32768
	ds_read_b128 v[200:203], v137 offset:33792
	ds_read_b128 v[204:207], v139 offset:32768
	ds_read_b128 v[208:211], v139 offset:33792
	s_nop 0
	v_lshl_add_u64 v[146:147], s[66:67], 0, v[0:1]
	global_load_lds_dwordx4 v[146:147], off
	v_lshl_add_u64 v[146:147], s[66:67], 0, v[140:141]
	s_mov_b32 m0, s38
	s_nop 0
	global_load_lds_dwordx4 v[146:147], off
	s_waitcnt lgkmcnt(8)
	s_barrier
	s_waitcnt lgkmcnt(0)
	v_mfma_f32_16x16x32_bf16 v[126:129], v[164:167], v[148:151], v[126:129]
	v_mfma_f32_16x16x32_bf16 v[122:125], v[164:167], v[156:159], v[122:125]
	v_mfma_f32_16x16x32_bf16 v[118:121], v[188:191], v[148:151], v[118:121]
	v_mfma_f32_16x16x32_bf16 v[114:117], v[188:191], v[156:159], v[114:117]
	v_mfma_f32_16x16x32_bf16 v[110:113], v[196:199], v[148:151], v[110:113]
	v_mfma_f32_16x16x32_bf16 v[106:109], v[196:199], v[156:159], v[106:109]
	v_mfma_f32_16x16x32_bf16 v[102:105], v[204:207], v[148:151], v[102:105]
	v_mfma_f32_16x16x32_bf16 v[98:101], v[204:207], v[156:159], v[98:101]
	v_mfma_f32_16x16x32_bf16 v[126:129], v[184:187], v[152:155], v[126:129]
	v_mfma_f32_16x16x32_bf16 v[122:125], v[184:187], v[160:163], v[122:125]
	v_mfma_f32_16x16x32_bf16 v[118:121], v[192:195], v[152:155], v[118:121]
	v_mfma_f32_16x16x32_bf16 v[114:117], v[192:195], v[160:163], v[114:117]
	v_mfma_f32_16x16x32_bf16 v[110:113], v[200:203], v[152:155], v[110:113]
	v_mfma_f32_16x16x32_bf16 v[106:109], v[200:203], v[160:163], v[106:109]
	v_mfma_f32_16x16x32_bf16 v[102:105], v[208:211], v[152:155], v[102:105]
	v_mfma_f32_16x16x32_bf16 v[98:101], v[208:211], v[160:163], v[98:101]
	s_barrier
	v_add_u32_e32 v146, s78, v142
	ds_read_b128 v[212:215], v146
	ds_read_b128 v[216:219], v146 offset:1024
	ds_read_b128 v[220:223], v146 offset:2048
	ds_read_b128 v[224:227], v146 offset:3072
	s_add_u32 s66, s59, 0x180
	s_addc_u32 s67, s63, 0
	s_mov_b32 m0, s39
	s_nop 0
	v_lshl_add_u64 v[228:229], s[66:67], 0, v[0:1]
	global_load_lds_dwordx4 v[228:229], off
	v_lshl_add_u64 v[228:229], s[66:67], 0, v[140:141]
	s_mov_b32 m0, s40
	s_nop 0
	global_load_lds_dwordx4 v[228:229], off
	s_barrier
	s_waitcnt lgkmcnt(0)
	v_mfma_f32_16x16x32_bf16 v[94:97], v[164:167], v[212:215], v[94:97]
	v_mfma_f32_16x16x32_bf16 v[90:93], v[164:167], v[220:223], v[90:93]
	v_mfma_f32_16x16x32_bf16 v[86:89], v[188:191], v[212:215], v[86:89]
	v_mfma_f32_16x16x32_bf16 v[82:85], v[188:191], v[220:223], v[82:85]
	v_mfma_f32_16x16x32_bf16 v[78:81], v[196:199], v[212:215], v[78:81]
	v_mfma_f32_16x16x32_bf16 v[74:77], v[196:199], v[220:223], v[74:77]
	v_mfma_f32_16x16x32_bf16 v[70:73], v[204:207], v[212:215], v[70:73]
	v_mfma_f32_16x16x32_bf16 v[66:69], v[204:207], v[220:223], v[66:69]
	v_mfma_f32_16x16x32_bf16 v[94:97], v[184:187], v[216:219], v[94:97]
	v_mfma_f32_16x16x32_bf16 v[90:93], v[184:187], v[224:227], v[90:93]
	v_mfma_f32_16x16x32_bf16 v[86:89], v[192:195], v[216:219], v[86:89]
	v_mfma_f32_16x16x32_bf16 v[82:85], v[192:195], v[224:227], v[82:85]
	v_mfma_f32_16x16x32_bf16 v[78:81], v[200:203], v[216:219], v[78:81]
	v_mfma_f32_16x16x32_bf16 v[74:77], v[200:203], v[224:227], v[74:77]
	v_mfma_f32_16x16x32_bf16 v[70:73], v[208:211], v[216:219], v[70:73]
	v_mfma_f32_16x16x32_bf16 v[66:69], v[208:211], v[224:227], v[66:69]
	s_barrier
	ds_read_b128 v[164:167], v133 offset:49152
	ds_read_b128 v[184:187], v133 offset:50176
	ds_read_b128 v[188:191], v134 offset:49152
	ds_read_b128 v[192:195], v134 offset:50176
	ds_read_b128 v[196:199], v137 offset:49152
	ds_read_b128 v[200:203], v137 offset:50176
	ds_read_b128 v[204:207], v139 offset:49152
	ds_read_b128 v[208:211], v139 offset:50176
	s_add_u32 s66, s65, 0x180
	s_addc_u32 s67, s70, 0
	s_mov_b32 m0, s41
	s_nop 0
	v_lshl_add_u64 v[228:229], s[66:67], 0, v[0:1]
	global_load_lds_dwordx4 v[228:229], off
	v_lshl_add_u64 v[228:229], s[66:67], 0, v[140:141]
	s_mov_b32 m0, s42
	s_nop 0
	global_load_lds_dwordx4 v[228:229], off
	s_barrier
; #define LDA(dst, b, h) for (int m = 0; m < 4; ++m) for (int k = 0; k < 2; ++k) \
;     dst[m][k] = *reinterpret_cast<const bf16x8*>((char*)SA(b, h) + lds_byte(wr * 64 + m * 16 + fr, k * 32 + fq * 8))
; #define LDB(dst, b, h) for (int n = 0; n < 2; ++n) for (int k = 0; k < 2; ++k) \
;     dst[n][k] = *reinterpret_cast<const bf16x8*>((char*)SB(b, h) + lds_byte(wc * 32 + n * 16 + fr, k * 32 + fq * 8))
; #define MMA(ai, bj, At, Bt_) do { __builtin_amdgcn_s_setprio(1); \
;     for (int m = 0; m < 4; ++m) for (int n = 0; n < 2; ++n) for (int k = 0; k < 2; ++k) \
;       acc[ai][bj][m][n] = __builtin_amdgcn_mfma_f32_16x16x32_bf16(At[m][k], Bt_[n][k], acc[ai][bj][m][n], 0, 0, 0); \
;     __builtin_amdgcn_s_setprio(0); } while (0)
; #define WAIT_V(n) asm volatile("s_waitcnt vmcnt(" #n ")" ::: "memory")
; #define WAIT_L(n) asm volatile("s_waitcnt lgkmcnt(" #n ")" ::: "memory")
; #define BAR __builtin_amdgcn_s_barrier()
; #define SCHED __builtin_amdgcn_sched_barrier(0)
;     ...
;       WAIT_V(6); BAR; MMA(1, 1, At, B1); BAR;
;       LDB(B0, 1, 0); SCHED; LDA(At, 1, 0); STAGE(SA(0, 1), A, brow + HALF, t + 2);
;       WAIT_L(8); BAR; WAIT_L(0); MMA(0, 0, At, B0); BAR; SCHED;
;       LDB(B1, 1, 1); STAGE(SB(1, 0), Bt, bcol, t + 3);
;       BAR; WAIT_L(0); MMA(0, 1, At, B1); BAR;
;       LDA(At, 1, 1); STAGE(SA(1, 0), A, brow, t + 3);
;       BAR; WAIT_L(0); MMA(1, 0, At, B0); BAR; SCHED;
;       STAGE(SB(1, 1), Bt, bcol + HALF, t + 3);
;       WAIT_V(6); BAR; MMA(1, 1, At, B1); BAR;
;     }
;     { LDB(B0, 0, 0); LDA(At, 0, 0); STAGE(SA(1, 1), A, brow + HALF, nt - 1);
;       BAR; WAIT_L(0); MMA(0, 0, At, B0); BAR;
;       LDB(B1, 0, 1); BAR; WAIT_L(0); MMA(0, 1, At, B1); BAR;
;       LDA(At, 0, 1); WAIT_V(4); BAR; WAIT_L(0); MMA(1, 0, At, B0); MMA(1, 1, At, B1); BAR; }
;     { LDB(B0, 1, 0); LDA(At, 1, 0); WAIT_V(2); BAR; WAIT_L(0); MMA(0, 0, At, B0); BAR;
;       LDB(B1, 1, 1); WAIT_V(0); BAR; WAIT_L(0); MMA(0, 1, At, B1); BAR;
;       LDA(At, 1, 1); BAR; WAIT_L(0); MMA(1, 0, At, B0); MMA(1, 1, At, B1); BAR; }
	s_waitcnt lgkmcnt(0)
	v_mfma_f32_16x16x32_bf16 v[62:65], v[164:167], v[148:151], v[62:65]
	v_mfma_f32_16x16x32_bf16 v[58:61], v[164:167], v[156:159], v[58:61]
	v_mfma_f32_16x16x32_bf16 v[54:57], v[188:191], v[148:151], v[54:57]
	v_mfma_f32_16x16x32_bf16 v[50:53], v[188:191], v[156:159], v[50:53]
	v_mfma_f32_16x16x32_bf16 v[46:49], v[196:199], v[148:151], v[46:49]
	v_mfma_f32_16x16x32_bf16 v[42:45], v[196:199], v[156:159], v[42:45]
	v_mfma_f32_16x16x32_bf16 v[38:41], v[204:207], v[148:151], v[38:41]
	v_mfma_f32_16x16x32_bf16 v[34:37], v[204:207], v[156:159], v[34:37]
	v_mfma_f32_16x16x32_bf16 v[62:65], v[184:187], v[152:155], v[62:65]
	v_mfma_f32_16x16x32_bf16 v[58:61], v[184:187], v[160:163], v[58:61]
	v_mfma_f32_16x16x32_bf16 v[54:57], v[192:195], v[152:155], v[54:57]
	v_mfma_f32_16x16x32_bf16 v[50:53], v[192:195], v[160:163], v[50:53]
	v_mfma_f32_16x16x32_bf16 v[46:49], v[200:203], v[152:155], v[46:49]
	v_mfma_f32_16x16x32_bf16 v[42:45], v[200:203], v[160:163], v[42:45]
	v_mfma_f32_16x16x32_bf16 v[38:41], v[208:211], v[152:155], v[38:41]
	v_mfma_f32_16x16x32_bf16 v[34:37], v[208:211], v[160:163], v[34:37]
	s_barrier
	s_add_u32 s66, s59, 0x80180
	s_addc_u32 s67, s63, 0
	s_mov_b32 m0, s18
	s_nop 0
	v_lshl_add_u64 v[148:149], s[66:67], 0, v[0:1]
	global_load_lds_dwordx4 v[148:149], off
	v_lshl_add_u64 v[148:149], s[66:67], 0, v[140:141]
	s_mov_b32 m0, s19
	s_nop 0
	global_load_lds_dwordx4 v[148:149], off
	s_add_u32 s11, s11, 0x100
	s_addc_u32 s44, s44, 0
	s_add_u32 s13, s13, 0x100
	s_addc_u32 s45, s45, 0
	s_add_u32 s50, s50, 0x100
	s_addc_u32 s51, s51, 0
	s_cmp_ge_u32 s55, s43
	s_waitcnt vmcnt(6)
	s_barrier
	v_mfma_f32_16x16x32_bf16 v[30:33], v[164:167], v[212:215], v[30:33]
	v_mfma_f32_16x16x32_bf16 v[26:29], v[164:167], v[220:223], v[26:29]
	v_mfma_f32_16x16x32_bf16 v[22:25], v[188:191], v[212:215], v[22:25]
	v_mfma_f32_16x16x32_bf16 v[18:21], v[188:191], v[220:223], v[18:21]
	v_mfma_f32_16x16x32_bf16 v[14:17], v[196:199], v[212:215], v[14:17]
	v_mfma_f32_16x16x32_bf16 v[10:13], v[196:199], v[220:223], v[10:13]
	v_mfma_f32_16x16x32_bf16 v[6:9], v[204:207], v[212:215], v[6:9]
	v_mfma_f32_16x16x32_bf16 v[2:5], v[204:207], v[220:223], v[2:5]
	v_mfma_f32_16x16x32_bf16 v[30:33], v[184:187], v[216:219], v[30:33]
	v_mfma_f32_16x16x32_bf16 v[26:29], v[184:187], v[224:227], v[26:29]
	v_mfma_f32_16x16x32_bf16 v[22:25], v[192:195], v[216:219], v[22:25]
	v_mfma_f32_16x16x32_bf16 v[18:21], v[192:195], v[224:227], v[18:21]
	v_mfma_f32_16x16x32_bf16 v[14:17], v[200:203], v[216:219], v[14:17]
	v_mfma_f32_16x16x32_bf16 v[10:13], v[200:203], v[224:227], v[10:13]
	v_mfma_f32_16x16x32_bf16 v[6:9], v[208:211], v[216:219], v[6:9]
	v_mfma_f32_16x16x32_bf16 v[2:5], v[208:211], v[224:227], v[2:5]
	s_barrier
	s_cbranch_scc0 .LBB0_202
	s_add_i32 s11, s48, s20
	s_add_i32 s48, s11, -1
	s_lshl_b64 s[16:17], s[48:49], 7
	s_add_u32 s11, s74, s16
	s_addc_u32 s13, s75, s17
	s_add_u32 s4, s11, s4
	s_addc_u32 s5, s13, s5
	s_mov_b32 m0, s58
	ds_read_b128 v[148:151], v143
	ds_read_b128 v[152:155], v143 offset:1024
	ds_read_b128 v[156:159], v143 offset:2048
	ds_read_b128 v[160:163], v143 offset:3072
	ds_read_b128 v[164:167], v133
	ds_read_b128 v[184:187], v133 offset:1024
	ds_read_b128 v[188:191], v134
	ds_read_b128 v[192:195], v134 offset:1024
	ds_read_b128 v[196:199], v137
	ds_read_b128 v[200:203], v137 offset:1024
	ds_read_b128 v[204:207], v139
	ds_read_b128 v[208:211], v139 offset:1024
	s_nop 0
	v_lshl_add_u64 v[142:143], s[4:5], 0, v[0:1]
	global_load_lds_dwordx4 v[142:143], off
	v_lshl_add_u64 v[140:141], s[4:5], 0, v[140:141]
	s_mov_b32 m0, s57
	s_nop 0
	global_load_lds_dwordx4 v[140:141], off
	s_barrier
	s_waitcnt lgkmcnt(0)
	s_setprio 1
	s_waitcnt lgkmcnt(0)
	v_mfma_f32_16x16x32_bf16 v[126:129], v[164:167], v[148:151], v[126:129]
	v_mfma_f32_16x16x32_bf16 v[122:125], v[164:167], v[156:159], v[122:125]
	v_mfma_f32_16x16x32_bf16 v[118:121], v[188:191], v[148:151], v[118:121]
	v_mfma_f32_16x16x32_bf16 v[110:113], v[196:199], v[148:151], v[110:113]
	v_mfma_f32_16x16x32_bf16 v[106:109], v[196:199], v[156:159], v[106:109]
	v_mfma_f32_16x16x32_bf16 v[102:105], v[204:207], v[148:151], v[102:105]
	v_mfma_f32_16x16x32_bf16 v[98:101], v[204:207], v[156:159], v[98:101]
	v_mfma_f32_16x16x32_bf16 v[126:129], v[184:187], v[152:155], v[126:129]
	v_mfma_f32_16x16x32_bf16 v[122:125], v[184:187], v[160:163], v[122:125]
	v_mfma_f32_16x16x32_bf16 v[118:121], v[192:195], v[152:155], v[118:121]
	v_mfma_f32_16x16x32_bf16 v[114:117], v[188:191], v[156:159], v[114:117]
	v_mfma_f32_16x16x32_bf16 v[110:113], v[200:203], v[152:155], v[110:113]
	v_mfma_f32_16x16x32_bf16 v[106:109], v[200:203], v[160:163], v[106:109]
	v_mfma_f32_16x16x32_bf16 v[102:105], v[208:211], v[152:155], v[102:105]
	v_mfma_f32_16x16x32_bf16 v[98:101], v[208:211], v[160:163], v[98:101]
	v_mfma_f32_16x16x32_bf16 v[140:143], v[192:195], v[160:163], v[114:117]
	s_setprio 0
	s_barrier
	s_nop 0
	ds_read_b128 v[114:117], v144
	ds_read_b128 v[212:215], v144 offset:1024
	ds_read_b128 v[216:219], v144 offset:2048
	ds_read_b128 v[220:223], v144 offset:3072
	s_barrier
; #define LDA(dst, b, h) for (int m = 0; m < 4; ++m) for (int k = 0; k < 2; ++k) \
;     dst[m][k] = *reinterpret_cast<const bf16x8*>((char*)SA(b, h) + lds_byte(wr * 64 + m * 16 + fr, k * 32 + fq * 8))
; #define LDB(dst, b, h) for (int n = 0; n < 2; ++n) for (int k = 0; k < 2; ++k) \
;     dst[n][k] = *reinterpret_cast<const bf16x8*>((char*)SB(b, h) + lds_byte(wc * 32 + n * 16 + fr, k * 32 + fq * 8))
; #define MMA(ai, bj, At, Bt_) do { __builtin_amdgcn_s_setprio(1); \
;     for (int m = 0; m < 4; ++m) for (int n = 0; n < 2; ++n) for (int k = 0; k < 2; ++k) \
;       acc[ai][bj][m][n] = __builtin_amdgcn_mfma_f32_16x16x32_bf16(At[m][k], Bt_[n][k], acc[ai][bj][m][n], 0, 0, 0); \
;     __builtin_amdgcn_s_setprio(0); } while (0)
; #define WAIT_V(n) asm volatile("s_waitcnt vmcnt(" #n ")" ::: "memory")
; #define WAIT_L(n) asm volatile("s_waitcnt lgkmcnt(" #n ")" ::: "memory")
; #define BAR __builtin_amdgcn_s_barrier()
;     ...
;       LDB(B1, 0, 1); BAR; WAIT_L(0); MMA(0, 1, At, B1); BAR;
;       LDA(At, 0, 1); WAIT_V(4); BAR; WAIT_L(0); MMA(1, 0, At, B0); MMA(1, 1, At, B1); BAR; }
;     { LDB(B0, 1, 0); LDA(At, 1, 0); WAIT_V(2); BAR; WAIT_L(0); MMA(0, 0, At, B0); BAR;
;       LDB(B1, 1, 1); WAIT_V(0); BAR; WAIT_L(0); MMA(0, 1, At, B1); BAR;
;       LDA(At, 1, 1); BAR; WAIT_L(0); MMA(1, 0, At, B0); MMA(1, 1, At, B1); BAR; }
	s_waitcnt lgkmcnt(0)
	s_setprio 1
	s_waitcnt lgkmcnt(0)
	v_mfma_f32_16x16x32_bf16 v[90:93], v[164:167], v[216:219], v[90:93]
	v_mfma_f32_16x16x32_bf16 v[86:89], v[188:191], v[114:117], v[86:89]
	v_mfma_f32_16x16x32_bf16 v[94:97], v[164:167], v[114:117], v[94:97]
	v_mfma_f32_16x16x32_bf16 v[90:93], v[184:187], v[220:223], v[90:93]
	v_mfma_f32_16x16x32_bf16 v[86:89], v[192:195], v[212:215], v[86:89]
	v_mfma_f32_16x16x32_bf16 v[82:85], v[188:191], v[216:219], v[82:85]
	v_mfma_f32_16x16x32_bf16 v[78:81], v[196:199], v[114:117], v[78:81]
	v_mfma_f32_16x16x32_bf16 v[74:77], v[196:199], v[216:219], v[74:77]
	v_mfma_f32_16x16x32_bf16 v[70:73], v[204:207], v[114:117], v[70:73]
	v_mfma_f32_16x16x32_bf16 v[66:69], v[204:207], v[216:219], v[66:69]
	v_mfma_f32_16x16x32_bf16 v[224:227], v[184:187], v[212:215], v[94:97]
	v_mfma_f32_16x16x32_bf16 v[164:167], v[192:195], v[220:223], v[82:85]
	v_mfma_f32_16x16x32_bf16 v[184:187], v[200:203], v[212:215], v[78:81]
	v_mfma_f32_16x16x32_bf16 v[188:191], v[200:203], v[220:223], v[74:77]
	v_mfma_f32_16x16x32_bf16 v[192:195], v[208:211], v[212:215], v[70:73]
	v_mfma_f32_16x16x32_bf16 v[196:199], v[208:211], v[220:223], v[66:69]
	s_setprio 0
	s_barrier
	s_nop 0
	ds_read_b128 v[66:69], v133 offset:16384
	ds_read_b128 v[70:73], v133 offset:17408
	ds_read_b128 v[74:77], v134 offset:16384
	ds_read_b128 v[78:81], v134 offset:17408
	ds_read_b128 v[82:85], v137 offset:16384
	ds_read_b128 v[94:97], v137 offset:17408
	ds_read_b128 v[200:203], v139 offset:16384
	ds_read_b128 v[204:207], v139 offset:17408
	s_waitcnt vmcnt(4)
	s_barrier
	s_waitcnt lgkmcnt(0)
	s_setprio 1
	s_waitcnt lgkmcnt(0)
	v_mfma_f32_16x16x32_bf16 v[62:65], v[66:69], v[148:151], v[62:65]
	v_mfma_f32_16x16x32_bf16 v[58:61], v[66:69], v[156:159], v[58:61]
	v_mfma_f32_16x16x32_bf16 v[54:57], v[74:77], v[148:151], v[54:57]
	v_mfma_f32_16x16x32_bf16 v[50:53], v[74:77], v[156:159], v[50:53]
	v_mfma_f32_16x16x32_bf16 v[46:49], v[82:85], v[148:151], v[46:49]
	v_mfma_f32_16x16x32_bf16 v[42:45], v[82:85], v[156:159], v[42:45]
	v_mfma_f32_16x16x32_bf16 v[38:41], v[200:203], v[148:151], v[38:41]
	v_mfma_f32_16x16x32_bf16 v[34:37], v[200:203], v[156:159], v[34:37]
	v_mfma_f32_16x16x32_bf16 v[62:65], v[70:73], v[152:155], v[62:65]
	v_mfma_f32_16x16x32_bf16 v[58:61], v[70:73], v[160:163], v[58:61]
	v_mfma_f32_16x16x32_bf16 v[54:57], v[78:81], v[152:155], v[54:57]
	v_mfma_f32_16x16x32_bf16 v[50:53], v[78:81], v[160:163], v[50:53]
	v_mfma_f32_16x16x32_bf16 v[46:49], v[94:97], v[152:155], v[46:49]
	v_mfma_f32_16x16x32_bf16 v[42:45], v[94:97], v[160:163], v[42:45]
	v_mfma_f32_16x16x32_bf16 v[38:41], v[204:207], v[152:155], v[38:41]
	v_mfma_f32_16x16x32_bf16 v[34:37], v[204:207], v[160:163], v[34:37]
	s_setprio 0
	s_setprio 1
	v_mfma_f32_16x16x32_bf16 v[30:33], v[66:69], v[114:117], v[30:33]
	v_mfma_f32_16x16x32_bf16 v[26:29], v[66:69], v[216:219], v[26:29]
	v_mfma_f32_16x16x32_bf16 v[22:25], v[74:77], v[114:117], v[22:25]
	v_mfma_f32_16x16x32_bf16 v[18:21], v[74:77], v[216:219], v[18:21]
	v_mfma_f32_16x16x32_bf16 v[14:17], v[82:85], v[114:117], v[14:17]
	v_mfma_f32_16x16x32_bf16 v[10:13], v[82:85], v[216:219], v[10:13]
	v_mfma_f32_16x16x32_bf16 v[6:9], v[200:203], v[114:117], v[6:9]
	v_mfma_f32_16x16x32_bf16 v[2:5], v[200:203], v[216:219], v[2:5]
	v_mfma_f32_16x16x32_bf16 v[148:151], v[70:73], v[212:215], v[30:33]
	v_mfma_f32_16x16x32_bf16 v[152:155], v[70:73], v[220:223], v[26:29]
	v_mfma_f32_16x16x32_bf16 v[156:159], v[78:81], v[212:215], v[22:25]
	v_mfma_f32_16x16x32_bf16 v[160:163], v[78:81], v[220:223], v[18:21]
	v_mfma_f32_16x16x32_bf16 v[208:211], v[94:97], v[212:215], v[14:17]
	v_mfma_f32_16x16x32_bf16 v[228:231], v[94:97], v[220:223], v[10:13]
	v_mfma_f32_16x16x32_bf16 v[212:215], v[204:207], v[212:215], v[6:9]
	v_mfma_f32_16x16x32_bf16 v[200:203], v[204:207], v[220:223], v[2:5]
	s_setprio 0
	s_barrier
	ds_read_b128 v[14:17], v145
	ds_read_b128 v[30:33], v145 offset:1024
	ds_read_b128 v[204:207], v145 offset:2048
	ds_read_b128 v[216:219], v145 offset:3072
	ds_read_b128 v[2:5], v133 offset:32768
	ds_read_b128 v[6:9], v133 offset:33792
	ds_read_b128 v[10:13], v134 offset:32768
	ds_read_b128 v[18:21], v134 offset:33792
	ds_read_b128 v[22:25], v137 offset:32768
	ds_read_b128 v[26:29], v137 offset:33792
	ds_read_b128 v[220:223], v139 offset:32768
	ds_read_b128 v[232:235], v139 offset:33792
	s_waitcnt vmcnt(2)
	s_barrier
; #define LDA(dst, b, h) for (int m = 0; m < 4; ++m) for (int k = 0; k < 2; ++k) \
;     dst[m][k] = *reinterpret_cast<const bf16x8*>((char*)SA(b, h) + lds_byte(wr * 64 + m * 16 + fr, k * 32 + fq * 8))
; #define LDB(dst, b, h) for (int n = 0; n < 2; ++n) for (int k = 0; k < 2; ++k) \
;     dst[n][k] = *reinterpret_cast<const bf16x8*>((char*)SB(b, h) + lds_byte(wc * 32 + n * 16 + fr, k * 32 + fq * 8))
; #define MMA(ai, bj, At, Bt_) do { __builtin_amdgcn_s_setprio(1); \
;     for (int m = 0; m < 4; ++m) for (int n = 0; n < 2; ++n) for (int k = 0; k < 2; ++k) \
;       acc[ai][bj][m][n] = __builtin_amdgcn_mfma_f32_16x16x32_bf16(At[m][k], Bt_[n][k], acc[ai][bj][m][n], 0, 0, 0); \
;     __builtin_amdgcn_s_setprio(0); } while (0)
; #define WAIT_V(n) asm volatile("s_waitcnt vmcnt(" #n ")" ::: "memory")
; #define WAIT_L(n) asm volatile("s_waitcnt lgkmcnt(" #n ")" ::: "memory")
; #define BAR __builtin_amdgcn_s_barrier()
;     ...
;     { LDB(B0, 1, 0); LDA(At, 1, 0); WAIT_V(2); BAR; WAIT_L(0); MMA(0, 0, At, B0); BAR;
;       LDB(B1, 1, 1); WAIT_V(0); BAR; WAIT_L(0); MMA(0, 1, At, B1); BAR;
;       LDA(At, 1, 1); BAR; WAIT_L(0); MMA(1, 0, At, B0); MMA(1, 1, At, B1); BAR; }
;     if (wr == 0) BAR;
	s_waitcnt lgkmcnt(0)
	s_setprio 1
	s_waitcnt lgkmcnt(0)
	v_mfma_f32_16x16x32_bf16 v[66:69], v[2:5], v[14:17], v[126:129]
	v_mfma_f32_16x16x32_bf16 v[114:117], v[6:9], v[30:33], v[66:69]
	v_mfma_f32_16x16x32_bf16 v[66:69], v[2:5], v[204:207], v[122:125]
	v_mfma_f32_16x16x32_bf16 v[126:129], v[6:9], v[216:219], v[66:69]
	v_mfma_f32_16x16x32_bf16 v[66:69], v[10:13], v[14:17], v[118:121]
	v_mfma_f32_16x16x32_bf16 v[82:85], v[18:21], v[30:33], v[66:69]
	v_mfma_f32_16x16x32_bf16 v[66:69], v[10:13], v[204:207], v[140:143]
	v_mfma_f32_16x16x32_bf16 v[94:97], v[18:21], v[216:219], v[66:69]
	v_mfma_f32_16x16x32_bf16 v[66:69], v[22:25], v[14:17], v[110:113]
	v_mfma_f32_16x16x32_bf16 v[74:77], v[26:29], v[30:33], v[66:69]
	v_mfma_f32_16x16x32_bf16 v[66:69], v[22:25], v[204:207], v[106:109]
	v_mfma_f32_16x16x32_bf16 v[78:81], v[26:29], v[216:219], v[66:69]
	v_mfma_f32_16x16x32_bf16 v[66:69], v[220:223], v[14:17], v[102:105]
	v_mfma_f32_16x16x32_bf16 v[70:73], v[220:223], v[204:207], v[98:101]
	v_mfma_f32_16x16x32_bf16 v[66:69], v[232:235], v[30:33], v[66:69]
	v_mfma_f32_16x16x32_bf16 v[70:73], v[232:235], v[216:219], v[70:73]
	s_setprio 0
	s_barrier
	ds_read_b128 v[140:143], v146
	ds_read_b128 v[236:239], v146 offset:1024
	ds_read_b128 v[240:243], v146 offset:2048
	ds_read_b128 v[144:147], v146 offset:3072
	s_waitcnt vmcnt(0)
	s_barrier
	s_waitcnt lgkmcnt(0)
	s_setprio 1
	s_waitcnt lgkmcnt(0)
	v_mfma_f32_16x16x32_bf16 v[98:101], v[2:5], v[140:143], v[224:227]
	v_mfma_f32_16x16x32_bf16 v[2:5], v[2:5], v[240:243], v[90:93]
	v_mfma_f32_16x16x32_bf16 v[118:121], v[6:9], v[144:147], v[2:5]
	v_mfma_f32_16x16x32_bf16 v[2:5], v[10:13], v[140:143], v[86:89]
	v_mfma_f32_16x16x32_bf16 v[102:105], v[18:21], v[236:239], v[2:5]
	v_mfma_f32_16x16x32_bf16 v[2:5], v[10:13], v[240:243], v[164:167]
	v_mfma_f32_16x16x32_bf16 v[122:125], v[18:21], v[144:147], v[2:5]
	v_mfma_f32_16x16x32_bf16 v[2:5], v[22:25], v[140:143], v[184:187]
	v_mfma_f32_16x16x32_bf16 v[90:93], v[26:29], v[236:239], v[2:5]
	v_mfma_f32_16x16x32_bf16 v[2:5], v[22:25], v[240:243], v[188:191]
	v_mfma_f32_16x16x32_bf16 v[110:113], v[26:29], v[144:147], v[2:5]
	v_mfma_f32_16x16x32_bf16 v[2:5], v[220:223], v[140:143], v[192:195]
	v_mfma_f32_16x16x32_bf16 v[86:89], v[232:235], v[236:239], v[2:5]
	v_mfma_f32_16x16x32_bf16 v[2:5], v[220:223], v[240:243], v[196:199]
	v_mfma_f32_16x16x32_bf16 v[98:101], v[6:9], v[236:239], v[98:101]
	v_mfma_f32_16x16x32_bf16 v[106:109], v[232:235], v[144:147], v[2:5]
	s_setprio 0
	s_barrier
	ds_read_b128 v[164:167], v133 offset:49152
	ds_read_b128 v[184:187], v133 offset:50176
	ds_read_b128 v[188:191], v134 offset:49152
	ds_read_b128 v[192:195], v134 offset:50176
	ds_read_b128 v[196:199], v137 offset:49152
	ds_read_b128 v[220:223], v137 offset:50176
	ds_read_b128 v[224:227], v139 offset:49152
	ds_read_b128 v[232:235], v139 offset:50176
	s_barrier
	s_waitcnt lgkmcnt(0)
	s_setprio 1
	s_waitcnt lgkmcnt(0)
	v_mfma_f32_16x16x32_bf16 v[6:9], v[164:167], v[204:207], v[58:61]
	v_mfma_f32_16x16x32_bf16 v[10:13], v[188:191], v[204:207], v[50:53]
	v_mfma_f32_16x16x32_bf16 v[2:5], v[164:167], v[14:17], v[62:65]
	v_mfma_f32_16x16x32_bf16 v[18:21], v[184:187], v[216:219], v[6:9]
	v_mfma_f32_16x16x32_bf16 v[6:9], v[188:191], v[14:17], v[54:57]
	v_mfma_f32_16x16x32_bf16 v[22:25], v[192:195], v[216:219], v[10:13]
	v_mfma_f32_16x16x32_bf16 v[10:13], v[196:199], v[14:17], v[46:49]
	v_mfma_f32_16x16x32_bf16 v[14:17], v[224:227], v[14:17], v[38:41]
	v_mfma_f32_16x16x32_bf16 v[2:5], v[184:187], v[30:33], v[2:5]
	v_mfma_f32_16x16x32_bf16 v[6:9], v[192:195], v[30:33], v[6:9]
	v_mfma_f32_16x16x32_bf16 v[10:13], v[220:223], v[30:33], v[10:13]
	v_mfma_f32_16x16x32_bf16 v[26:29], v[196:199], v[204:207], v[42:45]
	v_mfma_f32_16x16x32_bf16 v[14:17], v[232:235], v[30:33], v[14:17]
	v_mfma_f32_16x16x32_bf16 v[30:33], v[224:227], v[204:207], v[34:37]
	v_mfma_f32_16x16x32_bf16 v[26:29], v[220:223], v[216:219], v[26:29]
	v_mfma_f32_16x16x32_bf16 v[30:33], v[232:235], v[216:219], v[30:33]
	s_setprio 0
	s_setprio 1
	v_mfma_f32_16x16x32_bf16 v[38:41], v[164:167], v[240:243], v[152:155]
	v_mfma_f32_16x16x32_bf16 v[42:45], v[188:191], v[240:243], v[160:163]
	v_mfma_f32_16x16x32_bf16 v[46:49], v[196:199], v[240:243], v[228:231]
	v_mfma_f32_16x16x32_bf16 v[34:37], v[164:167], v[140:143], v[148:151]
	v_mfma_f32_16x16x32_bf16 v[50:53], v[184:187], v[144:147], v[38:41]
	v_mfma_f32_16x16x32_bf16 v[38:41], v[188:191], v[140:143], v[156:159]
	v_mfma_f32_16x16x32_bf16 v[54:57], v[192:195], v[144:147], v[42:45]
	v_mfma_f32_16x16x32_bf16 v[42:45], v[196:199], v[140:143], v[208:211]
	v_mfma_f32_16x16x32_bf16 v[58:61], v[220:223], v[144:147], v[46:49]
	v_mfma_f32_16x16x32_bf16 v[46:49], v[224:227], v[140:143], v[212:215]
	v_mfma_f32_16x16x32_bf16 v[62:65], v[224:227], v[240:243], v[200:203]
	v_mfma_f32_16x16x32_bf16 v[34:37], v[184:187], v[236:239], v[34:37]
	v_mfma_f32_16x16x32_bf16 v[38:41], v[192:195], v[236:239], v[38:41]
	v_mfma_f32_16x16x32_bf16 v[42:45], v[220:223], v[236:239], v[42:45]
	v_mfma_f32_16x16x32_bf16 v[46:49], v[232:235], v[236:239], v[46:49]
	v_mfma_f32_16x16x32_bf16 v[62:65], v[232:235], v[144:147], v[62:65]
	s_setprio 0
	v_readlane_b32 s4, v245, 33
	v_readlane_b32 s5, v245, 34
	s_and_b64 vcc, exec, s[4:5]
	s_barrier
	s_cbranch_vccz .LBB0_205
	s_barrier

; #define LDA(dst, b, h) for (int m = 0; m < 4; ++m) for (int k = 0; k < 2; ++k) \
;     dst[m][k] = *reinterpret_cast<const bf16x8*>((char*)SA(b, h) + lds_byte(wr * 64 + m * 16 + fr, k * 32 + fq * 8))
; #define LDB(dst, b, h) for (int n = 0; n < 2; ++n) for (int k = 0; k < 2; ++k) \
;     dst[n][k] = *reinterpret_cast<const bf16x8*>((char*)SB(b, h) + lds_byte(wc * 32 + n * 16 + fr, k * 32 + fq * 8))
; #define MMA(ai, bj, At, Bt_) do { __builtin_amdgcn_s_setprio(1); \
;     for (int m = 0; m < 4; ++m) for (int n = 0; n < 2; ++n) for (int k = 0; k < 2; ++k) \
;       acc[ai][bj][m][n] = __builtin_amdgcn_mfma_f32_16x16x32_bf16(At[m][k], Bt_[n][k], acc[ai][bj][m][n], 0, 0, 0); \
;     __builtin_amdgcn_s_setprio(0); } while (0)
; #define WAIT_V(n) asm volatile("s_waitcnt vmcnt(" #n ")" ::: "memory")
; #define WAIT_L(n) asm volatile("s_waitcnt lgkmcnt(" #n ")" ::: "memory")
; #define BAR __builtin_amdgcn_s_barrier()
; #define SCHED __builtin_amdgcn_sched_barrier(0)
;     ...
;     for (int t = 0; t < nt - 2; t += 2) {
;       LDB(B0, 0, 0); SCHED; LDA(At, 0, 0); STAGE(SA(1, 1), A, brow + HALF, t + 1);
;       WAIT_L(8); BAR; WAIT_L(0); MMA(0, 0, At, B0); BAR; SCHED;
;       LDB(B1, 0, 1); STAGE(SB(0, 0), Bt, bcol, t + 2);
;       BAR; WAIT_L(0); MMA(0, 1, At, B1); BAR;
;       LDA(At, 0, 1); STAGE(SA(0, 0), A, brow, t + 2);
;       BAR; WAIT_L(0); MMA(1, 0, At, B0); BAR; SCHED;
;       STAGE(SB(0, 1), Bt, bcol + HALF, t + 2);
;       WAIT_V(6); BAR; MMA(1, 1, At, B1); BAR;
;       LDB(B0, 1, 0); SCHED; LDA(At, 1, 0); STAGE(SA(0, 1), A, brow + HALF, t + 2);
;       WAIT_L(8); BAR; WAIT_L(0); MMA(0, 0, At, B0); BAR; SCHED;
;       LDB(B1, 1, 1); STAGE(SB(1, 0), Bt, bcol, t + 3);
;       BAR; WAIT_L(0); MMA(0, 1, At, B1); BAR;
;       LDA(At, 1, 1); STAGE(SA(1, 0), A, brow, t + 3);
;       BAR; WAIT_L(0); MMA(1, 0, At, B0); BAR; SCHED;
;       STAGE(SB(1, 1), Bt, bcol + HALF, t + 3);
;       WAIT_V(6); BAR; MMA(1, 1, At, B1); BAR;
;     }
.LBB0_418:
	v_add_u32_e32 v143, s2, v142
	ds_read_b128 v[146:149], v143
	ds_read_b128 v[150:153], v143 offset:1024
	ds_read_b128 v[154:157], v143 offset:2048
	ds_read_b128 v[158:161], v143 offset:3072
	s_add_u32 s42, s30, s6
	s_addc_u32 s43, s31, s7
	s_add_u32 s44, s42, 0x80080
	s_addc_u32 s45, s43, 0
	s_add_i32 s41, s15, 0xc000
	ds_read_b128 v[162:165], v133
	ds_read_b128 v[184:187], v133 offset:1024
	ds_read_b128 v[188:191], v134
	ds_read_b128 v[192:195], v134 offset:1024
	ds_read_b128 v[196:199], v137
	ds_read_b128 v[200:203], v137 offset:1024
	ds_read_b128 v[204:207], v139
	ds_read_b128 v[208:211], v139 offset:1024
	s_mov_b32 m0, s41
	v_lshl_add_u64 v[144:145], s[44:45], 0, v[0:1]
	s_add_i32 s37, s15, 0xe000
	global_load_lds_dwordx4 v[144:145], off
	v_lshl_add_u64 v[144:145], s[44:45], 0, v[140:141]
	s_mov_b32 m0, s37
	s_nop 0
	global_load_lds_dwordx4 v[144:145], off
	s_waitcnt lgkmcnt(8)
	s_barrier
	s_waitcnt lgkmcnt(0)
	v_mfma_f32_16x16x32_bf16 v[126:129], v[162:165], v[146:149], v[126:129]
	v_mfma_f32_16x16x32_bf16 v[122:125], v[162:165], v[154:157], v[122:125]
	v_mfma_f32_16x16x32_bf16 v[118:121], v[188:191], v[146:149], v[118:121]
	v_mfma_f32_16x16x32_bf16 v[114:117], v[188:191], v[154:157], v[114:117]
	v_mfma_f32_16x16x32_bf16 v[110:113], v[196:199], v[146:149], v[110:113]
	v_mfma_f32_16x16x32_bf16 v[106:109], v[196:199], v[154:157], v[106:109]
	v_mfma_f32_16x16x32_bf16 v[102:105], v[204:207], v[146:149], v[102:105]
	v_mfma_f32_16x16x32_bf16 v[98:101], v[204:207], v[154:157], v[98:101]
	v_mfma_f32_16x16x32_bf16 v[126:129], v[184:187], v[150:153], v[126:129]
	v_mfma_f32_16x16x32_bf16 v[122:125], v[184:187], v[158:161], v[122:125]
	v_mfma_f32_16x16x32_bf16 v[118:121], v[192:195], v[150:153], v[118:121]
	v_mfma_f32_16x16x32_bf16 v[114:117], v[192:195], v[158:161], v[114:117]
	v_mfma_f32_16x16x32_bf16 v[110:113], v[200:203], v[150:153], v[110:113]
	v_mfma_f32_16x16x32_bf16 v[106:109], v[200:203], v[158:161], v[106:109]
	v_mfma_f32_16x16x32_bf16 v[102:105], v[208:211], v[150:153], v[102:105]
	v_mfma_f32_16x16x32_bf16 v[98:101], v[208:211], v[158:161], v[98:101]
	s_barrier
	v_add_u32_e32 v144, s76, v142
	ds_read_b128 v[212:215], v144
	ds_read_b128 v[216:219], v144 offset:1024
	ds_read_b128 v[220:223], v144 offset:2048
	ds_read_b128 v[224:227], v144 offset:3072
	s_add_u32 s44, s34, s6
	s_addc_u32 s45, s35, s7
	s_add_u32 s50, s44, 0x100
	s_addc_u32 s51, s45, 0
	s_mov_b32 m0, s23
	s_nop 0
	v_lshl_add_u64 v[166:167], s[50:51], 0, v[0:1]
	global_load_lds_dwordx4 v[166:167], off
	v_lshl_add_u64 v[166:167], s[50:51], 0, v[140:141]
	s_mov_b32 m0, s26
	s_nop 0
	global_load_lds_dwordx4 v[166:167], off
	s_barrier
	s_waitcnt lgkmcnt(0)
	v_mfma_f32_16x16x32_bf16 v[94:97], v[162:165], v[212:215], v[94:97]
	v_mfma_f32_16x16x32_bf16 v[90:93], v[162:165], v[220:223], v[90:93]
	v_mfma_f32_16x16x32_bf16 v[86:89], v[188:191], v[212:215], v[86:89]
	v_mfma_f32_16x16x32_bf16 v[82:85], v[188:191], v[220:223], v[82:85]
	v_mfma_f32_16x16x32_bf16 v[78:81], v[196:199], v[212:215], v[78:81]
	v_mfma_f32_16x16x32_bf16 v[74:77], v[196:199], v[220:223], v[74:77]
	v_mfma_f32_16x16x32_bf16 v[70:73], v[204:207], v[212:215], v[70:73]
	v_mfma_f32_16x16x32_bf16 v[66:69], v[204:207], v[220:223], v[66:69]
	v_mfma_f32_16x16x32_bf16 v[94:97], v[184:187], v[216:219], v[94:97]
	v_mfma_f32_16x16x32_bf16 v[90:93], v[184:187], v[224:227], v[90:93]
	v_mfma_f32_16x16x32_bf16 v[86:89], v[192:195], v[216:219], v[86:89]
	v_mfma_f32_16x16x32_bf16 v[82:85], v[192:195], v[224:227], v[82:85]
	v_mfma_f32_16x16x32_bf16 v[78:81], v[200:203], v[216:219], v[78:81]
	v_mfma_f32_16x16x32_bf16 v[74:77], v[200:203], v[224:227], v[74:77]
	v_mfma_f32_16x16x32_bf16 v[70:73], v[208:211], v[216:219], v[70:73]
	v_mfma_f32_16x16x32_bf16 v[66:69], v[208:211], v[224:227], v[66:69]
	s_barrier
	ds_read_b128 v[162:165], v133 offset:16384
	ds_read_b128 v[184:187], v133 offset:17408
	ds_read_b128 v[188:191], v134 offset:16384
	ds_read_b128 v[192:195], v134 offset:17408
	ds_read_b128 v[196:199], v137 offset:16384
	ds_read_b128 v[200:203], v137 offset:17408
	ds_read_b128 v[204:207], v139 offset:16384
	ds_read_b128 v[208:211], v139 offset:17408
	s_add_u32 s50, s42, 0x100
	s_addc_u32 s51, s43, 0
	s_mov_b32 m0, s15
	s_nop 0
	v_lshl_add_u64 v[166:167], s[50:51], 0, v[0:1]
	global_load_lds_dwordx4 v[166:167], off
	v_lshl_add_u64 v[166:167], s[50:51], 0, v[140:141]
	s_mov_b32 m0, s25
	s_nop 0
	global_load_lds_dwordx4 v[166:167], off
	s_barrier
	s_waitcnt lgkmcnt(0)
	v_mfma_f32_16x16x32_bf16 v[62:65], v[162:165], v[146:149], v[62:65]
	v_mfma_f32_16x16x32_bf16 v[58:61], v[162:165], v[154:157], v[58:61]
	v_mfma_f32_16x16x32_bf16 v[54:57], v[188:191], v[146:149], v[54:57]
	v_mfma_f32_16x16x32_bf16 v[50:53], v[188:191], v[154:157], v[50:53]
	v_mfma_f32_16x16x32_bf16 v[46:49], v[196:199], v[146:149], v[46:49]
	v_mfma_f32_16x16x32_bf16 v[42:45], v[196:199], v[154:157], v[42:45]
	v_mfma_f32_16x16x32_bf16 v[38:41], v[204:207], v[146:149], v[38:41]
	v_mfma_f32_16x16x32_bf16 v[34:37], v[204:207], v[154:157], v[34:37]
	v_mfma_f32_16x16x32_bf16 v[62:65], v[184:187], v[150:153], v[62:65]
	v_mfma_f32_16x16x32_bf16 v[58:61], v[184:187], v[158:161], v[58:61]
	v_mfma_f32_16x16x32_bf16 v[54:57], v[192:195], v[150:153], v[54:57]
	v_mfma_f32_16x16x32_bf16 v[50:53], v[192:195], v[158:161], v[50:53]
	v_mfma_f32_16x16x32_bf16 v[46:49], v[200:203], v[150:153], v[46:49]
	v_mfma_f32_16x16x32_bf16 v[42:45], v[200:203], v[158:161], v[42:45]
	v_mfma_f32_16x16x32_bf16 v[38:41], v[208:211], v[150:153], v[38:41]
	v_mfma_f32_16x16x32_bf16 v[34:37], v[208:211], v[158:161], v[34:37]
	s_barrier
; #define LDA(dst, b, h) for (int m = 0; m < 4; ++m) for (int k = 0; k < 2; ++k) \
;     dst[m][k] = *reinterpret_cast<const bf16x8*>((char*)SA(b, h) + lds_byte(wr * 64 + m * 16 + fr, k * 32 + fq * 8))
; #define LDB(dst, b, h) for (int n = 0; n < 2; ++n) for (int k = 0; k < 2; ++k) \
;     dst[n][k] = *reinterpret_cast<const bf16x8*>((char*)SB(b, h) + lds_byte(wc * 32 + n * 16 + fr, k * 32 + fq * 8))
; #define MMA(ai, bj, At, Bt_) do { __builtin_amdgcn_s_setprio(1); \
;     for (int m = 0; m < 4; ++m) for (int n = 0; n < 2; ++n) for (int k = 0; k < 2; ++k) \
;       acc[ai][bj][m][n] = __builtin_amdgcn_mfma_f32_16x16x32_bf16(At[m][k], Bt_[n][k], acc[ai][bj][m][n], 0, 0, 0); \
;     __builtin_amdgcn_s_setprio(0); } while (0)
; #define WAIT_V(n) asm volatile("s_waitcnt vmcnt(" #n ")" ::: "memory")
; #define WAIT_L(n) asm volatile("s_waitcnt lgkmcnt(" #n ")" ::: "memory")
; #define BAR __builtin_amdgcn_s_barrier()
; #define SCHED __builtin_amdgcn_sched_barrier(0)
;     ...
;     for (int t = 0; t < nt - 2; t += 2) {
;       LDB(B0, 0, 0); SCHED; LDA(At, 0, 0); STAGE(SA(1, 1), A, brow + HALF, t + 1);
;       WAIT_L(8); BAR; WAIT_L(0); MMA(0, 0, At, B0); BAR; SCHED;
;       LDB(B1, 0, 1); STAGE(SB(0, 0), Bt, bcol, t + 2);
;       BAR; WAIT_L(0); MMA(0, 1, At, B1); BAR;
;       LDA(At, 0, 1); STAGE(SA(0, 0), A, brow, t + 2);
;       BAR; WAIT_L(0); MMA(1, 0, At, B0); BAR; SCHED;
;       STAGE(SB(0, 1), Bt, bcol + HALF, t + 2);
;       WAIT_V(6); BAR; MMA(1, 1, At, B1); BAR;
;       LDB(B0, 1, 0); SCHED; LDA(At, 1, 0); STAGE(SA(0, 1), A, brow + HALF, t + 2);
;       WAIT_L(8); BAR; WAIT_L(0); MMA(0, 0, At, B0); BAR; SCHED;
;       LDB(B1, 1, 1); STAGE(SB(1, 0), Bt, bcol, t + 3);
;       BAR; WAIT_L(0); MMA(0, 1, At, B1); BAR;
;       LDA(At, 1, 1); STAGE(SA(1, 0), A, brow, t + 3);
;       BAR; WAIT_L(0); MMA(1, 0, At, B0); BAR; SCHED;
;       STAGE(SB(1, 1), Bt, bcol + HALF, t + 3);
;       WAIT_V(6); BAR; MMA(1, 1, At, B1); BAR;
;     }
	s_add_u32 s50, s44, 0x80100
	s_addc_u32 s51, s45, 0
	s_mov_b32 m0, s27
	s_nop 0
	v_lshl_add_u64 v[146:147], s[50:51], 0, v[0:1]
	global_load_lds_dwordx4 v[146:147], off
	v_lshl_add_u64 v[146:147], s[50:51], 0, v[140:141]
	s_mov_b32 m0, s28
	s_nop 0
	global_load_lds_dwordx4 v[146:147], off
	s_waitcnt vmcnt(6)
	s_barrier
	v_mfma_f32_16x16x32_bf16 v[30:33], v[162:165], v[212:215], v[30:33]
	v_mfma_f32_16x16x32_bf16 v[26:29], v[162:165], v[220:223], v[26:29]
	v_mfma_f32_16x16x32_bf16 v[22:25], v[188:191], v[212:215], v[22:25]
	v_mfma_f32_16x16x32_bf16 v[18:21], v[188:191], v[220:223], v[18:21]
	v_mfma_f32_16x16x32_bf16 v[14:17], v[196:199], v[212:215], v[14:17]
	v_mfma_f32_16x16x32_bf16 v[10:13], v[196:199], v[220:223], v[10:13]
	v_mfma_f32_16x16x32_bf16 v[6:9], v[204:207], v[212:215], v[6:9]
	v_mfma_f32_16x16x32_bf16 v[2:5], v[204:207], v[220:223], v[2:5]
	v_mfma_f32_16x16x32_bf16 v[30:33], v[184:187], v[216:219], v[30:33]
	v_mfma_f32_16x16x32_bf16 v[26:29], v[184:187], v[224:227], v[26:29]
	v_mfma_f32_16x16x32_bf16 v[22:25], v[192:195], v[216:219], v[22:25]
	v_mfma_f32_16x16x32_bf16 v[18:21], v[192:195], v[224:227], v[18:21]
	v_mfma_f32_16x16x32_bf16 v[14:17], v[200:203], v[216:219], v[14:17]
	v_mfma_f32_16x16x32_bf16 v[10:13], v[200:203], v[224:227], v[10:13]
	v_mfma_f32_16x16x32_bf16 v[6:9], v[208:211], v[216:219], v[6:9]
	v_mfma_f32_16x16x32_bf16 v[2:5], v[208:211], v[224:227], v[2:5]
	s_barrier
	v_add_u32_e32 v145, s77, v142
	ds_read_b128 v[148:151], v145
	ds_read_b128 v[152:155], v145 offset:1024
	ds_read_b128 v[156:159], v145 offset:2048
	ds_read_b128 v[160:163], v145 offset:3072
	s_add_u32 s50, s42, 0x80100
	s_addc_u32 s51, s43, 0
	s_mov_b32 m0, s17
	ds_read_b128 v[164:167], v133 offset:32768
	ds_read_b128 v[184:187], v133 offset:33792
	ds_read_b128 v[188:191], v134 offset:32768
	ds_read_b128 v[192:195], v134 offset:33792
	ds_read_b128 v[196:199], v137 offset:32768
	ds_read_b128 v[200:203], v137 offset:33792
	ds_read_b128 v[204:207], v139 offset:32768
	ds_read_b128 v[208:211], v139 offset:33792
	s_nop 0
	v_lshl_add_u64 v[146:147], s[50:51], 0, v[0:1]
	global_load_lds_dwordx4 v[146:147], off
	v_lshl_add_u64 v[146:147], s[50:51], 0, v[140:141]
	s_mov_b32 m0, s29
	s_nop 0
	global_load_lds_dwordx4 v[146:147], off
	s_waitcnt lgkmcnt(8)
	s_barrier
	s_waitcnt lgkmcnt(0)
	v_mfma_f32_16x16x32_bf16 v[126:129], v[164:167], v[148:151], v[126:129]
	v_mfma_f32_16x16x32_bf16 v[122:125], v[164:167], v[156:159], v[122:125]
	v_mfma_f32_16x16x32_bf16 v[118:121], v[188:191], v[148:151], v[118:121]
	v_mfma_f32_16x16x32_bf16 v[114:117], v[188:191], v[156:159], v[114:117]
	v_mfma_f32_16x16x32_bf16 v[110:113], v[196:199], v[148:151], v[110:113]
	v_mfma_f32_16x16x32_bf16 v[106:109], v[196:199], v[156:159], v[106:109]
	v_mfma_f32_16x16x32_bf16 v[102:105], v[204:207], v[148:151], v[102:105]
	v_mfma_f32_16x16x32_bf16 v[98:101], v[204:207], v[156:159], v[98:101]
	v_mfma_f32_16x16x32_bf16 v[126:129], v[184:187], v[152:155], v[126:129]
	v_mfma_f32_16x16x32_bf16 v[122:125], v[184:187], v[160:163], v[122:125]
	v_mfma_f32_16x16x32_bf16 v[118:121], v[192:195], v[152:155], v[118:121]
	v_mfma_f32_16x16x32_bf16 v[114:117], v[192:195], v[160:163], v[114:117]
	v_mfma_f32_16x16x32_bf16 v[110:113], v[200:203], v[152:155], v[110:113]
	v_mfma_f32_16x16x32_bf16 v[106:109], v[200:203], v[160:163], v[106:109]
	v_mfma_f32_16x16x32_bf16 v[102:105], v[208:211], v[152:155], v[102:105]
	v_mfma_f32_16x16x32_bf16 v[98:101], v[208:211], v[160:163], v[98:101]
	s_barrier
	v_add_u32_e32 v146, s78, v142
	ds_read_b128 v[212:215], v146
	ds_read_b128 v[216:219], v146 offset:1024
	ds_read_b128 v[220:223], v146 offset:2048
	ds_read_b128 v[224:227], v146 offset:3072
	s_add_u32 s50, s44, 0x180
	s_addc_u32 s51, s45, 0
	s_mov_b32 m0, s8
	s_nop 0
	v_lshl_add_u64 v[228:229], s[50:51], 0, v[0:1]
	global_load_lds_dwordx4 v[228:229], off
	v_lshl_add_u64 v[228:229], s[50:51], 0, v[140:141]
	s_mov_b32 m0, s9
	s_nop 0
	global_load_lds_dwordx4 v[228:229], off
	s_barrier
	s_waitcnt lgkmcnt(0)
	v_mfma_f32_16x16x32_bf16 v[94:97], v[164:167], v[212:215], v[94:97]
	v_mfma_f32_16x16x32_bf16 v[90:93], v[164:167], v[220:223], v[90:93]
	v_mfma_f32_16x16x32_bf16 v[86:89], v[188:191], v[212:215], v[86:89]
	v_mfma_f32_16x16x32_bf16 v[82:85], v[188:191], v[220:223], v[82:85]
	v_mfma_f32_16x16x32_bf16 v[78:81], v[196:199], v[212:215], v[78:81]
	v_mfma_f32_16x16x32_bf16 v[74:77], v[196:199], v[220:223], v[74:77]
	v_mfma_f32_16x16x32_bf16 v[70:73], v[204:207], v[212:215], v[70:73]
	v_mfma_f32_16x16x32_bf16 v[66:69], v[204:207], v[220:223], v[66:69]
	v_mfma_f32_16x16x32_bf16 v[94:97], v[184:187], v[216:219], v[94:97]
	v_mfma_f32_16x16x32_bf16 v[90:93], v[184:187], v[224:227], v[90:93]
	v_mfma_f32_16x16x32_bf16 v[86:89], v[192:195], v[216:219], v[86:89]
	v_mfma_f32_16x16x32_bf16 v[82:85], v[192:195], v[224:227], v[82:85]
	v_mfma_f32_16x16x32_bf16 v[78:81], v[200:203], v[216:219], v[78:81]
	v_mfma_f32_16x16x32_bf16 v[74:77], v[200:203], v[224:227], v[74:77]
	v_mfma_f32_16x16x32_bf16 v[70:73], v[208:211], v[216:219], v[70:73]
	v_mfma_f32_16x16x32_bf16 v[66:69], v[208:211], v[224:227], v[66:69]
	s_barrier
	ds_read_b128 v[164:167], v133 offset:49152
	ds_read_b128 v[184:187], v133 offset:50176
	ds_read_b128 v[188:191], v134 offset:49152
	ds_read_b128 v[192:195], v134 offset:50176
	ds_read_b128 v[196:199], v137 offset:49152
	ds_read_b128 v[200:203], v137 offset:50176
	ds_read_b128 v[204:207], v139 offset:49152
	ds_read_b128 v[208:211], v139 offset:50176
	s_add_u32 s42, s42, 0x180
	s_addc_u32 s43, s43, 0
	s_mov_b32 m0, s18
	s_nop 0
	v_lshl_add_u64 v[228:229], s[42:43], 0, v[0:1]
	global_load_lds_dwordx4 v[228:229], off
	v_lshl_add_u64 v[228:229], s[42:43], 0, v[140:141]
	s_mov_b32 m0, s19
	s_nop 0
	global_load_lds_dwordx4 v[228:229], off
	s_barrier
; #define LDA(dst, b, h) for (int m = 0; m < 4; ++m) for (int k = 0; k < 2; ++k) \
;     dst[m][k] = *reinterpret_cast<const bf16x8*>((char*)SA(b, h) + lds_byte(wr * 64 + m * 16 + fr, k * 32 + fq * 8))
; #define LDB(dst, b, h) for (int n = 0; n < 2; ++n) for (int k = 0; k < 2; ++k) \
;     dst[n][k] = *reinterpret_cast<const bf16x8*>((char*)SB(b, h) + lds_byte(wc * 32 + n * 16 + fr, k * 32 + fq * 8))
; #define MMA(ai, bj, At, Bt_) do { __builtin_amdgcn_s_setprio(1); \
;     for (int m = 0; m < 4; ++m) for (int n = 0; n < 2; ++n) for (int k = 0; k < 2; ++k) \
;       acc[ai][bj][m][n] = __builtin_amdgcn_mfma_f32_16x16x32_bf16(At[m][k], Bt_[n][k], acc[ai][bj][m][n], 0, 0, 0); \
;     __builtin_amdgcn_s_setprio(0); } while (0)
; #define WAIT_V(n) asm volatile("s_waitcnt vmcnt(" #n ")" ::: "memory")
; #define WAIT_L(n) asm volatile("s_waitcnt lgkmcnt(" #n ")" ::: "memory")
; #define BAR __builtin_amdgcn_s_barrier()
; #define SCHED __builtin_amdgcn_sched_barrier(0)
;     ...
;       WAIT_V(6); BAR; MMA(1, 1, At, B1); BAR;
;       LDB(B0, 1, 0); SCHED; LDA(At, 1, 0); STAGE(SA(0, 1), A, brow + HALF, t + 2);
;       WAIT_L(8); BAR; WAIT_L(0); MMA(0, 0, At, B0); BAR; SCHED;
;       LDB(B1, 1, 1); STAGE(SB(1, 0), Bt, bcol, t + 3);
;       BAR; WAIT_L(0); MMA(0, 1, At, B1); BAR;
;       LDA(At, 1, 1); STAGE(SA(1, 0), A, brow, t + 3);
;       BAR; WAIT_L(0); MMA(1, 0, At, B0); BAR; SCHED;
;       STAGE(SB(1, 1), Bt, bcol + HALF, t + 3);
;       WAIT_V(6); BAR; MMA(1, 1, At, B1); BAR;
;     }
;     { LDB(B0, 0, 0); LDA(At, 0, 0); STAGE(SA(1, 1), A, brow + HALF, nt - 1);
;       BAR; WAIT_L(0); MMA(0, 0, At, B0); BAR;
;       LDB(B1, 0, 1); BAR; WAIT_L(0); MMA(0, 1, At, B1); BAR;
;       LDA(At, 0, 1); WAIT_V(4); BAR; WAIT_L(0); MMA(1, 0, At, B0); MMA(1, 1, At, B1); BAR; }
;     { LDB(B0, 1, 0); LDA(At, 1, 0); WAIT_V(2); BAR; WAIT_L(0); MMA(0, 0, At, B0); BAR;
;       LDB(B1, 1, 1); WAIT_V(0); BAR; WAIT_L(0); MMA(0, 1, At, B1); BAR;
;       LDA(At, 1, 1); BAR; WAIT_L(0); MMA(1, 0, At, B0); MMA(1, 1, At, B1); BAR; }
	s_waitcnt lgkmcnt(0)
	v_mfma_f32_16x16x32_bf16 v[62:65], v[164:167], v[148:151], v[62:65]
	v_mfma_f32_16x16x32_bf16 v[58:61], v[164:167], v[156:159], v[58:61]
	v_mfma_f32_16x16x32_bf16 v[54:57], v[188:191], v[148:151], v[54:57]
	v_mfma_f32_16x16x32_bf16 v[50:53], v[188:191], v[156:159], v[50:53]
	v_mfma_f32_16x16x32_bf16 v[46:49], v[196:199], v[148:151], v[46:49]
	v_mfma_f32_16x16x32_bf16 v[42:45], v[196:199], v[156:159], v[42:45]
	v_mfma_f32_16x16x32_bf16 v[38:41], v[204:207], v[148:151], v[38:41]
	v_mfma_f32_16x16x32_bf16 v[34:37], v[204:207], v[156:159], v[34:37]
	v_mfma_f32_16x16x32_bf16 v[62:65], v[184:187], v[152:155], v[62:65]
	v_mfma_f32_16x16x32_bf16 v[58:61], v[184:187], v[160:163], v[58:61]
	v_mfma_f32_16x16x32_bf16 v[54:57], v[192:195], v[152:155], v[54:57]
	v_mfma_f32_16x16x32_bf16 v[50:53], v[192:195], v[160:163], v[50:53]
	v_mfma_f32_16x16x32_bf16 v[46:49], v[200:203], v[152:155], v[46:49]
	v_mfma_f32_16x16x32_bf16 v[42:45], v[200:203], v[160:163], v[42:45]
	v_mfma_f32_16x16x32_bf16 v[38:41], v[208:211], v[152:155], v[38:41]
	v_mfma_f32_16x16x32_bf16 v[34:37], v[208:211], v[160:163], v[34:37]
	s_barrier
	s_add_u32 s42, s44, 0x80180
	s_addc_u32 s43, s45, 0
	s_mov_b32 m0, s20
	s_nop 0
	v_lshl_add_u64 v[148:149], s[42:43], 0, v[0:1]
	global_load_lds_dwordx4 v[148:149], off
	v_lshl_add_u64 v[148:149], s[42:43], 0, v[140:141]
	s_mov_b32 m0, s21
	s_nop 0
	global_load_lds_dwordx4 v[148:149], off
	s_add_i32 s36, s36, 2
	s_add_u32 s6, s6, 0x100
	s_addc_u32 s7, s7, 0
	s_cmp_gt_u32 s36, 27
	s_waitcnt vmcnt(6)
	s_barrier
	v_mfma_f32_16x16x32_bf16 v[30:33], v[164:167], v[212:215], v[30:33]
	v_mfma_f32_16x16x32_bf16 v[26:29], v[164:167], v[220:223], v[26:29]
	v_mfma_f32_16x16x32_bf16 v[22:25], v[188:191], v[212:215], v[22:25]
	v_mfma_f32_16x16x32_bf16 v[18:21], v[188:191], v[220:223], v[18:21]
	v_mfma_f32_16x16x32_bf16 v[14:17], v[196:199], v[212:215], v[14:17]
	v_mfma_f32_16x16x32_bf16 v[10:13], v[196:199], v[220:223], v[10:13]
	v_mfma_f32_16x16x32_bf16 v[6:9], v[204:207], v[212:215], v[6:9]
	v_mfma_f32_16x16x32_bf16 v[2:5], v[204:207], v[220:223], v[2:5]
	v_mfma_f32_16x16x32_bf16 v[30:33], v[184:187], v[216:219], v[30:33]
	v_mfma_f32_16x16x32_bf16 v[26:29], v[184:187], v[224:227], v[26:29]
	v_mfma_f32_16x16x32_bf16 v[22:25], v[192:195], v[216:219], v[22:25]
	v_mfma_f32_16x16x32_bf16 v[18:21], v[192:195], v[224:227], v[18:21]
	v_mfma_f32_16x16x32_bf16 v[14:17], v[200:203], v[216:219], v[14:17]
	v_mfma_f32_16x16x32_bf16 v[10:13], v[200:203], v[224:227], v[10:13]
	v_mfma_f32_16x16x32_bf16 v[6:9], v[208:211], v[216:219], v[6:9]
	v_mfma_f32_16x16x32_bf16 v[2:5], v[208:211], v[224:227], v[2:5]
	s_barrier
	s_cbranch_scc0 .LBB0_418
	s_add_u32 s4, s4, 0xf80
	s_addc_u32 s5, s5, 0
	s_mov_b32 m0, s41
	ds_read_b128 v[148:151], v143
	ds_read_b128 v[152:155], v143 offset:1024
	ds_read_b128 v[156:159], v143 offset:2048
	ds_read_b128 v[160:163], v143 offset:3072
	ds_read_b128 v[164:167], v133
	ds_read_b128 v[184:187], v133 offset:1024
	ds_read_b128 v[188:191], v134
	ds_read_b128 v[192:195], v134 offset:1024
	ds_read_b128 v[196:199], v137
	ds_read_b128 v[200:203], v137 offset:1024
	ds_read_b128 v[204:207], v139
	ds_read_b128 v[208:211], v139 offset:1024
	s_nop 0
	v_lshl_add_u64 v[142:143], s[4:5], 0, v[0:1]
	global_load_lds_dwordx4 v[142:143], off
	v_lshl_add_u64 v[140:141], s[4:5], 0, v[140:141]
	s_mov_b32 m0, s37
	s_nop 0
	global_load_lds_dwordx4 v[140:141], off
	s_barrier
	s_waitcnt lgkmcnt(0)
	s_setprio 1
	s_waitcnt lgkmcnt(0)
	v_mfma_f32_16x16x32_bf16 v[126:129], v[164:167], v[148:151], v[126:129]
	v_mfma_f32_16x16x32_bf16 v[122:125], v[164:167], v[156:159], v[122:125]
	v_mfma_f32_16x16x32_bf16 v[118:121], v[188:191], v[148:151], v[118:121]
	v_mfma_f32_16x16x32_bf16 v[110:113], v[196:199], v[148:151], v[110:113]
	v_mfma_f32_16x16x32_bf16 v[106:109], v[196:199], v[156:159], v[106:109]
	v_mfma_f32_16x16x32_bf16 v[102:105], v[204:207], v[148:151], v[102:105]
	v_mfma_f32_16x16x32_bf16 v[98:101], v[204:207], v[156:159], v[98:101]
	v_mfma_f32_16x16x32_bf16 v[126:129], v[184:187], v[152:155], v[126:129]
	v_mfma_f32_16x16x32_bf16 v[122:125], v[184:187], v[160:163], v[122:125]
	v_mfma_f32_16x16x32_bf16 v[118:121], v[192:195], v[152:155], v[118:121]
	v_mfma_f32_16x16x32_bf16 v[114:117], v[188:191], v[156:159], v[114:117]
	v_mfma_f32_16x16x32_bf16 v[110:113], v[200:203], v[152:155], v[110:113]
	v_mfma_f32_16x16x32_bf16 v[106:109], v[200:203], v[160:163], v[106:109]
	v_mfma_f32_16x16x32_bf16 v[102:105], v[208:211], v[152:155], v[102:105]
	v_mfma_f32_16x16x32_bf16 v[98:101], v[208:211], v[160:163], v[98:101]
	v_mfma_f32_16x16x32_bf16 v[140:143], v[192:195], v[160:163], v[114:117]
	s_setprio 0
	s_barrier
	s_nop 0
	ds_read_b128 v[114:117], v144
	ds_read_b128 v[212:215], v144 offset:1024
	ds_read_b128 v[216:219], v144 offset:2048
	ds_read_b128 v[220:223], v144 offset:3072
	s_barrier
	s_waitcnt lgkmcnt(0)
	s_setprio 1
	s_waitcnt lgkmcnt(0)
	v_mfma_f32_16x16x32_bf16 v[90:93], v[164:167], v[216:219], v[90:93]
	v_mfma_f32_16x16x32_bf16 v[86:89], v[188:191], v[114:117], v[86:89]
	v_mfma_f32_16x16x32_bf16 v[94:97], v[164:167], v[114:117], v[94:97]
	v_mfma_f32_16x16x32_bf16 v[90:93], v[184:187], v[220:223], v[90:93]
	v_mfma_f32_16x16x32_bf16 v[86:89], v[192:195], v[212:215], v[86:89]
	v_mfma_f32_16x16x32_bf16 v[82:85], v[188:191], v[216:219], v[82:85]
	v_mfma_f32_16x16x32_bf16 v[78:81], v[196:199], v[114:117], v[78:81]
	v_mfma_f32_16x16x32_bf16 v[74:77], v[196:199], v[216:219], v[74:77]
	v_mfma_f32_16x16x32_bf16 v[70:73], v[204:207], v[114:117], v[70:73]
	v_mfma_f32_16x16x32_bf16 v[66:69], v[204:207], v[216:219], v[66:69]
	v_mfma_f32_16x16x32_bf16 v[224:227], v[184:187], v[212:215], v[94:97]
	v_mfma_f32_16x16x32_bf16 v[164:167], v[192:195], v[220:223], v[82:85]
	v_mfma_f32_16x16x32_bf16 v[184:187], v[200:203], v[212:215], v[78:81]
	v_mfma_f32_16x16x32_bf16 v[188:191], v[200:203], v[220:223], v[74:77]
	v_mfma_f32_16x16x32_bf16 v[192:195], v[208:211], v[212:215], v[70:73]
	v_mfma_f32_16x16x32_bf16 v[196:199], v[208:211], v[220:223], v[66:69]
	s_setprio 0
	s_barrier
; #define LDA(dst, b, h) for (int m = 0; m < 4; ++m) for (int k = 0; k < 2; ++k) \
;     dst[m][k] = *reinterpret_cast<const bf16x8*>((char*)SA(b, h) + lds_byte(wr * 64 + m * 16 + fr, k * 32 + fq * 8))
; #define LDB(dst, b, h) for (int n = 0; n < 2; ++n) for (int k = 0; k < 2; ++k) \
;     dst[n][k] = *reinterpret_cast<const bf16x8*>((char*)SB(b, h) + lds_byte(wc * 32 + n * 16 + fr, k * 32 + fq * 8))
; #define MMA(ai, bj, At, Bt_) do { __builtin_amdgcn_s_setprio(1); \
;     for (int m = 0; m < 4; ++m) for (int n = 0; n < 2; ++n) for (int k = 0; k < 2; ++k) \
;       acc[ai][bj][m][n] = __builtin_amdgcn_mfma_f32_16x16x32_bf16(At[m][k], Bt_[n][k], acc[ai][bj][m][n], 0, 0, 0); \
;     __builtin_amdgcn_s_setprio(0); } while (0)
; #define WAIT_V(n) asm volatile("s_waitcnt vmcnt(" #n ")" ::: "memory")
; #define WAIT_L(n) asm volatile("s_waitcnt lgkmcnt(" #n ")" ::: "memory")
; #define BAR __builtin_amdgcn_s_barrier()
;     ...
;       LDB(B1, 0, 1); BAR; WAIT_L(0); MMA(0, 1, At, B1); BAR;
;       LDA(At, 0, 1); WAIT_V(4); BAR; WAIT_L(0); MMA(1, 0, At, B0); MMA(1, 1, At, B1); BAR; }
;     { LDB(B0, 1, 0); LDA(At, 1, 0); WAIT_V(2); BAR; WAIT_L(0); MMA(0, 0, At, B0); BAR;
;       LDB(B1, 1, 1); WAIT_V(0); BAR; WAIT_L(0); MMA(0, 1, At, B1); BAR;
;       LDA(At, 1, 1); BAR; WAIT_L(0); MMA(1, 0, At, B0); MMA(1, 1, At, B1); BAR; }
	s_nop 0
	ds_read_b128 v[66:69], v133 offset:16384
	ds_read_b128 v[70:73], v133 offset:17408
	ds_read_b128 v[74:77], v134 offset:16384
	ds_read_b128 v[78:81], v134 offset:17408
	ds_read_b128 v[82:85], v137 offset:16384
	ds_read_b128 v[94:97], v137 offset:17408
	ds_read_b128 v[200:203], v139 offset:16384
	ds_read_b128 v[204:207], v139 offset:17408
	s_waitcnt vmcnt(4)
	s_barrier
	s_waitcnt lgkmcnt(0)
	s_setprio 1
	s_waitcnt lgkmcnt(0)
	v_mfma_f32_16x16x32_bf16 v[62:65], v[66:69], v[148:151], v[62:65]
	v_mfma_f32_16x16x32_bf16 v[58:61], v[66:69], v[156:159], v[58:61]
	v_mfma_f32_16x16x32_bf16 v[54:57], v[74:77], v[148:151], v[54:57]
	v_mfma_f32_16x16x32_bf16 v[50:53], v[74:77], v[156:159], v[50:53]
	v_mfma_f32_16x16x32_bf16 v[46:49], v[82:85], v[148:151], v[46:49]
	v_mfma_f32_16x16x32_bf16 v[42:45], v[82:85], v[156:159], v[42:45]
	v_mfma_f32_16x16x32_bf16 v[38:41], v[200:203], v[148:151], v[38:41]
	v_mfma_f32_16x16x32_bf16 v[34:37], v[200:203], v[156:159], v[34:37]
	v_mfma_f32_16x16x32_bf16 v[62:65], v[70:73], v[152:155], v[62:65]
	v_mfma_f32_16x16x32_bf16 v[58:61], v[70:73], v[160:163], v[58:61]
	v_mfma_f32_16x16x32_bf16 v[54:57], v[78:81], v[152:155], v[54:57]
	v_mfma_f32_16x16x32_bf16 v[50:53], v[78:81], v[160:163], v[50:53]
	v_mfma_f32_16x16x32_bf16 v[46:49], v[94:97], v[152:155], v[46:49]
	v_mfma_f32_16x16x32_bf16 v[42:45], v[94:97], v[160:163], v[42:45]
	v_mfma_f32_16x16x32_bf16 v[38:41], v[204:207], v[152:155], v[38:41]
	v_mfma_f32_16x16x32_bf16 v[34:37], v[204:207], v[160:163], v[34:37]
	s_setprio 0
	s_setprio 1
	v_mfma_f32_16x16x32_bf16 v[30:33], v[66:69], v[114:117], v[30:33]
	v_mfma_f32_16x16x32_bf16 v[26:29], v[66:69], v[216:219], v[26:29]
	v_mfma_f32_16x16x32_bf16 v[22:25], v[74:77], v[114:117], v[22:25]
	v_mfma_f32_16x16x32_bf16 v[18:21], v[74:77], v[216:219], v[18:21]
	v_mfma_f32_16x16x32_bf16 v[14:17], v[82:85], v[114:117], v[14:17]
	v_mfma_f32_16x16x32_bf16 v[10:13], v[82:85], v[216:219], v[10:13]
	v_mfma_f32_16x16x32_bf16 v[6:9], v[200:203], v[114:117], v[6:9]
	v_mfma_f32_16x16x32_bf16 v[2:5], v[200:203], v[216:219], v[2:5]
	v_mfma_f32_16x16x32_bf16 v[148:151], v[70:73], v[212:215], v[30:33]
	v_mfma_f32_16x16x32_bf16 v[152:155], v[70:73], v[220:223], v[26:29]
	v_mfma_f32_16x16x32_bf16 v[156:159], v[78:81], v[212:215], v[22:25]
	v_mfma_f32_16x16x32_bf16 v[160:163], v[78:81], v[220:223], v[18:21]
	v_mfma_f32_16x16x32_bf16 v[208:211], v[94:97], v[212:215], v[14:17]
	v_mfma_f32_16x16x32_bf16 v[228:231], v[94:97], v[220:223], v[10:13]
	v_mfma_f32_16x16x32_bf16 v[212:215], v[204:207], v[212:215], v[6:9]
	v_mfma_f32_16x16x32_bf16 v[200:203], v[204:207], v[220:223], v[2:5]
	s_setprio 0
	s_barrier
	ds_read_b128 v[14:17], v145
	ds_read_b128 v[30:33], v145 offset:1024
	ds_read_b128 v[204:207], v145 offset:2048
	ds_read_b128 v[216:219], v145 offset:3072
	ds_read_b128 v[2:5], v133 offset:32768
	ds_read_b128 v[6:9], v133 offset:33792
	ds_read_b128 v[10:13], v134 offset:32768
	ds_read_b128 v[18:21], v134 offset:33792
	ds_read_b128 v[22:25], v137 offset:32768
	ds_read_b128 v[26:29], v137 offset:33792
	ds_read_b128 v[220:223], v139 offset:32768
	ds_read_b128 v[232:235], v139 offset:33792
	s_waitcnt vmcnt(2)
	s_barrier
	s_waitcnt lgkmcnt(0)
	s_setprio 1
	s_waitcnt lgkmcnt(0)
	v_mfma_f32_16x16x32_bf16 v[66:69], v[2:5], v[14:17], v[126:129]
	v_mfma_f32_16x16x32_bf16 v[114:117], v[6:9], v[30:33], v[66:69]
	v_mfma_f32_16x16x32_bf16 v[66:69], v[2:5], v[204:207], v[122:125]
	v_mfma_f32_16x16x32_bf16 v[126:129], v[6:9], v[216:219], v[66:69]
	v_mfma_f32_16x16x32_bf16 v[66:69], v[10:13], v[14:17], v[118:121]
	v_mfma_f32_16x16x32_bf16 v[82:85], v[18:21], v[30:33], v[66:69]
	v_mfma_f32_16x16x32_bf16 v[66:69], v[10:13], v[204:207], v[140:143]
	v_mfma_f32_16x16x32_bf16 v[94:97], v[18:21], v[216:219], v[66:69]
	v_mfma_f32_16x16x32_bf16 v[66:69], v[22:25], v[14:17], v[110:113]
	v_mfma_f32_16x16x32_bf16 v[74:77], v[26:29], v[30:33], v[66:69]
	v_mfma_f32_16x16x32_bf16 v[66:69], v[22:25], v[204:207], v[106:109]
	v_mfma_f32_16x16x32_bf16 v[78:81], v[26:29], v[216:219], v[66:69]
	v_mfma_f32_16x16x32_bf16 v[66:69], v[220:223], v[14:17], v[102:105]
	v_mfma_f32_16x16x32_bf16 v[70:73], v[220:223], v[204:207], v[98:101]
	v_mfma_f32_16x16x32_bf16 v[66:69], v[232:235], v[30:33], v[66:69]
	v_mfma_f32_16x16x32_bf16 v[70:73], v[232:235], v[216:219], v[70:73]
	s_setprio 0
	s_barrier
; #define LDA(dst, b, h) for (int m = 0; m < 4; ++m) for (int k = 0; k < 2; ++k) \
;     dst[m][k] = *reinterpret_cast<const bf16x8*>((char*)SA(b, h) + lds_byte(wr * 64 + m * 16 + fr, k * 32 + fq * 8))
; #define LDB(dst, b, h) for (int n = 0; n < 2; ++n) for (int k = 0; k < 2; ++k) \
;     dst[n][k] = *reinterpret_cast<const bf16x8*>((char*)SB(b, h) + lds_byte(wc * 32 + n * 16 + fr, k * 32 + fq * 8))
; #define MMA(ai, bj, At, Bt_) do { __builtin_amdgcn_s_setprio(1); \
;     for (int m = 0; m < 4; ++m) for (int n = 0; n < 2; ++n) for (int k = 0; k < 2; ++k) \
;       acc[ai][bj][m][n] = __builtin_amdgcn_mfma_f32_16x16x32_bf16(At[m][k], Bt_[n][k], acc[ai][bj][m][n], 0, 0, 0); \
;     __builtin_amdgcn_s_setprio(0); } while (0)
; #define WAIT_V(n) asm volatile("s_waitcnt vmcnt(" #n ")" ::: "memory")
; #define WAIT_L(n) asm volatile("s_waitcnt lgkmcnt(" #n ")" ::: "memory")
; #define BAR __builtin_amdgcn_s_barrier()
;     ...
;     { LDB(B0, 1, 0); LDA(At, 1, 0); WAIT_V(2); BAR; WAIT_L(0); MMA(0, 0, At, B0); BAR;
;       LDB(B1, 1, 1); WAIT_V(0); BAR; WAIT_L(0); MMA(0, 1, At, B1); BAR;
;       LDA(At, 1, 1); BAR; WAIT_L(0); MMA(1, 0, At, B0); MMA(1, 1, At, B1); BAR; }
;     if (wr == 0) BAR;
	ds_read_b128 v[140:143], v146
	ds_read_b128 v[236:239], v146 offset:1024
	ds_read_b128 v[240:243], v146 offset:2048
	ds_read_b128 v[144:147], v146 offset:3072
	s_waitcnt vmcnt(0)
	s_barrier
	s_waitcnt lgkmcnt(0)
	s_setprio 1
	s_waitcnt lgkmcnt(0)
	v_mfma_f32_16x16x32_bf16 v[98:101], v[2:5], v[140:143], v[224:227]
	v_mfma_f32_16x16x32_bf16 v[2:5], v[2:5], v[240:243], v[90:93]
	v_mfma_f32_16x16x32_bf16 v[118:121], v[6:9], v[144:147], v[2:5]
	v_mfma_f32_16x16x32_bf16 v[2:5], v[10:13], v[140:143], v[86:89]
	v_mfma_f32_16x16x32_bf16 v[102:105], v[18:21], v[236:239], v[2:5]
	v_mfma_f32_16x16x32_bf16 v[2:5], v[10:13], v[240:243], v[164:167]
	v_mfma_f32_16x16x32_bf16 v[122:125], v[18:21], v[144:147], v[2:5]
	v_mfma_f32_16x16x32_bf16 v[2:5], v[22:25], v[140:143], v[184:187]
	v_mfma_f32_16x16x32_bf16 v[90:93], v[26:29], v[236:239], v[2:5]
	v_mfma_f32_16x16x32_bf16 v[2:5], v[22:25], v[240:243], v[188:191]
	v_mfma_f32_16x16x32_bf16 v[110:113], v[26:29], v[144:147], v[2:5]
	v_mfma_f32_16x16x32_bf16 v[2:5], v[220:223], v[140:143], v[192:195]
	v_mfma_f32_16x16x32_bf16 v[86:89], v[232:235], v[236:239], v[2:5]
	v_mfma_f32_16x16x32_bf16 v[2:5], v[220:223], v[240:243], v[196:199]
	v_mfma_f32_16x16x32_bf16 v[98:101], v[6:9], v[236:239], v[98:101]
	v_mfma_f32_16x16x32_bf16 v[106:109], v[232:235], v[144:147], v[2:5]
	s_setprio 0
	s_barrier
	ds_read_b128 v[164:167], v133 offset:49152
	ds_read_b128 v[184:187], v133 offset:50176
	ds_read_b128 v[188:191], v134 offset:49152
	ds_read_b128 v[192:195], v134 offset:50176
	ds_read_b128 v[196:199], v137 offset:49152
	ds_read_b128 v[220:223], v137 offset:50176
	ds_read_b128 v[224:227], v139 offset:49152
	ds_read_b128 v[232:235], v139 offset:50176
	s_barrier
	s_waitcnt lgkmcnt(0)
	s_setprio 1
	s_waitcnt lgkmcnt(0)
	v_mfma_f32_16x16x32_bf16 v[6:9], v[164:167], v[204:207], v[58:61]
	v_mfma_f32_16x16x32_bf16 v[10:13], v[188:191], v[204:207], v[50:53]
	v_mfma_f32_16x16x32_bf16 v[2:5], v[164:167], v[14:17], v[62:65]
	v_mfma_f32_16x16x32_bf16 v[18:21], v[184:187], v[216:219], v[6:9]
	v_mfma_f32_16x16x32_bf16 v[6:9], v[188:191], v[14:17], v[54:57]
	v_mfma_f32_16x16x32_bf16 v[22:25], v[192:195], v[216:219], v[10:13]
	v_mfma_f32_16x16x32_bf16 v[10:13], v[196:199], v[14:17], v[46:49]
	v_mfma_f32_16x16x32_bf16 v[14:17], v[224:227], v[14:17], v[38:41]
	v_mfma_f32_16x16x32_bf16 v[2:5], v[184:187], v[30:33], v[2:5]
	v_mfma_f32_16x16x32_bf16 v[6:9], v[192:195], v[30:33], v[6:9]
	v_mfma_f32_16x16x32_bf16 v[10:13], v[220:223], v[30:33], v[10:13]
	v_mfma_f32_16x16x32_bf16 v[26:29], v[196:199], v[204:207], v[42:45]
	v_mfma_f32_16x16x32_bf16 v[14:17], v[232:235], v[30:33], v[14:17]
	v_mfma_f32_16x16x32_bf16 v[30:33], v[224:227], v[204:207], v[34:37]
	v_mfma_f32_16x16x32_bf16 v[26:29], v[220:223], v[216:219], v[26:29]
	v_mfma_f32_16x16x32_bf16 v[30:33], v[232:235], v[216:219], v[30:33]
	s_setprio 0
	s_setprio 1
	v_mfma_f32_16x16x32_bf16 v[38:41], v[164:167], v[240:243], v[152:155]
	v_mfma_f32_16x16x32_bf16 v[42:45], v[188:191], v[240:243], v[160:163]
	v_mfma_f32_16x16x32_bf16 v[46:49], v[196:199], v[240:243], v[228:231]
	v_mfma_f32_16x16x32_bf16 v[34:37], v[164:167], v[140:143], v[148:151]
	v_mfma_f32_16x16x32_bf16 v[50:53], v[184:187], v[144:147], v[38:41]
	v_mfma_f32_16x16x32_bf16 v[38:41], v[188:191], v[140:143], v[156:159]
	v_mfma_f32_16x16x32_bf16 v[54:57], v[192:195], v[144:147], v[42:45]
	v_mfma_f32_16x16x32_bf16 v[42:45], v[196:199], v[140:143], v[208:211]
	v_mfma_f32_16x16x32_bf16 v[58:61], v[220:223], v[144:147], v[46:49]
	v_mfma_f32_16x16x32_bf16 v[46:49], v[224:227], v[140:143], v[212:215]
	v_mfma_f32_16x16x32_bf16 v[62:65], v[224:227], v[240:243], v[200:203]
	v_mfma_f32_16x16x32_bf16 v[34:37], v[184:187], v[236:239], v[34:37]
	v_mfma_f32_16x16x32_bf16 v[38:41], v[192:195], v[236:239], v[38:41]
	v_mfma_f32_16x16x32_bf16 v[42:45], v[220:223], v[236:239], v[42:45]
	v_mfma_f32_16x16x32_bf16 v[46:49], v[232:235], v[236:239], v[46:49]
	v_mfma_f32_16x16x32_bf16 v[62:65], v[232:235], v[144:147], v[62:65]
	s_setprio 0
	v_readlane_b32 s4, v245, 33
	v_readlane_b32 s5, v245, 34
	s_and_b64 vcc, exec, s[4:5]
	s_barrier
	s_cbranch_vccz .LBB0_421
	s_barrier
